# norm phases (latent rows): hand-written software-pipelined loop (next 4 rows prefetched, params hoisted per wave, DPP wave sums instead of ds_bpermute chains), rows remapped so a wave stays in one bat
# baseline (speedup 1.0000x reference)
; template <int R, bool SRCB> ...
;     f32x4 h[R][2][2]; u32x4 yr[R][2];
; #pragma unroll
;     for (int r = 0; r < R; ++r)
; #pragma unroll
;         for (int j = 0; j < 2; ++j) { const int c = 8 * lane + 512 * j;
;             if (SRCB) { const u32x4 t = *(const u32x4*)((const bf16_t*)hp_ + (size_t)r * DM + c);
;                 h[r][j][0] = (f32x4){hf_lo(t.x), hf_hi(t.x), hf_lo(t.y), hf_hi(t.y)}; h[r][j][1] = (f32x4){hf_lo(t.z), hf_hi(t.z), hf_lo(t.w), hf_hi(t.w)}; }
;             else { h[r][j][0] = *(const f32x4*)((const float*)hp_ + (size_t)r * DM + c); h[r][j][1] = *(const f32x4*)((const float*)hp_ + (size_t)r * DM + c + 4); }
;             if (Y) yr[r][j] = *(const u32x4*)(Y + (size_t)(row0 + r) * DM + c); }
;     if (Y) {
;         f32x4 gg[2][2];
; #pragma unroll
;         for (int j = 0; j < 2; ++j)
; #pragma unroll
;             for (int k = 0; k < 2; ++k) { const int c = 8 * lane + 512 * j + 4 * k; gg[j][k] = *(const f32x4*)(gpost + c) * *(const f32x4*)(gate + (size_t)mrow * 9216 + c); }
; #pragma unroll
;         for (int r = 0; r < R; ++r) {
;             f32x4 y[2][2]; float ss = 0.f;
; #pragma unroll
;             for (int j = 0; j < 2; ++j) { const u32x4 t = yr[r][j];
;                 y[j][0] = (f32x4){bf_lo(t.x), bf_hi(t.x), bf_lo(t.y), bf_hi(t.y)}; y[j][1] = (f32x4){bf_lo(t.z), bf_hi(t.z), bf_lo(t.w), bf_hi(t.w)};
;                 if (R == 1 && YP) {
; #pragma unroll
;                     for (int k = 0; k < 2; ++k) { const float* pp = YP + (size_t)(row0 - M_LAT) * DM + 8 * lane + 512 * j + 4 * k; f32x4 s = *(const f32x4*)pp;
; #pragma unroll
;                         for (int q = 1; q < pg8::NSL; ++q) s = s + *(const f32x4*)(pp + (size_t)q * 2048 * DM);
;                         y[j][k] = s; } }
; #pragma unroll
;                 for (int k = 0; k < 2; ++k) ss += (y[j][k][0] * y[j][k][0] + y[j][k][1] * y[j][k][1]) + (y[j][k][2] * y[j][k][2] + y[j][k][3] * y[j][k][3]); }
;             const float rr = __builtin_amdgcn_rsqf(wave_sum(ss) * (1.0f / DM) + 1e-6f) * w;
; #pragma unroll
;             for (int j = 0; j < 2; ++j)
; #pragma unroll
;                 for (int k = 0; k < 2; ++k) h[r][j][k] = h[r][j][k] + gg[j][k] * (y[j][k] * rr);
;         }
;     }
; #pragma unroll
;     for (int r = 0; r < R; ++r)
; #pragma unroll
;         for (int j = 0; j < 2; ++j) { const int c = 8 * lane + 512 * j;
.LBB0_208:
	v_readlane_b32 s6, v255, 0
	s_mul_i32 s3, s6, 0x51000
	v_readlane_b32 s4, v254, 61
	v_readlane_b32 s7, v255, 1
	s_mul_hi_i32 s2, s6, 0x51000
	v_readlane_b32 s5, v254, 62
	s_add_u32 s4, s4, s3
	s_addc_u32 s5, s5, s2
	s_mul_hi_i32 s2, s6, 0x6000
	s_mul_i32 s3, s6, 0x6000
	s_load_dwordx2 s[6:7], s[0:1], 0x30
	s_movk_i32 s8, 0x6000
	s_mov_b32 s9, 0x51000
	s_movk_i32 s10, 0x7000
	v_xor_b32_e32 v0, 8, v216
	s_waitcnt lgkmcnt(0)
	s_add_u32 s6, s6, s3
	s_addc_u32 s7, s7, s2
	s_cmp_eq_u32 s91, 6
	s_cselect_b64 s[24:25], -1, 0
	s_and_b64 s[2:3], s[24:25], exec
	s_movk_i32 s3, 0x1400
	s_cselect_b32 s2, 0xc00, s3
	s_cselect_b32 s3, s3, 0x2000
	s_cselect_b32 s8, 0x4000, s8
	s_cselect_b32 s9, 0x6000, s9
	s_cselect_b32 s10, s10, 0x52000
	s_cmp_eq_u32 s91, 2
	s_cselect_b32 s8, 0x2000, s8
	s_cselect_b32 s9, 0x3000, s9
	s_cselect_b32 s10, 0x4000, s10
	s_cselect_b32 s2, 0x400, s2
	s_cselect_b32 s3, 0x800, s3
	s_add_u32 s26, s6, s8
	s_addc_u32 s27, s7, 0
	s_add_u32 s28, s4, s9
	s_addc_u32 s29, s5, 0
	s_add_u32 s30, s4, s10
	s_addc_u32 s31, s5, 0
	s_lshl_b32 s2, s2, 2
	s_add_u32 s34, s6, s2
	s_addc_u32 s35, s7, 0
	s_lshl_b32 s2, s3, 2
	s_add_u32 s36, s4, s2
	s_addc_u32 s37, s5, 0
	s_add_i32 s22, s38, s72
	s_waitcnt vmcnt(0)
	v_cndmask_b32_e64 v144, 0.5, 1.0, s[24:25]
	s_mov_b32 s52, s38
	s_cmpk_gt_i32 s22, 0x1fff
	v_cmp_lt_i32_e64 s[14:15], v226, v217
	v_cmp_lt_i32_e64 s[12:13], v246, v217
	v_cmp_lt_i32_e64 s[10:11], v247, v217
	v_cmp_lt_i32_e64 s[8:9], v0, v217
	v_cmp_lt_i32_e64 s[6:7], v222, v217
	v_cmp_lt_i32_e32 vcc, v223, v217
	s_cbranch_scc1 .LBB0_245
	s_cmp_lg_u64 s[18:19], 0
	s_cbranch_scc1 nrmx_orig
	s_cmp_eq_u64 s[16:17], 0
	s_cbranch_scc1 nrmx_orig
	s_cmpk_gt_i32 s22, 0x7ff
	s_cbranch_scc1 .LBB0_245
	s_mov_b32 s23, s22
	v_lshlrev_b32_e32 v184, 4, v196
	v_lshlrev_b32_e32 v182, 5, v196
	v_add_u32_e32 v184, 0x1000, v184
	v_readlane_b32 s14, v254, 59
	v_readlane_b32 s15, v254, 60
	v_add_u32_e32 v185, 0x200000, v184
	v_add_u32_e32 v186, 0x400000, v184
	v_add_u32_e32 v187, 0x600000, v184
nrmx_chunk:
	s_lshr_b32 s2, s23, 8
	s_and_b32 s3, s23, 0xff
	s_lshl_b32 s4, s2, 23
	s_lshl_b32 s3, s3, 13
	s_add_u32 s4, s4, s3
	s_add_u32 s42, s98, s4
	s_addc_u32 s43, s99, 0
	s_add_u32 s44, s14, s4
	s_addc_u32 s45, s15, 0
	s_mul_i32 s2, s2, 0x9000
	s_add_u32 s8, s36, s2
	s_addc_u32 s9, s37, 0
	s_add_u32 s10, s30, s2
	s_addc_u32 s11, s31, 0
	s_add_u32 s12, s28, s2
	s_addc_u32 s13, s29, 0
	global_load_dwordx4 v[0:3], v182, s[34:35]
	global_load_dwordx4 v[4:7], v182, s[34:35] offset:16
	global_load_dwordx4 v[8:11], v182, s[34:35] offset:2048
	global_load_dwordx4 v[12:15], v182, s[34:35] offset:2064
	global_load_dwordx4 v[116:119], v182, s[8:9]
	global_load_dwordx4 v[120:123], v182, s[8:9] offset:16
	global_load_dwordx4 v[124:127], v182, s[8:9] offset:2048
	global_load_dwordx4 v[128:131], v182, s[8:9] offset:2064
	global_load_dwordx4 v[16:19], v182, s[26:27]
	global_load_dwordx4 v[20:23], v182, s[26:27] offset:16
	global_load_dwordx4 v[24:27], v182, s[26:27] offset:2048
	global_load_dwordx4 v[28:31], v182, s[26:27] offset:2064
	global_load_dwordx4 v[32:35], v182, s[10:11]
	global_load_dwordx4 v[36:39], v182, s[10:11] offset:16
	global_load_dwordx4 v[40:43], v182, s[10:11] offset:2048
	global_load_dwordx4 v[44:47], v182, s[10:11] offset:2064
	global_load_dwordx4 v[48:51], v182, s[12:13]
	global_load_dwordx4 v[52:55], v182, s[12:13] offset:16
	global_load_dwordx4 v[56:59], v182, s[12:13] offset:2048
	global_load_dwordx4 v[60:63], v182, s[12:13] offset:2064
	global_load_dwordx4 v[64:67], v184, s[42:43] offset:-4096
	global_load_dwordx4 v[68:71], v184, s[42:43] offset:-3072
	global_load_dwordx4 v[148:151], v184, s[44:45] offset:-4096
	global_load_dwordx4 v[152:155], v184, s[44:45] offset:-3072
	global_load_dwordx4 v[72:75], v184, s[42:43] offset:-2048
	global_load_dwordx4 v[76:79], v184, s[42:43] offset:-1024
	global_load_dwordx4 v[156:159], v184, s[44:45] offset:-2048
	global_load_dwordx4 v[160:163], v184, s[44:45] offset:-1024
	global_load_dwordx4 v[80:83], v184, s[42:43] offset:0
	global_load_dwordx4 v[84:87], v184, s[42:43] offset:1024
	global_load_dwordx4 v[164:167], v184, s[44:45] offset:0
	global_load_dwordx4 v[168:171], v184, s[44:45] offset:1024
	global_load_dwordx4 v[88:91], v184, s[42:43] offset:2048
	global_load_dwordx4 v[92:95], v184, s[42:43] offset:3072
	global_load_dwordx4 v[172:175], v184, s[44:45] offset:2048
	global_load_dwordx4 v[176:179], v184, s[44:45] offset:3072
	s_waitcnt vmcnt(16)
	v_pk_mul_f32 v[0:1], v[0:1], v[116:117]
	v_pk_mul_f32 v[2:3], v[2:3], v[118:119]
	v_pk_mul_f32 v[4:5], v[4:5], v[120:121]
	v_pk_mul_f32 v[6:7], v[6:7], v[122:123]
	v_pk_mul_f32 v[8:9], v[8:9], v[124:125]
	v_pk_mul_f32 v[10:11], v[10:11], v[126:127]
	v_pk_mul_f32 v[12:13], v[12:13], v[128:129]
	v_pk_mul_f32 v[14:15], v[14:15], v[130:131]
	v_pk_add_f32 v[32:33], v[32:33], 1.0 op_sel_hi:[1,0]
	v_pk_add_f32 v[34:35], v[34:35], 1.0 op_sel_hi:[1,0]
	v_pk_add_f32 v[36:37], v[36:37], 1.0 op_sel_hi:[1,0]
	v_pk_add_f32 v[38:39], v[38:39], 1.0 op_sel_hi:[1,0]
	v_pk_add_f32 v[40:41], v[40:41], 1.0 op_sel_hi:[1,0]
	v_pk_add_f32 v[42:43], v[42:43], 1.0 op_sel_hi:[1,0]
	v_pk_add_f32 v[44:45], v[44:45], 1.0 op_sel_hi:[1,0]
	v_pk_add_f32 v[46:47], v[46:47], 1.0 op_sel_hi:[1,0]
	s_waitcnt vmcnt(12)
; template <int R, bool SRCB> ...
;     ...
;         for (int r = 0; r < R; ++r) {
;             f32x4 y[2][2]; float ss = 0.f;
; #pragma unroll
;             for (int j = 0; j < 2; ++j) { const u32x4 t = yr[r][j];
;                 y[j][0] = (f32x4){bf_lo(t.x), bf_hi(t.x), bf_lo(t.y), bf_hi(t.y)}; y[j][1] = (f32x4){bf_lo(t.z), bf_hi(t.z), bf_lo(t.w), bf_hi(t.w)};
;                 if (R == 1 && YP) {
; #pragma unroll
;                     for (int k = 0; k < 2; ++k) { const float* pp = YP + (size_t)(row0 - M_LAT) * DM + 8 * lane + 512 * j + 4 * k; f32x4 s = *(const f32x4*)pp;
; #pragma unroll
;                         for (int q = 1; q < pg8::NSL; ++q) s = s + *(const f32x4*)(pp + (size_t)q * 2048 * DM);
;                         y[j][k] = s; } }
; #pragma unroll
;                 for (int k = 0; k < 2; ++k) ss += (y[j][k][0] * y[j][k][0] + y[j][k][1] * y[j][k][1]) + (y[j][k][2] * y[j][k][2] + y[j][k][3] * y[j][k][3]); }
;             const float rr = __builtin_amdgcn_rsqf(wave_sum(ss) * (1.0f / DM) + 1e-6f) * w;
; #pragma unroll
;             for (int j = 0; j < 2; ++j)
; #pragma unroll
;                 for (int k = 0; k < 2; ++k) h[r][j][k] = h[r][j][k] + gg[j][k] * (y[j][k] * rr);
;         }
;     }
; #pragma unroll
;     for (int r = 0; r < R; ++r)
; #pragma unroll
;         for (int j = 0; j < 2; ++j) { const int c = 8 * lane + 512 * j;
;             if (final_out) { *(f32x4*)(final_out + (size_t)(row0 + r) * DM + c) = h[r][j][0]; *(f32x4*)(final_out + (size_t)(row0 + r) * DM + c + 4) = h[r][j][1]; }
;             else { u32x4 t; t.x = pkh2(h[r][j][0][0], h[r][j][0][1]); t.y = pkh2(h[r][j][0][2], h[r][j][0][3]); t.z = pkh2(h[r][j][1][0], h[r][j][1][1]); t.w = pkh2(h[r][j][1][2], h[r][j][1][3]);
;                 *(u32x4*)(hout + (size_t)(row0 + r) * DM + c) = t; } }
;     if (U) {
;         f32x4 gp[2][2], sc1[2][2], sh[2][2];
; #pragma unroll
;         for (int j = 0; j < 2; ++j)
; #pragma unroll
;             for (int k = 0; k < 2; ++k) { const int c = 8 * lane + 512 * j + 4 * k; gp[j][k] = *(const f32x4*)(gpre + c); sc1[j][k] = *(const f32x4*)(scale + (size_t)mrow * 9216 + c) + 1.0f; sh[j][k] = *(const f32x4*)(shift + (size_t)mrow * 9216 + c); }
; #pragma unroll
;         for (int r = 0; r < R; ++r) {
;             float ss = 0.f;
; #pragma unroll
;             for (int j = 0; j < 2; ++j)
; #pragma unroll
	v_lshlrev_b32_e32 v116, 16, v148
	v_and_b32_e32 v117, 0xffff0000, v148
	v_lshlrev_b32_e32 v118, 16, v149
	v_and_b32_e32 v119, 0xffff0000, v149
	v_lshlrev_b32_e32 v120, 16, v150
	v_and_b32_e32 v121, 0xffff0000, v150
	v_lshlrev_b32_e32 v122, 16, v151
	v_and_b32_e32 v123, 0xffff0000, v151
	v_lshlrev_b32_e32 v124, 16, v152
	v_and_b32_e32 v125, 0xffff0000, v152
	v_lshlrev_b32_e32 v126, 16, v153
	v_and_b32_e32 v127, 0xffff0000, v153
	v_lshlrev_b32_e32 v128, 16, v154
	v_and_b32_e32 v129, 0xffff0000, v154
	v_lshlrev_b32_e32 v130, 16, v155
	v_and_b32_e32 v131, 0xffff0000, v155
	v_cvt_f32_f16_e32 v198, v64
	v_cvt_f32_f16_sdwa v199, v64 dst_sel:DWORD dst_unused:UNUSED_PAD src0_sel:WORD_1
	v_cvt_f32_f16_e32 v200, v65
	v_cvt_f32_f16_sdwa v201, v65 dst_sel:DWORD dst_unused:UNUSED_PAD src0_sel:WORD_1
	v_cvt_f32_f16_e32 v202, v66
	v_cvt_f32_f16_sdwa v203, v66 dst_sel:DWORD dst_unused:UNUSED_PAD src0_sel:WORD_1
	v_cvt_f32_f16_e32 v204, v67
	v_cvt_f32_f16_sdwa v205, v67 dst_sel:DWORD dst_unused:UNUSED_PAD src0_sel:WORD_1
	v_cvt_f32_f16_e32 v206, v68
	v_cvt_f32_f16_sdwa v207, v68 dst_sel:DWORD dst_unused:UNUSED_PAD src0_sel:WORD_1
	v_cvt_f32_f16_e32 v208, v69
	v_cvt_f32_f16_sdwa v209, v69 dst_sel:DWORD dst_unused:UNUSED_PAD src0_sel:WORD_1
	v_cvt_f32_f16_e32 v210, v70
	v_cvt_f32_f16_sdwa v211, v70 dst_sel:DWORD dst_unused:UNUSED_PAD src0_sel:WORD_1
	v_cvt_f32_f16_e32 v212, v71
	v_cvt_f32_f16_sdwa v213, v71 dst_sel:DWORD dst_unused:UNUSED_PAD src0_sel:WORD_1
	global_load_dwordx4 v[64:67], v185, s[42:43] offset:-4096
	global_load_dwordx4 v[68:71], v185, s[42:43] offset:-3072
	global_load_dwordx4 v[148:151], v185, s[44:45] offset:-4096
	global_load_dwordx4 v[152:155], v185, s[44:45] offset:-3072
	v_pk_mul_f32 v[140:141], v[116:117], v[116:117]
	v_pk_fma_f32 v[140:141], v[118:119], v[118:119], v[140:141]
	v_pk_fma_f32 v[140:141], v[120:121], v[120:121], v[140:141]
	v_pk_fma_f32 v[140:141], v[122:123], v[122:123], v[140:141]
	v_pk_fma_f32 v[140:141], v[124:125], v[124:125], v[140:141]
	v_pk_fma_f32 v[140:141], v[126:127], v[126:127], v[140:141]
	v_pk_fma_f32 v[140:141], v[128:129], v[128:129], v[140:141]
	v_pk_fma_f32 v[140:141], v[130:131], v[130:131], v[140:141]
	v_add_f32_e32 v140, v140, v141
	s_nop 1
	v_add_f32_dpp v140, v140, v140 quad_perm:[1,0,3,2] row_mask:0xf bank_mask:0xf
	s_nop 1
	v_add_f32_dpp v140, v140, v140 quad_perm:[2,3,0,1] row_mask:0xf bank_mask:0xf
	s_nop 1
	v_add_f32_dpp v140, v140, v140 row_ror:4 row_mask:0xf bank_mask:0xf
	s_nop 1
	v_add_f32_dpp v140, v140, v140 row_ror:8 row_mask:0xf bank_mask:0xf
	s_nop 1
	v_add_f32_dpp v140, v140, v140 row_bcast:15 row_mask:0xa bank_mask:0xf
	s_nop 1
	v_add_f32_dpp v140, v140, v140 row_bcast:31 row_mask:0xc bank_mask:0xf
	s_nop 1
	v_fmamk_f32 v140, v140, 0x3a800000, v224
	v_rsq_f32_e32 v140, v140
	s_nop 0
	v_mul_f32_e32 v140, v144, v140
	s_nop 0
	v_readlane_b32 s4, v140, 63
	s_nop 1
	v_pk_mul_f32 v[116:117], v[116:117], s[4:5] op_sel_hi:[1,0]
	v_pk_mul_f32 v[118:119], v[118:119], s[4:5] op_sel_hi:[1,0]
	v_pk_mul_f32 v[120:121], v[120:121], s[4:5] op_sel_hi:[1,0]
	v_pk_mul_f32 v[122:123], v[122:123], s[4:5] op_sel_hi:[1,0]
	v_pk_mul_f32 v[124:125], v[124:125], s[4:5] op_sel_hi:[1,0]
	v_pk_mul_f32 v[126:127], v[126:127], s[4:5] op_sel_hi:[1,0]
	v_pk_mul_f32 v[128:129], v[128:129], s[4:5] op_sel_hi:[1,0]
	v_pk_mul_f32 v[130:131], v[130:131], s[4:5] op_sel_hi:[1,0]
	v_pk_fma_f32 v[198:199], v[0:1], v[116:117], v[198:199]
	v_pk_fma_f32 v[200:201], v[2:3], v[118:119], v[200:201]
	v_pk_fma_f32 v[202:203], v[4:5], v[120:121], v[202:203]
	v_pk_fma_f32 v[204:205], v[6:7], v[122:123], v[204:205]
	v_pk_fma_f32 v[206:207], v[8:9], v[124:125], v[206:207]
	v_pk_fma_f32 v[208:209], v[10:11], v[126:127], v[208:209]
	v_pk_fma_f32 v[210:211], v[12:13], v[128:129], v[210:211]
	v_pk_fma_f32 v[212:213], v[14:15], v[130:131], v[212:213]
	v_cvt_f16_f32_e32 v132, v198
	v_cvt_f16_f32_e32 v133, v200
	v_cvt_f16_f32_e32 v134, v202
	v_cvt_f16_f32_e32 v135, v204
	v_cvt_f16_f32_e32 v136, v206
	v_cvt_f16_f32_e32 v137, v208
	v_cvt_f16_f32_e32 v138, v210
	v_cvt_f16_f32_e32 v139, v212
	v_cvt_f16_f32_sdwa v132, v199 dst_sel:WORD_1 dst_unused:UNUSED_PRESERVE src0_sel:DWORD
	v_cvt_f16_f32_sdwa v133, v201 dst_sel:WORD_1 dst_unused:UNUSED_PRESERVE src0_sel:DWORD
	v_cvt_f16_f32_sdwa v134, v203 dst_sel:WORD_1 dst_unused:UNUSED_PRESERVE src0_sel:DWORD
	v_cvt_f16_f32_sdwa v135, v205 dst_sel:WORD_1 dst_unused:UNUSED_PRESERVE src0_sel:DWORD
	v_cvt_f16_f32_sdwa v136, v207 dst_sel:WORD_1 dst_unused:UNUSED_PRESERVE src0_sel:DWORD
	v_cvt_f16_f32_sdwa v137, v209 dst_sel:WORD_1 dst_unused:UNUSED_PRESERVE src0_sel:DWORD
	v_cvt_f16_f32_sdwa v138, v211 dst_sel:WORD_1 dst_unused:UNUSED_PRESERVE src0_sel:DWORD
	v_cvt_f16_f32_sdwa v139, v213 dst_sel:WORD_1 dst_unused:UNUSED_PRESERVE src0_sel:DWORD
	s_nop 0
	global_store_dwordx4 v184, v[132:135], s[42:43] offset:-4096
	global_store_dwordx4 v184, v[136:139], s[42:43] offset:-3072
	v_pk_mul_f32 v[140:141], v[198:199], v[198:199]
	v_pk_fma_f32 v[140:141], v[200:201], v[200:201], v[140:141]
	v_pk_fma_f32 v[140:141], v[202:203], v[202:203], v[140:141]
	v_pk_fma_f32 v[140:141], v[204:205], v[204:205], v[140:141]
	v_pk_fma_f32 v[140:141], v[206:207], v[206:207], v[140:141]
	v_pk_fma_f32 v[140:141], v[208:209], v[208:209], v[140:141]
	v_pk_fma_f32 v[140:141], v[210:211], v[210:211], v[140:141]
	v_pk_fma_f32 v[140:141], v[212:213], v[212:213], v[140:141]
	v_add_f32_e32 v140, v140, v141
	s_nop 1
	v_add_f32_dpp v140, v140, v140 quad_perm:[1,0,3,2] row_mask:0xf bank_mask:0xf
	s_nop 1
	v_add_f32_dpp v140, v140, v140 quad_perm:[2,3,0,1] row_mask:0xf bank_mask:0xf
	s_nop 1
	v_add_f32_dpp v140, v140, v140 row_ror:4 row_mask:0xf bank_mask:0xf
; template <int R, bool SRCB> ...
;     ...
;         for (int r = 0; r < R; ++r) {
;             f32x4 y[2][2]; float ss = 0.f;
; #pragma unroll
;             for (int j = 0; j < 2; ++j) { const u32x4 t = yr[r][j];
;                 y[j][0] = (f32x4){bf_lo(t.x), bf_hi(t.x), bf_lo(t.y), bf_hi(t.y)}; y[j][1] = (f32x4){bf_lo(t.z), bf_hi(t.z), bf_lo(t.w), bf_hi(t.w)};
;                 if (R == 1 && YP) {
; #pragma unroll
;                     for (int k = 0; k < 2; ++k) { const float* pp = YP + (size_t)(row0 - M_LAT) * DM + 8 * lane + 512 * j + 4 * k; f32x4 s = *(const f32x4*)pp;
; #pragma unroll
;                         for (int q = 1; q < pg8::NSL; ++q) s = s + *(const f32x4*)(pp + (size_t)q * 2048 * DM);
;                         y[j][k] = s; } }
; #pragma unroll
;                 for (int k = 0; k < 2; ++k) ss += (y[j][k][0] * y[j][k][0] + y[j][k][1] * y[j][k][1]) + (y[j][k][2] * y[j][k][2] + y[j][k][3] * y[j][k][3]); }
;             const float rr = __builtin_amdgcn_rsqf(wave_sum(ss) * (1.0f / DM) + 1e-6f) * w;
; #pragma unroll
;             for (int j = 0; j < 2; ++j)
; #pragma unroll
;                 for (int k = 0; k < 2; ++k) h[r][j][k] = h[r][j][k] + gg[j][k] * (y[j][k] * rr);
;         }
;     }
; #pragma unroll
;     for (int r = 0; r < R; ++r)
; #pragma unroll
;         for (int j = 0; j < 2; ++j) { const int c = 8 * lane + 512 * j;
;             if (final_out) { *(f32x4*)(final_out + (size_t)(row0 + r) * DM + c) = h[r][j][0]; *(f32x4*)(final_out + (size_t)(row0 + r) * DM + c + 4) = h[r][j][1]; }
;             else { u32x4 t; t.x = pkh2(h[r][j][0][0], h[r][j][0][1]); t.y = pkh2(h[r][j][0][2], h[r][j][0][3]); t.z = pkh2(h[r][j][1][0], h[r][j][1][1]); t.w = pkh2(h[r][j][1][2], h[r][j][1][3]);
;                 *(u32x4*)(hout + (size_t)(row0 + r) * DM + c) = t; } }
;     if (U) {
;         f32x4 gp[2][2], sc1[2][2], sh[2][2];
; #pragma unroll
;         for (int j = 0; j < 2; ++j)
; #pragma unroll
;             for (int k = 0; k < 2; ++k) { const int c = 8 * lane + 512 * j + 4 * k; gp[j][k] = *(const f32x4*)(gpre + c); sc1[j][k] = *(const f32x4*)(scale + (size_t)mrow * 9216 + c) + 1.0f; sh[j][k] = *(const f32x4*)(shift + (size_t)mrow * 9216 + c); }
; #pragma unroll
;         for (int r = 0; r < R; ++r) {
;             float ss = 0.f;
; #pragma unroll
;             for (int j = 0; j < 2; ++j)
; #pragma unroll
	s_nop 1
	v_add_f32_dpp v140, v140, v140 row_ror:8 row_mask:0xf bank_mask:0xf
	s_nop 1
	v_add_f32_dpp v140, v140, v140 row_bcast:15 row_mask:0xa bank_mask:0xf
	s_nop 1
	v_add_f32_dpp v140, v140, v140 row_bcast:31 row_mask:0xc bank_mask:0xf
	s_nop 1
	v_fmamk_f32 v140, v140, 0x3a800000, v224
	v_rsq_f32_e32 v140, v140
	s_nop 0
	v_readlane_b32 s6, v140, 63
	s_nop 1
	v_pk_mul_f32 v[198:199], v[198:199], s[6:7] op_sel_hi:[1,0]
	v_pk_mul_f32 v[200:201], v[200:201], s[6:7] op_sel_hi:[1,0]
	v_pk_mul_f32 v[202:203], v[202:203], s[6:7] op_sel_hi:[1,0]
	v_pk_mul_f32 v[204:205], v[204:205], s[6:7] op_sel_hi:[1,0]
	v_pk_mul_f32 v[206:207], v[206:207], s[6:7] op_sel_hi:[1,0]
	v_pk_mul_f32 v[208:209], v[208:209], s[6:7] op_sel_hi:[1,0]
	v_pk_mul_f32 v[210:211], v[210:211], s[6:7] op_sel_hi:[1,0]
	v_pk_mul_f32 v[212:213], v[212:213], s[6:7] op_sel_hi:[1,0]
	v_pk_mul_f32 v[198:199], v[16:17], v[198:199]
	v_pk_mul_f32 v[200:201], v[18:19], v[200:201]
	v_pk_mul_f32 v[202:203], v[20:21], v[202:203]
	v_pk_mul_f32 v[204:205], v[22:23], v[204:205]
	v_pk_mul_f32 v[206:207], v[24:25], v[206:207]
	v_pk_mul_f32 v[208:209], v[26:27], v[208:209]
	v_pk_mul_f32 v[210:211], v[28:29], v[210:211]
	v_pk_mul_f32 v[212:213], v[30:31], v[212:213]
	v_pk_fma_f32 v[198:199], v[32:33], v[198:199], v[48:49]
	v_pk_fma_f32 v[200:201], v[34:35], v[200:201], v[50:51]
	v_pk_fma_f32 v[202:203], v[36:37], v[202:203], v[52:53]
	v_pk_fma_f32 v[204:205], v[38:39], v[204:205], v[54:55]
	v_pk_fma_f32 v[206:207], v[40:41], v[206:207], v[56:57]
	v_pk_fma_f32 v[208:209], v[42:43], v[208:209], v[58:59]
	v_pk_fma_f32 v[210:211], v[44:45], v[210:211], v[60:61]
	v_pk_fma_f32 v[212:213], v[46:47], v[212:213], v[62:63]
	v_cvt_pk_bf16_f32 v230, v198, v199
	v_cvt_pk_bf16_f32 v231, v200, v201
	v_cvt_pk_bf16_f32 v232, v202, v203
	v_cvt_pk_bf16_f32 v233, v204, v205
	v_cvt_pk_bf16_f32 v234, v206, v207
	v_cvt_pk_bf16_f32 v235, v208, v209
	v_cvt_pk_bf16_f32 v236, v210, v211
	v_cvt_pk_bf16_f32 v237, v212, v213
	global_store_dwordx4 v184, v[230:233], s[44:45] offset:-4096
	global_store_dwordx4 v184, v[234:237], s[44:45] offset:-3072
	s_waitcnt vmcnt(16)
	v_lshlrev_b32_e32 v116, 16, v156
	v_and_b32_e32 v117, 0xffff0000, v156
	v_lshlrev_b32_e32 v118, 16, v157
	v_and_b32_e32 v119, 0xffff0000, v157
	v_lshlrev_b32_e32 v120, 16, v158
	v_and_b32_e32 v121, 0xffff0000, v158
	v_lshlrev_b32_e32 v122, 16, v159
	v_and_b32_e32 v123, 0xffff0000, v159
	v_lshlrev_b32_e32 v124, 16, v160
	v_and_b32_e32 v125, 0xffff0000, v160
	v_lshlrev_b32_e32 v126, 16, v161
	v_and_b32_e32 v127, 0xffff0000, v161
	v_lshlrev_b32_e32 v128, 16, v162
	v_and_b32_e32 v129, 0xffff0000, v162
	v_lshlrev_b32_e32 v130, 16, v163
	v_and_b32_e32 v131, 0xffff0000, v163
	v_cvt_f32_f16_e32 v198, v72
	v_cvt_f32_f16_sdwa v199, v72 dst_sel:DWORD dst_unused:UNUSED_PAD src0_sel:WORD_1
	v_cvt_f32_f16_e32 v200, v73
	v_cvt_f32_f16_sdwa v201, v73 dst_sel:DWORD dst_unused:UNUSED_PAD src0_sel:WORD_1
	v_cvt_f32_f16_e32 v202, v74
	v_cvt_f32_f16_sdwa v203, v74 dst_sel:DWORD dst_unused:UNUSED_PAD src0_sel:WORD_1
	v_cvt_f32_f16_e32 v204, v75
	v_cvt_f32_f16_sdwa v205, v75 dst_sel:DWORD dst_unused:UNUSED_PAD src0_sel:WORD_1
	v_cvt_f32_f16_e32 v206, v76
	v_cvt_f32_f16_sdwa v207, v76 dst_sel:DWORD dst_unused:UNUSED_PAD src0_sel:WORD_1
	v_cvt_f32_f16_e32 v208, v77
	v_cvt_f32_f16_sdwa v209, v77 dst_sel:DWORD dst_unused:UNUSED_PAD src0_sel:WORD_1
	v_cvt_f32_f16_e32 v210, v78
	v_cvt_f32_f16_sdwa v211, v78 dst_sel:DWORD dst_unused:UNUSED_PAD src0_sel:WORD_1
	v_cvt_f32_f16_e32 v212, v79
	v_cvt_f32_f16_sdwa v213, v79 dst_sel:DWORD dst_unused:UNUSED_PAD src0_sel:WORD_1
	global_load_dwordx4 v[72:75], v185, s[42:43] offset:-2048
	global_load_dwordx4 v[76:79], v185, s[42:43] offset:-1024
	global_load_dwordx4 v[156:159], v185, s[44:45] offset:-2048
	global_load_dwordx4 v[160:163], v185, s[44:45] offset:-1024
	v_pk_mul_f32 v[140:141], v[116:117], v[116:117]
	v_pk_fma_f32 v[140:141], v[118:119], v[118:119], v[140:141]
	v_pk_fma_f32 v[140:141], v[120:121], v[120:121], v[140:141]
	v_pk_fma_f32 v[140:141], v[122:123], v[122:123], v[140:141]
	v_pk_fma_f32 v[140:141], v[124:125], v[124:125], v[140:141]
	v_pk_fma_f32 v[140:141], v[126:127], v[126:127], v[140:141]
	v_pk_fma_f32 v[140:141], v[128:129], v[128:129], v[140:141]
	v_pk_fma_f32 v[140:141], v[130:131], v[130:131], v[140:141]
	v_add_f32_e32 v140, v140, v141
	s_nop 1
	v_add_f32_dpp v140, v140, v140 quad_perm:[1,0,3,2] row_mask:0xf bank_mask:0xf
	s_nop 1
	v_add_f32_dpp v140, v140, v140 quad_perm:[2,3,0,1] row_mask:0xf bank_mask:0xf
	s_nop 1
	v_add_f32_dpp v140, v140, v140 row_ror:4 row_mask:0xf bank_mask:0xf
	s_nop 1
	v_add_f32_dpp v140, v140, v140 row_ror:8 row_mask:0xf bank_mask:0xf
	s_nop 1
	v_add_f32_dpp v140, v140, v140 row_bcast:15 row_mask:0xa bank_mask:0xf
	s_nop 1
	v_add_f32_dpp v140, v140, v140 row_bcast:31 row_mask:0xc bank_mask:0xf
	s_nop 1
	v_fmamk_f32 v140, v140, 0x3a800000, v224
	v_rsq_f32_e32 v140, v140
	s_nop 0
	v_mul_f32_e32 v140, v144, v140
	s_nop 0
	v_readlane_b32 s4, v140, 63
	s_nop 1
	v_pk_mul_f32 v[116:117], v[116:117], s[4:5] op_sel_hi:[1,0]
	v_pk_mul_f32 v[118:119], v[118:119], s[4:5] op_sel_hi:[1,0]
	v_pk_mul_f32 v[120:121], v[120:121], s[4:5] op_sel_hi:[1,0]
	v_pk_mul_f32 v[122:123], v[122:123], s[4:5] op_sel_hi:[1,0]
	v_pk_mul_f32 v[124:125], v[124:125], s[4:5] op_sel_hi:[1,0]
	v_pk_mul_f32 v[126:127], v[126:127], s[4:5] op_sel_hi:[1,0]
	v_pk_mul_f32 v[128:129], v[128:129], s[4:5] op_sel_hi:[1,0]
	v_pk_mul_f32 v[130:131], v[130:131], s[4:5] op_sel_hi:[1,0]
	v_pk_fma_f32 v[198:199], v[0:1], v[116:117], v[198:199]
	v_pk_fma_f32 v[200:201], v[2:3], v[118:119], v[200:201]
	v_pk_fma_f32 v[202:203], v[4:5], v[120:121], v[202:203]
; __device__ __forceinline__ unsigned pk2(float lo, float hi) { return pg8::cvt_pk_bf16(lo, hi); }
; template <int R, bool SRCB> ...
;     ...
;             const float rr = __builtin_amdgcn_rsqf(wave_sum(ss) * (1.0f / DM) + 1e-6f) * w;
; #pragma unroll
;             for (int j = 0; j < 2; ++j)
; #pragma unroll
;                 for (int k = 0; k < 2; ++k) h[r][j][k] = h[r][j][k] + gg[j][k] * (y[j][k] * rr);
;         }
;     }
; #pragma unroll
;     for (int r = 0; r < R; ++r)
; #pragma unroll
;         for (int j = 0; j < 2; ++j) { const int c = 8 * lane + 512 * j;
;             if (final_out) { *(f32x4*)(final_out + (size_t)(row0 + r) * DM + c) = h[r][j][0]; *(f32x4*)(final_out + (size_t)(row0 + r) * DM + c + 4) = h[r][j][1]; }
;             else { u32x4 t; t.x = pkh2(h[r][j][0][0], h[r][j][0][1]); t.y = pkh2(h[r][j][0][2], h[r][j][0][3]); t.z = pkh2(h[r][j][1][0], h[r][j][1][1]); t.w = pkh2(h[r][j][1][2], h[r][j][1][3]);
;                 *(u32x4*)(hout + (size_t)(row0 + r) * DM + c) = t; } }
;     if (U) {
;         f32x4 gp[2][2], sc1[2][2], sh[2][2];
; #pragma unroll
;         for (int j = 0; j < 2; ++j)
; #pragma unroll
;             for (int k = 0; k < 2; ++k) { const int c = 8 * lane + 512 * j + 4 * k; gp[j][k] = *(const f32x4*)(gpre + c); sc1[j][k] = *(const f32x4*)(scale + (size_t)mrow * 9216 + c) + 1.0f; sh[j][k] = *(const f32x4*)(shift + (size_t)mrow * 9216 + c); }
; #pragma unroll
;         for (int r = 0; r < R; ++r) {
;             float ss = 0.f;
; #pragma unroll
;             for (int j = 0; j < 2; ++j)
; #pragma unroll
;                 for (int k = 0; k < 2; ++k) ss += (h[r][j][k][0] * h[r][j][k][0] + h[r][j][k][1] * h[r][j][k][1]) + (h[r][j][k][2] * h[r][j][k][2] + h[r][j][k][3] * h[r][j][k][3]);
;             const float rr = __builtin_amdgcn_rsqf(wave_sum(ss) * (1.0f / DM) + 1e-6f);
; #pragma unroll
;             for (int j = 0; j < 2; ++j) { const f32x4 v0 = (h[r][j][0] * rr * gp[j][0]) * sc1[j][0] + sh[j][0], v1 = (h[r][j][1] * rr * gp[j][1]) * sc1[j][1] + sh[j][1];
;                 u32x4 t; t.x = pk2(v0[0], v0[1]); t.y = pk2(v0[2], v0[3]); t.z = pk2(v1[0], v1[1]); t.w = pk2(v1[2], v1[3]);
;                 *(u32x4*)(U + (size_t)(row0 + r) * DM + 8 * lane + 512 * j) = t; }
	v_pk_fma_f32 v[204:205], v[6:7], v[122:123], v[204:205]
	v_pk_fma_f32 v[206:207], v[8:9], v[124:125], v[206:207]
	v_pk_fma_f32 v[208:209], v[10:11], v[126:127], v[208:209]
	v_pk_fma_f32 v[210:211], v[12:13], v[128:129], v[210:211]
	v_pk_fma_f32 v[212:213], v[14:15], v[130:131], v[212:213]
	v_cvt_f16_f32_e32 v132, v198
	v_cvt_f16_f32_e32 v133, v200
	v_cvt_f16_f32_e32 v134, v202
	v_cvt_f16_f32_e32 v135, v204
	v_cvt_f16_f32_e32 v136, v206
	v_cvt_f16_f32_e32 v137, v208
	v_cvt_f16_f32_e32 v138, v210
	v_cvt_f16_f32_e32 v139, v212
	v_cvt_f16_f32_sdwa v132, v199 dst_sel:WORD_1 dst_unused:UNUSED_PRESERVE src0_sel:DWORD
	v_cvt_f16_f32_sdwa v133, v201 dst_sel:WORD_1 dst_unused:UNUSED_PRESERVE src0_sel:DWORD
	v_cvt_f16_f32_sdwa v134, v203 dst_sel:WORD_1 dst_unused:UNUSED_PRESERVE src0_sel:DWORD
	v_cvt_f16_f32_sdwa v135, v205 dst_sel:WORD_1 dst_unused:UNUSED_PRESERVE src0_sel:DWORD
	v_cvt_f16_f32_sdwa v136, v207 dst_sel:WORD_1 dst_unused:UNUSED_PRESERVE src0_sel:DWORD
	v_cvt_f16_f32_sdwa v137, v209 dst_sel:WORD_1 dst_unused:UNUSED_PRESERVE src0_sel:DWORD
	v_cvt_f16_f32_sdwa v138, v211 dst_sel:WORD_1 dst_unused:UNUSED_PRESERVE src0_sel:DWORD
	v_cvt_f16_f32_sdwa v139, v213 dst_sel:WORD_1 dst_unused:UNUSED_PRESERVE src0_sel:DWORD
	s_nop 0
	global_store_dwordx4 v184, v[132:135], s[42:43] offset:-2048
	global_store_dwordx4 v184, v[136:139], s[42:43] offset:-1024
	v_pk_mul_f32 v[140:141], v[198:199], v[198:199]
	v_pk_fma_f32 v[140:141], v[200:201], v[200:201], v[140:141]
	v_pk_fma_f32 v[140:141], v[202:203], v[202:203], v[140:141]
	v_pk_fma_f32 v[140:141], v[204:205], v[204:205], v[140:141]
	v_pk_fma_f32 v[140:141], v[206:207], v[206:207], v[140:141]
	v_pk_fma_f32 v[140:141], v[208:209], v[208:209], v[140:141]
	v_pk_fma_f32 v[140:141], v[210:211], v[210:211], v[140:141]
	v_pk_fma_f32 v[140:141], v[212:213], v[212:213], v[140:141]
	v_add_f32_e32 v140, v140, v141
	s_nop 1
	v_add_f32_dpp v140, v140, v140 quad_perm:[1,0,3,2] row_mask:0xf bank_mask:0xf
	s_nop 1
	v_add_f32_dpp v140, v140, v140 quad_perm:[2,3,0,1] row_mask:0xf bank_mask:0xf
	s_nop 1
	v_add_f32_dpp v140, v140, v140 row_ror:4 row_mask:0xf bank_mask:0xf
	s_nop 1
	v_add_f32_dpp v140, v140, v140 row_ror:8 row_mask:0xf bank_mask:0xf
	s_nop 1
	v_add_f32_dpp v140, v140, v140 row_bcast:15 row_mask:0xa bank_mask:0xf
	s_nop 1
	v_add_f32_dpp v140, v140, v140 row_bcast:31 row_mask:0xc bank_mask:0xf
	s_nop 1
	v_fmamk_f32 v140, v140, 0x3a800000, v224
	v_rsq_f32_e32 v140, v140
	s_nop 0
	v_readlane_b32 s6, v140, 63
	s_nop 1
	v_pk_mul_f32 v[198:199], v[198:199], s[6:7] op_sel_hi:[1,0]
	v_pk_mul_f32 v[200:201], v[200:201], s[6:7] op_sel_hi:[1,0]
	v_pk_mul_f32 v[202:203], v[202:203], s[6:7] op_sel_hi:[1,0]
	v_pk_mul_f32 v[204:205], v[204:205], s[6:7] op_sel_hi:[1,0]
	v_pk_mul_f32 v[206:207], v[206:207], s[6:7] op_sel_hi:[1,0]
	v_pk_mul_f32 v[208:209], v[208:209], s[6:7] op_sel_hi:[1,0]
	v_pk_mul_f32 v[210:211], v[210:211], s[6:7] op_sel_hi:[1,0]
	v_pk_mul_f32 v[212:213], v[212:213], s[6:7] op_sel_hi:[1,0]
	v_pk_mul_f32 v[198:199], v[16:17], v[198:199]
	v_pk_mul_f32 v[200:201], v[18:19], v[200:201]
	v_pk_mul_f32 v[202:203], v[20:21], v[202:203]
	v_pk_mul_f32 v[204:205], v[22:23], v[204:205]
	v_pk_mul_f32 v[206:207], v[24:25], v[206:207]
	v_pk_mul_f32 v[208:209], v[26:27], v[208:209]
	v_pk_mul_f32 v[210:211], v[28:29], v[210:211]
	v_pk_mul_f32 v[212:213], v[30:31], v[212:213]
	v_pk_fma_f32 v[198:199], v[32:33], v[198:199], v[48:49]
	v_pk_fma_f32 v[200:201], v[34:35], v[200:201], v[50:51]
	v_pk_fma_f32 v[202:203], v[36:37], v[202:203], v[52:53]
	v_pk_fma_f32 v[204:205], v[38:39], v[204:205], v[54:55]
	v_pk_fma_f32 v[206:207], v[40:41], v[206:207], v[56:57]
	v_pk_fma_f32 v[208:209], v[42:43], v[208:209], v[58:59]
	v_pk_fma_f32 v[210:211], v[44:45], v[210:211], v[60:61]
	v_pk_fma_f32 v[212:213], v[46:47], v[212:213], v[62:63]
	v_cvt_pk_bf16_f32 v230, v198, v199
	v_cvt_pk_bf16_f32 v231, v200, v201
	v_cvt_pk_bf16_f32 v232, v202, v203
	v_cvt_pk_bf16_f32 v233, v204, v205
	v_cvt_pk_bf16_f32 v234, v206, v207
	v_cvt_pk_bf16_f32 v235, v208, v209
	v_cvt_pk_bf16_f32 v236, v210, v211
	v_cvt_pk_bf16_f32 v237, v212, v213
	global_store_dwordx4 v184, v[230:233], s[44:45] offset:-2048
	global_store_dwordx4 v184, v[234:237], s[44:45] offset:-1024
	s_waitcnt vmcnt(20)
; template <int R, bool SRCB> ...
;     ...
;         for (int r = 0; r < R; ++r) {
;             f32x4 y[2][2]; float ss = 0.f;
; #pragma unroll
;             for (int j = 0; j < 2; ++j) { const u32x4 t = yr[r][j];
;                 y[j][0] = (f32x4){bf_lo(t.x), bf_hi(t.x), bf_lo(t.y), bf_hi(t.y)}; y[j][1] = (f32x4){bf_lo(t.z), bf_hi(t.z), bf_lo(t.w), bf_hi(t.w)};
;                 if (R == 1 && YP) {
; #pragma unroll
;                     for (int k = 0; k < 2; ++k) { const float* pp = YP + (size_t)(row0 - M_LAT) * DM + 8 * lane + 512 * j + 4 * k; f32x4 s = *(const f32x4*)pp;
; #pragma unroll
;                         for (int q = 1; q < pg8::NSL; ++q) s = s + *(const f32x4*)(pp + (size_t)q * 2048 * DM);
;                         y[j][k] = s; } }
; #pragma unroll
;                 for (int k = 0; k < 2; ++k) ss += (y[j][k][0] * y[j][k][0] + y[j][k][1] * y[j][k][1]) + (y[j][k][2] * y[j][k][2] + y[j][k][3] * y[j][k][3]); }
;             const float rr = __builtin_amdgcn_rsqf(wave_sum(ss) * (1.0f / DM) + 1e-6f) * w;
; #pragma unroll
;             for (int j = 0; j < 2; ++j)
; #pragma unroll
;                 for (int k = 0; k < 2; ++k) h[r][j][k] = h[r][j][k] + gg[j][k] * (y[j][k] * rr);
;         }
;     }
; #pragma unroll
;     for (int r = 0; r < R; ++r)
; #pragma unroll
;         for (int j = 0; j < 2; ++j) { const int c = 8 * lane + 512 * j;
;             if (final_out) { *(f32x4*)(final_out + (size_t)(row0 + r) * DM + c) = h[r][j][0]; *(f32x4*)(final_out + (size_t)(row0 + r) * DM + c + 4) = h[r][j][1]; }
;             else { u32x4 t; t.x = pkh2(h[r][j][0][0], h[r][j][0][1]); t.y = pkh2(h[r][j][0][2], h[r][j][0][3]); t.z = pkh2(h[r][j][1][0], h[r][j][1][1]); t.w = pkh2(h[r][j][1][2], h[r][j][1][3]);
;                 *(u32x4*)(hout + (size_t)(row0 + r) * DM + c) = t; } }
;     if (U) {
;         f32x4 gp[2][2], sc1[2][2], sh[2][2];
; #pragma unroll
;         for (int j = 0; j < 2; ++j)
; #pragma unroll
;             for (int k = 0; k < 2; ++k) { const int c = 8 * lane + 512 * j + 4 * k; gp[j][k] = *(const f32x4*)(gpre + c); sc1[j][k] = *(const f32x4*)(scale + (size_t)mrow * 9216 + c) + 1.0f; sh[j][k] = *(const f32x4*)(shift + (size_t)mrow * 9216 + c); }
; #pragma unroll
;         for (int r = 0; r < R; ++r) {
;             float ss = 0.f;
; #pragma unroll
;             for (int j = 0; j < 2; ++j)
; #pragma unroll
	v_lshlrev_b32_e32 v116, 16, v164
	v_and_b32_e32 v117, 0xffff0000, v164
	v_lshlrev_b32_e32 v118, 16, v165
	v_and_b32_e32 v119, 0xffff0000, v165
	v_lshlrev_b32_e32 v120, 16, v166
	v_and_b32_e32 v121, 0xffff0000, v166
	v_lshlrev_b32_e32 v122, 16, v167
	v_and_b32_e32 v123, 0xffff0000, v167
	v_lshlrev_b32_e32 v124, 16, v168
	v_and_b32_e32 v125, 0xffff0000, v168
	v_lshlrev_b32_e32 v126, 16, v169
	v_and_b32_e32 v127, 0xffff0000, v169
	v_lshlrev_b32_e32 v128, 16, v170
	v_and_b32_e32 v129, 0xffff0000, v170
	v_lshlrev_b32_e32 v130, 16, v171
	v_and_b32_e32 v131, 0xffff0000, v171
	v_cvt_f32_f16_e32 v198, v80
	v_cvt_f32_f16_sdwa v199, v80 dst_sel:DWORD dst_unused:UNUSED_PAD src0_sel:WORD_1
	v_cvt_f32_f16_e32 v200, v81
	v_cvt_f32_f16_sdwa v201, v81 dst_sel:DWORD dst_unused:UNUSED_PAD src0_sel:WORD_1
	v_cvt_f32_f16_e32 v202, v82
	v_cvt_f32_f16_sdwa v203, v82 dst_sel:DWORD dst_unused:UNUSED_PAD src0_sel:WORD_1
	v_cvt_f32_f16_e32 v204, v83
	v_cvt_f32_f16_sdwa v205, v83 dst_sel:DWORD dst_unused:UNUSED_PAD src0_sel:WORD_1
	v_cvt_f32_f16_e32 v206, v84
	v_cvt_f32_f16_sdwa v207, v84 dst_sel:DWORD dst_unused:UNUSED_PAD src0_sel:WORD_1
	v_cvt_f32_f16_e32 v208, v85
	v_cvt_f32_f16_sdwa v209, v85 dst_sel:DWORD dst_unused:UNUSED_PAD src0_sel:WORD_1
	v_cvt_f32_f16_e32 v210, v86
	v_cvt_f32_f16_sdwa v211, v86 dst_sel:DWORD dst_unused:UNUSED_PAD src0_sel:WORD_1
	v_cvt_f32_f16_e32 v212, v87
	v_cvt_f32_f16_sdwa v213, v87 dst_sel:DWORD dst_unused:UNUSED_PAD src0_sel:WORD_1
	global_load_dwordx4 v[80:83], v185, s[42:43] offset:0
	global_load_dwordx4 v[84:87], v185, s[42:43] offset:1024
	global_load_dwordx4 v[164:167], v185, s[44:45] offset:0
	global_load_dwordx4 v[168:171], v185, s[44:45] offset:1024
	v_pk_mul_f32 v[140:141], v[116:117], v[116:117]
	v_pk_fma_f32 v[140:141], v[118:119], v[118:119], v[140:141]
	v_pk_fma_f32 v[140:141], v[120:121], v[120:121], v[140:141]
	v_pk_fma_f32 v[140:141], v[122:123], v[122:123], v[140:141]
	v_pk_fma_f32 v[140:141], v[124:125], v[124:125], v[140:141]
	v_pk_fma_f32 v[140:141], v[126:127], v[126:127], v[140:141]
	v_pk_fma_f32 v[140:141], v[128:129], v[128:129], v[140:141]
	v_pk_fma_f32 v[140:141], v[130:131], v[130:131], v[140:141]
	v_add_f32_e32 v140, v140, v141
	s_nop 1
	v_add_f32_dpp v140, v140, v140 quad_perm:[1,0,3,2] row_mask:0xf bank_mask:0xf
	s_nop 1
	v_add_f32_dpp v140, v140, v140 quad_perm:[2,3,0,1] row_mask:0xf bank_mask:0xf
	s_nop 1
	v_add_f32_dpp v140, v140, v140 row_ror:4 row_mask:0xf bank_mask:0xf
	s_nop 1
	v_add_f32_dpp v140, v140, v140 row_ror:8 row_mask:0xf bank_mask:0xf
	s_nop 1
	v_add_f32_dpp v140, v140, v140 row_bcast:15 row_mask:0xa bank_mask:0xf
	s_nop 1
	v_add_f32_dpp v140, v140, v140 row_bcast:31 row_mask:0xc bank_mask:0xf
	s_nop 1
	v_fmamk_f32 v140, v140, 0x3a800000, v224
	v_rsq_f32_e32 v140, v140
	s_nop 0
	v_mul_f32_e32 v140, v144, v140
	s_nop 0
	v_readlane_b32 s4, v140, 63
	s_nop 1
	v_pk_mul_f32 v[116:117], v[116:117], s[4:5] op_sel_hi:[1,0]
	v_pk_mul_f32 v[118:119], v[118:119], s[4:5] op_sel_hi:[1,0]
	v_pk_mul_f32 v[120:121], v[120:121], s[4:5] op_sel_hi:[1,0]
	v_pk_mul_f32 v[122:123], v[122:123], s[4:5] op_sel_hi:[1,0]
	v_pk_mul_f32 v[124:125], v[124:125], s[4:5] op_sel_hi:[1,0]
	v_pk_mul_f32 v[126:127], v[126:127], s[4:5] op_sel_hi:[1,0]
	v_pk_mul_f32 v[128:129], v[128:129], s[4:5] op_sel_hi:[1,0]
	v_pk_mul_f32 v[130:131], v[130:131], s[4:5] op_sel_hi:[1,0]
	v_pk_fma_f32 v[198:199], v[0:1], v[116:117], v[198:199]
	v_pk_fma_f32 v[200:201], v[2:3], v[118:119], v[200:201]
	v_pk_fma_f32 v[202:203], v[4:5], v[120:121], v[202:203]
	v_pk_fma_f32 v[204:205], v[6:7], v[122:123], v[204:205]
	v_pk_fma_f32 v[206:207], v[8:9], v[124:125], v[206:207]
	v_pk_fma_f32 v[208:209], v[10:11], v[126:127], v[208:209]
	v_pk_fma_f32 v[210:211], v[12:13], v[128:129], v[210:211]
	v_pk_fma_f32 v[212:213], v[14:15], v[130:131], v[212:213]
	v_cvt_f16_f32_e32 v132, v198
	v_cvt_f16_f32_e32 v133, v200
	v_cvt_f16_f32_e32 v134, v202
	v_cvt_f16_f32_e32 v135, v204
	v_cvt_f16_f32_e32 v136, v206
	v_cvt_f16_f32_e32 v137, v208
	v_cvt_f16_f32_e32 v138, v210
	v_cvt_f16_f32_e32 v139, v212
	v_cvt_f16_f32_sdwa v132, v199 dst_sel:WORD_1 dst_unused:UNUSED_PRESERVE src0_sel:DWORD
	v_cvt_f16_f32_sdwa v133, v201 dst_sel:WORD_1 dst_unused:UNUSED_PRESERVE src0_sel:DWORD
	v_cvt_f16_f32_sdwa v134, v203 dst_sel:WORD_1 dst_unused:UNUSED_PRESERVE src0_sel:DWORD
	v_cvt_f16_f32_sdwa v135, v205 dst_sel:WORD_1 dst_unused:UNUSED_PRESERVE src0_sel:DWORD
	v_cvt_f16_f32_sdwa v136, v207 dst_sel:WORD_1 dst_unused:UNUSED_PRESERVE src0_sel:DWORD
	v_cvt_f16_f32_sdwa v137, v209 dst_sel:WORD_1 dst_unused:UNUSED_PRESERVE src0_sel:DWORD
	v_cvt_f16_f32_sdwa v138, v211 dst_sel:WORD_1 dst_unused:UNUSED_PRESERVE src0_sel:DWORD
	v_cvt_f16_f32_sdwa v139, v213 dst_sel:WORD_1 dst_unused:UNUSED_PRESERVE src0_sel:DWORD
	s_nop 0
	global_store_dwordx4 v184, v[132:135], s[42:43] offset:0
	global_store_dwordx4 v184, v[136:139], s[42:43] offset:1024
	v_pk_mul_f32 v[140:141], v[198:199], v[198:199]
	v_pk_fma_f32 v[140:141], v[200:201], v[200:201], v[140:141]
	v_pk_fma_f32 v[140:141], v[202:203], v[202:203], v[140:141]
	v_pk_fma_f32 v[140:141], v[204:205], v[204:205], v[140:141]
	v_pk_fma_f32 v[140:141], v[206:207], v[206:207], v[140:141]
	v_pk_fma_f32 v[140:141], v[208:209], v[208:209], v[140:141]
	v_pk_fma_f32 v[140:141], v[210:211], v[210:211], v[140:141]
	v_pk_fma_f32 v[140:141], v[212:213], v[212:213], v[140:141]
	v_add_f32_e32 v140, v140, v141
	s_nop 1
	v_add_f32_dpp v140, v140, v140 quad_perm:[1,0,3,2] row_mask:0xf bank_mask:0xf
	s_nop 1
	v_add_f32_dpp v140, v140, v140 quad_perm:[2,3,0,1] row_mask:0xf bank_mask:0xf
	s_nop 1
	v_add_f32_dpp v140, v140, v140 row_ror:4 row_mask:0xf bank_mask:0xf
; template <int R, bool SRCB> ...
;     ...
;         for (int r = 0; r < R; ++r) {
;             f32x4 y[2][2]; float ss = 0.f;
; #pragma unroll
;             for (int j = 0; j < 2; ++j) { const u32x4 t = yr[r][j];
;                 y[j][0] = (f32x4){bf_lo(t.x), bf_hi(t.x), bf_lo(t.y), bf_hi(t.y)}; y[j][1] = (f32x4){bf_lo(t.z), bf_hi(t.z), bf_lo(t.w), bf_hi(t.w)};
;                 if (R == 1 && YP) {
; #pragma unroll
;                     for (int k = 0; k < 2; ++k) { const float* pp = YP + (size_t)(row0 - M_LAT) * DM + 8 * lane + 512 * j + 4 * k; f32x4 s = *(const f32x4*)pp;
; #pragma unroll
;                         for (int q = 1; q < pg8::NSL; ++q) s = s + *(const f32x4*)(pp + (size_t)q * 2048 * DM);
;                         y[j][k] = s; } }
; #pragma unroll
;                 for (int k = 0; k < 2; ++k) ss += (y[j][k][0] * y[j][k][0] + y[j][k][1] * y[j][k][1]) + (y[j][k][2] * y[j][k][2] + y[j][k][3] * y[j][k][3]); }
;             const float rr = __builtin_amdgcn_rsqf(wave_sum(ss) * (1.0f / DM) + 1e-6f) * w;
; #pragma unroll
;             for (int j = 0; j < 2; ++j)
; #pragma unroll
;                 for (int k = 0; k < 2; ++k) h[r][j][k] = h[r][j][k] + gg[j][k] * (y[j][k] * rr);
;         }
;     }
; #pragma unroll
;     for (int r = 0; r < R; ++r)
; #pragma unroll
;         for (int j = 0; j < 2; ++j) { const int c = 8 * lane + 512 * j;
;             if (final_out) { *(f32x4*)(final_out + (size_t)(row0 + r) * DM + c) = h[r][j][0]; *(f32x4*)(final_out + (size_t)(row0 + r) * DM + c + 4) = h[r][j][1]; }
;             else { u32x4 t; t.x = pkh2(h[r][j][0][0], h[r][j][0][1]); t.y = pkh2(h[r][j][0][2], h[r][j][0][3]); t.z = pkh2(h[r][j][1][0], h[r][j][1][1]); t.w = pkh2(h[r][j][1][2], h[r][j][1][3]);
;                 *(u32x4*)(hout + (size_t)(row0 + r) * DM + c) = t; } }
;     if (U) {
;         f32x4 gp[2][2], sc1[2][2], sh[2][2];
; #pragma unroll
;         for (int j = 0; j < 2; ++j)
; #pragma unroll
;             for (int k = 0; k < 2; ++k) { const int c = 8 * lane + 512 * j + 4 * k; gp[j][k] = *(const f32x4*)(gpre + c); sc1[j][k] = *(const f32x4*)(scale + (size_t)mrow * 9216 + c) + 1.0f; sh[j][k] = *(const f32x4*)(shift + (size_t)mrow * 9216 + c); }
; #pragma unroll
;         for (int r = 0; r < R; ++r) {
;             float ss = 0.f;
; #pragma unroll
;             for (int j = 0; j < 2; ++j)
; #pragma unroll
	s_nop 1
	v_add_f32_dpp v140, v140, v140 row_ror:8 row_mask:0xf bank_mask:0xf
	s_nop 1
	v_add_f32_dpp v140, v140, v140 row_bcast:15 row_mask:0xa bank_mask:0xf
	s_nop 1
	v_add_f32_dpp v140, v140, v140 row_bcast:31 row_mask:0xc bank_mask:0xf
	s_nop 1
	v_fmamk_f32 v140, v140, 0x3a800000, v224
	v_rsq_f32_e32 v140, v140
	s_nop 0
	v_readlane_b32 s6, v140, 63
	s_nop 1
	v_pk_mul_f32 v[198:199], v[198:199], s[6:7] op_sel_hi:[1,0]
	v_pk_mul_f32 v[200:201], v[200:201], s[6:7] op_sel_hi:[1,0]
	v_pk_mul_f32 v[202:203], v[202:203], s[6:7] op_sel_hi:[1,0]
	v_pk_mul_f32 v[204:205], v[204:205], s[6:7] op_sel_hi:[1,0]
	v_pk_mul_f32 v[206:207], v[206:207], s[6:7] op_sel_hi:[1,0]
	v_pk_mul_f32 v[208:209], v[208:209], s[6:7] op_sel_hi:[1,0]
	v_pk_mul_f32 v[210:211], v[210:211], s[6:7] op_sel_hi:[1,0]
	v_pk_mul_f32 v[212:213], v[212:213], s[6:7] op_sel_hi:[1,0]
	v_pk_mul_f32 v[198:199], v[16:17], v[198:199]
	v_pk_mul_f32 v[200:201], v[18:19], v[200:201]
	v_pk_mul_f32 v[202:203], v[20:21], v[202:203]
	v_pk_mul_f32 v[204:205], v[22:23], v[204:205]
	v_pk_mul_f32 v[206:207], v[24:25], v[206:207]
	v_pk_mul_f32 v[208:209], v[26:27], v[208:209]
	v_pk_mul_f32 v[210:211], v[28:29], v[210:211]
	v_pk_mul_f32 v[212:213], v[30:31], v[212:213]
	v_pk_fma_f32 v[198:199], v[32:33], v[198:199], v[48:49]
	v_pk_fma_f32 v[200:201], v[34:35], v[200:201], v[50:51]
	v_pk_fma_f32 v[202:203], v[36:37], v[202:203], v[52:53]
	v_pk_fma_f32 v[204:205], v[38:39], v[204:205], v[54:55]
	v_pk_fma_f32 v[206:207], v[40:41], v[206:207], v[56:57]
	v_pk_fma_f32 v[208:209], v[42:43], v[208:209], v[58:59]
	v_pk_fma_f32 v[210:211], v[44:45], v[210:211], v[60:61]
	v_pk_fma_f32 v[212:213], v[46:47], v[212:213], v[62:63]
	v_cvt_pk_bf16_f32 v230, v198, v199
	v_cvt_pk_bf16_f32 v231, v200, v201
	v_cvt_pk_bf16_f32 v232, v202, v203
	v_cvt_pk_bf16_f32 v233, v204, v205
	v_cvt_pk_bf16_f32 v234, v206, v207
	v_cvt_pk_bf16_f32 v235, v208, v209
	v_cvt_pk_bf16_f32 v236, v210, v211
	v_cvt_pk_bf16_f32 v237, v212, v213
	global_store_dwordx4 v184, v[230:233], s[44:45] offset:0
	global_store_dwordx4 v184, v[234:237], s[44:45] offset:1024
	s_waitcnt vmcnt(24)
	v_lshlrev_b32_e32 v116, 16, v172
	v_and_b32_e32 v117, 0xffff0000, v172
	v_lshlrev_b32_e32 v118, 16, v173
	v_and_b32_e32 v119, 0xffff0000, v173
	v_lshlrev_b32_e32 v120, 16, v174
	v_and_b32_e32 v121, 0xffff0000, v174
	v_lshlrev_b32_e32 v122, 16, v175
	v_and_b32_e32 v123, 0xffff0000, v175
	v_lshlrev_b32_e32 v124, 16, v176
	v_and_b32_e32 v125, 0xffff0000, v176
	v_lshlrev_b32_e32 v126, 16, v177
	v_and_b32_e32 v127, 0xffff0000, v177
	v_lshlrev_b32_e32 v128, 16, v178
	v_and_b32_e32 v129, 0xffff0000, v178
	v_lshlrev_b32_e32 v130, 16, v179
	v_and_b32_e32 v131, 0xffff0000, v179
	v_cvt_f32_f16_e32 v198, v88
	v_cvt_f32_f16_sdwa v199, v88 dst_sel:DWORD dst_unused:UNUSED_PAD src0_sel:WORD_1
	v_cvt_f32_f16_e32 v200, v89
	v_cvt_f32_f16_sdwa v201, v89 dst_sel:DWORD dst_unused:UNUSED_PAD src0_sel:WORD_1
	v_cvt_f32_f16_e32 v202, v90
	v_cvt_f32_f16_sdwa v203, v90 dst_sel:DWORD dst_unused:UNUSED_PAD src0_sel:WORD_1
	v_cvt_f32_f16_e32 v204, v91
	v_cvt_f32_f16_sdwa v205, v91 dst_sel:DWORD dst_unused:UNUSED_PAD src0_sel:WORD_1
	v_cvt_f32_f16_e32 v206, v92
	v_cvt_f32_f16_sdwa v207, v92 dst_sel:DWORD dst_unused:UNUSED_PAD src0_sel:WORD_1
	v_cvt_f32_f16_e32 v208, v93
	v_cvt_f32_f16_sdwa v209, v93 dst_sel:DWORD dst_unused:UNUSED_PAD src0_sel:WORD_1
	v_cvt_f32_f16_e32 v210, v94
	v_cvt_f32_f16_sdwa v211, v94 dst_sel:DWORD dst_unused:UNUSED_PAD src0_sel:WORD_1
	v_cvt_f32_f16_e32 v212, v95
	v_cvt_f32_f16_sdwa v213, v95 dst_sel:DWORD dst_unused:UNUSED_PAD src0_sel:WORD_1
	global_load_dwordx4 v[88:91], v185, s[42:43] offset:2048
	global_load_dwordx4 v[92:95], v185, s[42:43] offset:3072
	global_load_dwordx4 v[172:175], v185, s[44:45] offset:2048
	global_load_dwordx4 v[176:179], v185, s[44:45] offset:3072
	v_pk_mul_f32 v[140:141], v[116:117], v[116:117]
	v_pk_fma_f32 v[140:141], v[118:119], v[118:119], v[140:141]
	v_pk_fma_f32 v[140:141], v[120:121], v[120:121], v[140:141]
	v_pk_fma_f32 v[140:141], v[122:123], v[122:123], v[140:141]
	v_pk_fma_f32 v[140:141], v[124:125], v[124:125], v[140:141]
	v_pk_fma_f32 v[140:141], v[126:127], v[126:127], v[140:141]
	v_pk_fma_f32 v[140:141], v[128:129], v[128:129], v[140:141]
	v_pk_fma_f32 v[140:141], v[130:131], v[130:131], v[140:141]
	v_add_f32_e32 v140, v140, v141
	s_nop 1
	v_add_f32_dpp v140, v140, v140 quad_perm:[1,0,3,2] row_mask:0xf bank_mask:0xf
	s_nop 1
	v_add_f32_dpp v140, v140, v140 quad_perm:[2,3,0,1] row_mask:0xf bank_mask:0xf
	s_nop 1
	v_add_f32_dpp v140, v140, v140 row_ror:4 row_mask:0xf bank_mask:0xf
	s_nop 1
	v_add_f32_dpp v140, v140, v140 row_ror:8 row_mask:0xf bank_mask:0xf
	s_nop 1
	v_add_f32_dpp v140, v140, v140 row_bcast:15 row_mask:0xa bank_mask:0xf
	s_nop 1
	v_add_f32_dpp v140, v140, v140 row_bcast:31 row_mask:0xc bank_mask:0xf
	s_nop 1
	v_fmamk_f32 v140, v140, 0x3a800000, v224
	v_rsq_f32_e32 v140, v140
	s_nop 0
	v_mul_f32_e32 v140, v144, v140
	s_nop 0
	v_readlane_b32 s4, v140, 63
	s_nop 1
	v_pk_mul_f32 v[116:117], v[116:117], s[4:5] op_sel_hi:[1,0]
	v_pk_mul_f32 v[118:119], v[118:119], s[4:5] op_sel_hi:[1,0]
	v_pk_mul_f32 v[120:121], v[120:121], s[4:5] op_sel_hi:[1,0]
	v_pk_mul_f32 v[122:123], v[122:123], s[4:5] op_sel_hi:[1,0]
	v_pk_mul_f32 v[124:125], v[124:125], s[4:5] op_sel_hi:[1,0]
	v_pk_mul_f32 v[126:127], v[126:127], s[4:5] op_sel_hi:[1,0]
	v_pk_mul_f32 v[128:129], v[128:129], s[4:5] op_sel_hi:[1,0]
	v_pk_mul_f32 v[130:131], v[130:131], s[4:5] op_sel_hi:[1,0]
	v_pk_fma_f32 v[198:199], v[0:1], v[116:117], v[198:199]
	v_pk_fma_f32 v[200:201], v[2:3], v[118:119], v[200:201]
	v_pk_fma_f32 v[202:203], v[4:5], v[120:121], v[202:203]
; __device__ __forceinline__ unsigned pk2(float lo, float hi) { return pg8::cvt_pk_bf16(lo, hi); }
; template <int R, bool SRCB> ...
;     ...
;             const float rr = __builtin_amdgcn_rsqf(wave_sum(ss) * (1.0f / DM) + 1e-6f) * w;
; #pragma unroll
;             for (int j = 0; j < 2; ++j)
; #pragma unroll
;                 for (int k = 0; k < 2; ++k) h[r][j][k] = h[r][j][k] + gg[j][k] * (y[j][k] * rr);
;         }
;     }
; #pragma unroll
;     for (int r = 0; r < R; ++r)
; #pragma unroll
;         for (int j = 0; j < 2; ++j) { const int c = 8 * lane + 512 * j;
;             if (final_out) { *(f32x4*)(final_out + (size_t)(row0 + r) * DM + c) = h[r][j][0]; *(f32x4*)(final_out + (size_t)(row0 + r) * DM + c + 4) = h[r][j][1]; }
;             else { u32x4 t; t.x = pkh2(h[r][j][0][0], h[r][j][0][1]); t.y = pkh2(h[r][j][0][2], h[r][j][0][3]); t.z = pkh2(h[r][j][1][0], h[r][j][1][1]); t.w = pkh2(h[r][j][1][2], h[r][j][1][3]);
;                 *(u32x4*)(hout + (size_t)(row0 + r) * DM + c) = t; } }
;     if (U) {
;         f32x4 gp[2][2], sc1[2][2], sh[2][2];
; #pragma unroll
;         for (int j = 0; j < 2; ++j)
; #pragma unroll
;             for (int k = 0; k < 2; ++k) { const int c = 8 * lane + 512 * j + 4 * k; gp[j][k] = *(const f32x4*)(gpre + c); sc1[j][k] = *(const f32x4*)(scale + (size_t)mrow * 9216 + c) + 1.0f; sh[j][k] = *(const f32x4*)(shift + (size_t)mrow * 9216 + c); }
; #pragma unroll
;         for (int r = 0; r < R; ++r) {
;             float ss = 0.f;
; #pragma unroll
;             for (int j = 0; j < 2; ++j)
; #pragma unroll
;                 for (int k = 0; k < 2; ++k) ss += (h[r][j][k][0] * h[r][j][k][0] + h[r][j][k][1] * h[r][j][k][1]) + (h[r][j][k][2] * h[r][j][k][2] + h[r][j][k][3] * h[r][j][k][3]);
;             const float rr = __builtin_amdgcn_rsqf(wave_sum(ss) * (1.0f / DM) + 1e-6f);
; #pragma unroll
;             for (int j = 0; j < 2; ++j) { const f32x4 v0 = (h[r][j][0] * rr * gp[j][0]) * sc1[j][0] + sh[j][0], v1 = (h[r][j][1] * rr * gp[j][1]) * sc1[j][1] + sh[j][1];
;                 u32x4 t; t.x = pk2(v0[0], v0[1]); t.y = pk2(v0[2], v0[3]); t.z = pk2(v1[0], v1[1]); t.w = pk2(v1[2], v1[3]);
;                 *(u32x4*)(U + (size_t)(row0 + r) * DM + 8 * lane + 512 * j) = t; }
	v_pk_fma_f32 v[204:205], v[6:7], v[122:123], v[204:205]
	v_pk_fma_f32 v[206:207], v[8:9], v[124:125], v[206:207]
	v_pk_fma_f32 v[208:209], v[10:11], v[126:127], v[208:209]
	v_pk_fma_f32 v[210:211], v[12:13], v[128:129], v[210:211]
	v_pk_fma_f32 v[212:213], v[14:15], v[130:131], v[212:213]
	v_cvt_f16_f32_e32 v132, v198
	v_cvt_f16_f32_e32 v133, v200
	v_cvt_f16_f32_e32 v134, v202
	v_cvt_f16_f32_e32 v135, v204
	v_cvt_f16_f32_e32 v136, v206
	v_cvt_f16_f32_e32 v137, v208
	v_cvt_f16_f32_e32 v138, v210
	v_cvt_f16_f32_e32 v139, v212
	v_cvt_f16_f32_sdwa v132, v199 dst_sel:WORD_1 dst_unused:UNUSED_PRESERVE src0_sel:DWORD
	v_cvt_f16_f32_sdwa v133, v201 dst_sel:WORD_1 dst_unused:UNUSED_PRESERVE src0_sel:DWORD
	v_cvt_f16_f32_sdwa v134, v203 dst_sel:WORD_1 dst_unused:UNUSED_PRESERVE src0_sel:DWORD
	v_cvt_f16_f32_sdwa v135, v205 dst_sel:WORD_1 dst_unused:UNUSED_PRESERVE src0_sel:DWORD
	v_cvt_f16_f32_sdwa v136, v207 dst_sel:WORD_1 dst_unused:UNUSED_PRESERVE src0_sel:DWORD
	v_cvt_f16_f32_sdwa v137, v209 dst_sel:WORD_1 dst_unused:UNUSED_PRESERVE src0_sel:DWORD
	v_cvt_f16_f32_sdwa v138, v211 dst_sel:WORD_1 dst_unused:UNUSED_PRESERVE src0_sel:DWORD
	v_cvt_f16_f32_sdwa v139, v213 dst_sel:WORD_1 dst_unused:UNUSED_PRESERVE src0_sel:DWORD
	s_nop 0
	global_store_dwordx4 v184, v[132:135], s[42:43] offset:2048
	global_store_dwordx4 v184, v[136:139], s[42:43] offset:3072
	v_pk_mul_f32 v[140:141], v[198:199], v[198:199]
	v_pk_fma_f32 v[140:141], v[200:201], v[200:201], v[140:141]
	v_pk_fma_f32 v[140:141], v[202:203], v[202:203], v[140:141]
	v_pk_fma_f32 v[140:141], v[204:205], v[204:205], v[140:141]
	v_pk_fma_f32 v[140:141], v[206:207], v[206:207], v[140:141]
	v_pk_fma_f32 v[140:141], v[208:209], v[208:209], v[140:141]
	v_pk_fma_f32 v[140:141], v[210:211], v[210:211], v[140:141]
	v_pk_fma_f32 v[140:141], v[212:213], v[212:213], v[140:141]
	v_add_f32_e32 v140, v140, v141
	s_nop 1
	v_add_f32_dpp v140, v140, v140 quad_perm:[1,0,3,2] row_mask:0xf bank_mask:0xf
	s_nop 1
	v_add_f32_dpp v140, v140, v140 quad_perm:[2,3,0,1] row_mask:0xf bank_mask:0xf
	s_nop 1
	v_add_f32_dpp v140, v140, v140 row_ror:4 row_mask:0xf bank_mask:0xf
	s_nop 1
	v_add_f32_dpp v140, v140, v140 row_ror:8 row_mask:0xf bank_mask:0xf
	s_nop 1
	v_add_f32_dpp v140, v140, v140 row_bcast:15 row_mask:0xa bank_mask:0xf
	s_nop 1
	v_add_f32_dpp v140, v140, v140 row_bcast:31 row_mask:0xc bank_mask:0xf
	s_nop 1
	v_fmamk_f32 v140, v140, 0x3a800000, v224
	v_rsq_f32_e32 v140, v140
	s_nop 0
	v_readlane_b32 s6, v140, 63
	s_nop 1
	v_pk_mul_f32 v[198:199], v[198:199], s[6:7] op_sel_hi:[1,0]
	v_pk_mul_f32 v[200:201], v[200:201], s[6:7] op_sel_hi:[1,0]
	v_pk_mul_f32 v[202:203], v[202:203], s[6:7] op_sel_hi:[1,0]
	v_pk_mul_f32 v[204:205], v[204:205], s[6:7] op_sel_hi:[1,0]
	v_pk_mul_f32 v[206:207], v[206:207], s[6:7] op_sel_hi:[1,0]
	v_pk_mul_f32 v[208:209], v[208:209], s[6:7] op_sel_hi:[1,0]
	v_pk_mul_f32 v[210:211], v[210:211], s[6:7] op_sel_hi:[1,0]
	v_pk_mul_f32 v[212:213], v[212:213], s[6:7] op_sel_hi:[1,0]
	v_pk_mul_f32 v[198:199], v[16:17], v[198:199]
	v_pk_mul_f32 v[200:201], v[18:19], v[200:201]
	v_pk_mul_f32 v[202:203], v[20:21], v[202:203]
	v_pk_mul_f32 v[204:205], v[22:23], v[204:205]
	v_pk_mul_f32 v[206:207], v[24:25], v[206:207]
	v_pk_mul_f32 v[208:209], v[26:27], v[208:209]
	v_pk_mul_f32 v[210:211], v[28:29], v[210:211]
	v_pk_mul_f32 v[212:213], v[30:31], v[212:213]
	v_pk_fma_f32 v[198:199], v[32:33], v[198:199], v[48:49]
	v_pk_fma_f32 v[200:201], v[34:35], v[200:201], v[50:51]
	v_pk_fma_f32 v[202:203], v[36:37], v[202:203], v[52:53]
	v_pk_fma_f32 v[204:205], v[38:39], v[204:205], v[54:55]
	v_pk_fma_f32 v[206:207], v[40:41], v[206:207], v[56:57]
	v_pk_fma_f32 v[208:209], v[42:43], v[208:209], v[58:59]
	v_pk_fma_f32 v[210:211], v[44:45], v[210:211], v[60:61]
	v_pk_fma_f32 v[212:213], v[46:47], v[212:213], v[62:63]
	v_cvt_pk_bf16_f32 v230, v198, v199
	v_cvt_pk_bf16_f32 v231, v200, v201
	v_cvt_pk_bf16_f32 v232, v202, v203
	v_cvt_pk_bf16_f32 v233, v204, v205
	v_cvt_pk_bf16_f32 v234, v206, v207
	v_cvt_pk_bf16_f32 v235, v208, v209
	v_cvt_pk_bf16_f32 v236, v210, v211
	v_cvt_pk_bf16_f32 v237, v212, v213
	global_store_dwordx4 v184, v[230:233], s[44:45] offset:2048
	global_store_dwordx4 v184, v[234:237], s[44:45] offset:3072
	s_waitcnt vmcnt(28)
; template <int R, bool SRCB> ...
;     ...
;         for (int r = 0; r < R; ++r) {
;             f32x4 y[2][2]; float ss = 0.f;
; #pragma unroll
;             for (int j = 0; j < 2; ++j) { const u32x4 t = yr[r][j];
;                 y[j][0] = (f32x4){bf_lo(t.x), bf_hi(t.x), bf_lo(t.y), bf_hi(t.y)}; y[j][1] = (f32x4){bf_lo(t.z), bf_hi(t.z), bf_lo(t.w), bf_hi(t.w)};
;                 if (R == 1 && YP) {
; #pragma unroll
;                     for (int k = 0; k < 2; ++k) { const float* pp = YP + (size_t)(row0 - M_LAT) * DM + 8 * lane + 512 * j + 4 * k; f32x4 s = *(const f32x4*)pp;
; #pragma unroll
;                         for (int q = 1; q < pg8::NSL; ++q) s = s + *(const f32x4*)(pp + (size_t)q * 2048 * DM);
;                         y[j][k] = s; } }
; #pragma unroll
;                 for (int k = 0; k < 2; ++k) ss += (y[j][k][0] * y[j][k][0] + y[j][k][1] * y[j][k][1]) + (y[j][k][2] * y[j][k][2] + y[j][k][3] * y[j][k][3]); }
;             const float rr = __builtin_amdgcn_rsqf(wave_sum(ss) * (1.0f / DM) + 1e-6f) * w;
; #pragma unroll
;             for (int j = 0; j < 2; ++j)
; #pragma unroll
;                 for (int k = 0; k < 2; ++k) h[r][j][k] = h[r][j][k] + gg[j][k] * (y[j][k] * rr);
;         }
;     }
; #pragma unroll
;     for (int r = 0; r < R; ++r)
; #pragma unroll
;         for (int j = 0; j < 2; ++j) { const int c = 8 * lane + 512 * j;
;             if (final_out) { *(f32x4*)(final_out + (size_t)(row0 + r) * DM + c) = h[r][j][0]; *(f32x4*)(final_out + (size_t)(row0 + r) * DM + c + 4) = h[r][j][1]; }
;             else { u32x4 t; t.x = pkh2(h[r][j][0][0], h[r][j][0][1]); t.y = pkh2(h[r][j][0][2], h[r][j][0][3]); t.z = pkh2(h[r][j][1][0], h[r][j][1][1]); t.w = pkh2(h[r][j][1][2], h[r][j][1][3]);
;                 *(u32x4*)(hout + (size_t)(row0 + r) * DM + c) = t; } }
;     if (U) {
;         f32x4 gp[2][2], sc1[2][2], sh[2][2];
; #pragma unroll
;         for (int j = 0; j < 2; ++j)
; #pragma unroll
;             for (int k = 0; k < 2; ++k) { const int c = 8 * lane + 512 * j + 4 * k; gp[j][k] = *(const f32x4*)(gpre + c); sc1[j][k] = *(const f32x4*)(scale + (size_t)mrow * 9216 + c) + 1.0f; sh[j][k] = *(const f32x4*)(shift + (size_t)mrow * 9216 + c); }
; #pragma unroll
;         for (int r = 0; r < R; ++r) {
;             float ss = 0.f;
; #pragma unroll
;             for (int j = 0; j < 2; ++j)
; #pragma unroll
	v_lshlrev_b32_e32 v116, 16, v148
	v_and_b32_e32 v117, 0xffff0000, v148
	v_lshlrev_b32_e32 v118, 16, v149
	v_and_b32_e32 v119, 0xffff0000, v149
	v_lshlrev_b32_e32 v120, 16, v150
	v_and_b32_e32 v121, 0xffff0000, v150
	v_lshlrev_b32_e32 v122, 16, v151
	v_and_b32_e32 v123, 0xffff0000, v151
	v_lshlrev_b32_e32 v124, 16, v152
	v_and_b32_e32 v125, 0xffff0000, v152
	v_lshlrev_b32_e32 v126, 16, v153
	v_and_b32_e32 v127, 0xffff0000, v153
	v_lshlrev_b32_e32 v128, 16, v154
	v_and_b32_e32 v129, 0xffff0000, v154
	v_lshlrev_b32_e32 v130, 16, v155
	v_and_b32_e32 v131, 0xffff0000, v155
	v_cvt_f32_f16_e32 v198, v64
	v_cvt_f32_f16_sdwa v199, v64 dst_sel:DWORD dst_unused:UNUSED_PAD src0_sel:WORD_1
	v_cvt_f32_f16_e32 v200, v65
	v_cvt_f32_f16_sdwa v201, v65 dst_sel:DWORD dst_unused:UNUSED_PAD src0_sel:WORD_1
	v_cvt_f32_f16_e32 v202, v66
	v_cvt_f32_f16_sdwa v203, v66 dst_sel:DWORD dst_unused:UNUSED_PAD src0_sel:WORD_1
	v_cvt_f32_f16_e32 v204, v67
	v_cvt_f32_f16_sdwa v205, v67 dst_sel:DWORD dst_unused:UNUSED_PAD src0_sel:WORD_1
	v_cvt_f32_f16_e32 v206, v68
	v_cvt_f32_f16_sdwa v207, v68 dst_sel:DWORD dst_unused:UNUSED_PAD src0_sel:WORD_1
	v_cvt_f32_f16_e32 v208, v69
	v_cvt_f32_f16_sdwa v209, v69 dst_sel:DWORD dst_unused:UNUSED_PAD src0_sel:WORD_1
	v_cvt_f32_f16_e32 v210, v70
	v_cvt_f32_f16_sdwa v211, v70 dst_sel:DWORD dst_unused:UNUSED_PAD src0_sel:WORD_1
	v_cvt_f32_f16_e32 v212, v71
	v_cvt_f32_f16_sdwa v213, v71 dst_sel:DWORD dst_unused:UNUSED_PAD src0_sel:WORD_1
	global_load_dwordx4 v[64:67], v186, s[42:43] offset:-4096
	global_load_dwordx4 v[68:71], v186, s[42:43] offset:-3072
	global_load_dwordx4 v[148:151], v186, s[44:45] offset:-4096
	global_load_dwordx4 v[152:155], v186, s[44:45] offset:-3072
	v_pk_mul_f32 v[140:141], v[116:117], v[116:117]
	v_pk_fma_f32 v[140:141], v[118:119], v[118:119], v[140:141]
	v_pk_fma_f32 v[140:141], v[120:121], v[120:121], v[140:141]
	v_pk_fma_f32 v[140:141], v[122:123], v[122:123], v[140:141]
	v_pk_fma_f32 v[140:141], v[124:125], v[124:125], v[140:141]
	v_pk_fma_f32 v[140:141], v[126:127], v[126:127], v[140:141]
	v_pk_fma_f32 v[140:141], v[128:129], v[128:129], v[140:141]
	v_pk_fma_f32 v[140:141], v[130:131], v[130:131], v[140:141]
	v_add_f32_e32 v140, v140, v141
	s_nop 1
	v_add_f32_dpp v140, v140, v140 quad_perm:[1,0,3,2] row_mask:0xf bank_mask:0xf
	s_nop 1
	v_add_f32_dpp v140, v140, v140 quad_perm:[2,3,0,1] row_mask:0xf bank_mask:0xf
	s_nop 1
	v_add_f32_dpp v140, v140, v140 row_ror:4 row_mask:0xf bank_mask:0xf
	s_nop 1
	v_add_f32_dpp v140, v140, v140 row_ror:8 row_mask:0xf bank_mask:0xf
	s_nop 1
	v_add_f32_dpp v140, v140, v140 row_bcast:15 row_mask:0xa bank_mask:0xf
	s_nop 1
	v_add_f32_dpp v140, v140, v140 row_bcast:31 row_mask:0xc bank_mask:0xf
	s_nop 1
	v_fmamk_f32 v140, v140, 0x3a800000, v224
	v_rsq_f32_e32 v140, v140
	s_nop 0
	v_mul_f32_e32 v140, v144, v140
	s_nop 0
	v_readlane_b32 s4, v140, 63
	s_nop 1
	v_pk_mul_f32 v[116:117], v[116:117], s[4:5] op_sel_hi:[1,0]
	v_pk_mul_f32 v[118:119], v[118:119], s[4:5] op_sel_hi:[1,0]
	v_pk_mul_f32 v[120:121], v[120:121], s[4:5] op_sel_hi:[1,0]
	v_pk_mul_f32 v[122:123], v[122:123], s[4:5] op_sel_hi:[1,0]
	v_pk_mul_f32 v[124:125], v[124:125], s[4:5] op_sel_hi:[1,0]
	v_pk_mul_f32 v[126:127], v[126:127], s[4:5] op_sel_hi:[1,0]
	v_pk_mul_f32 v[128:129], v[128:129], s[4:5] op_sel_hi:[1,0]
	v_pk_mul_f32 v[130:131], v[130:131], s[4:5] op_sel_hi:[1,0]
	v_pk_fma_f32 v[198:199], v[0:1], v[116:117], v[198:199]
	v_pk_fma_f32 v[200:201], v[2:3], v[118:119], v[200:201]
	v_pk_fma_f32 v[202:203], v[4:5], v[120:121], v[202:203]
	v_pk_fma_f32 v[204:205], v[6:7], v[122:123], v[204:205]
	v_pk_fma_f32 v[206:207], v[8:9], v[124:125], v[206:207]
	v_pk_fma_f32 v[208:209], v[10:11], v[126:127], v[208:209]
	v_pk_fma_f32 v[210:211], v[12:13], v[128:129], v[210:211]
	v_pk_fma_f32 v[212:213], v[14:15], v[130:131], v[212:213]
	v_cvt_f16_f32_e32 v132, v198
	v_cvt_f16_f32_e32 v133, v200
	v_cvt_f16_f32_e32 v134, v202
	v_cvt_f16_f32_e32 v135, v204
	v_cvt_f16_f32_e32 v136, v206
	v_cvt_f16_f32_e32 v137, v208
	v_cvt_f16_f32_e32 v138, v210
	v_cvt_f16_f32_e32 v139, v212
	v_cvt_f16_f32_sdwa v132, v199 dst_sel:WORD_1 dst_unused:UNUSED_PRESERVE src0_sel:DWORD
	v_cvt_f16_f32_sdwa v133, v201 dst_sel:WORD_1 dst_unused:UNUSED_PRESERVE src0_sel:DWORD
	v_cvt_f16_f32_sdwa v134, v203 dst_sel:WORD_1 dst_unused:UNUSED_PRESERVE src0_sel:DWORD
	v_cvt_f16_f32_sdwa v135, v205 dst_sel:WORD_1 dst_unused:UNUSED_PRESERVE src0_sel:DWORD
	v_cvt_f16_f32_sdwa v136, v207 dst_sel:WORD_1 dst_unused:UNUSED_PRESERVE src0_sel:DWORD
	v_cvt_f16_f32_sdwa v137, v209 dst_sel:WORD_1 dst_unused:UNUSED_PRESERVE src0_sel:DWORD
	v_cvt_f16_f32_sdwa v138, v211 dst_sel:WORD_1 dst_unused:UNUSED_PRESERVE src0_sel:DWORD
	v_cvt_f16_f32_sdwa v139, v213 dst_sel:WORD_1 dst_unused:UNUSED_PRESERVE src0_sel:DWORD
	s_nop 0
	global_store_dwordx4 v185, v[132:135], s[42:43] offset:-4096
	global_store_dwordx4 v185, v[136:139], s[42:43] offset:-3072
	v_pk_mul_f32 v[140:141], v[198:199], v[198:199]
	v_pk_fma_f32 v[140:141], v[200:201], v[200:201], v[140:141]
	v_pk_fma_f32 v[140:141], v[202:203], v[202:203], v[140:141]
	v_pk_fma_f32 v[140:141], v[204:205], v[204:205], v[140:141]
	v_pk_fma_f32 v[140:141], v[206:207], v[206:207], v[140:141]
	v_pk_fma_f32 v[140:141], v[208:209], v[208:209], v[140:141]
	v_pk_fma_f32 v[140:141], v[210:211], v[210:211], v[140:141]
	v_pk_fma_f32 v[140:141], v[212:213], v[212:213], v[140:141]
	v_add_f32_e32 v140, v140, v141
	s_nop 1
	v_add_f32_dpp v140, v140, v140 quad_perm:[1,0,3,2] row_mask:0xf bank_mask:0xf
	s_nop 1
	v_add_f32_dpp v140, v140, v140 quad_perm:[2,3,0,1] row_mask:0xf bank_mask:0xf
	s_nop 1
	v_add_f32_dpp v140, v140, v140 row_ror:4 row_mask:0xf bank_mask:0xf
; template <int R, bool SRCB> ...
;     ...
;         for (int r = 0; r < R; ++r) {
;             f32x4 y[2][2]; float ss = 0.f;
; #pragma unroll
;             for (int j = 0; j < 2; ++j) { const u32x4 t = yr[r][j];
;                 y[j][0] = (f32x4){bf_lo(t.x), bf_hi(t.x), bf_lo(t.y), bf_hi(t.y)}; y[j][1] = (f32x4){bf_lo(t.z), bf_hi(t.z), bf_lo(t.w), bf_hi(t.w)};
;                 if (R == 1 && YP) {
; #pragma unroll
;                     for (int k = 0; k < 2; ++k) { const float* pp = YP + (size_t)(row0 - M_LAT) * DM + 8 * lane + 512 * j + 4 * k; f32x4 s = *(const f32x4*)pp;
; #pragma unroll
;                         for (int q = 1; q < pg8::NSL; ++q) s = s + *(const f32x4*)(pp + (size_t)q * 2048 * DM);
;                         y[j][k] = s; } }
; #pragma unroll
;                 for (int k = 0; k < 2; ++k) ss += (y[j][k][0] * y[j][k][0] + y[j][k][1] * y[j][k][1]) + (y[j][k][2] * y[j][k][2] + y[j][k][3] * y[j][k][3]); }
;             const float rr = __builtin_amdgcn_rsqf(wave_sum(ss) * (1.0f / DM) + 1e-6f) * w;
; #pragma unroll
;             for (int j = 0; j < 2; ++j)
; #pragma unroll
;                 for (int k = 0; k < 2; ++k) h[r][j][k] = h[r][j][k] + gg[j][k] * (y[j][k] * rr);
;         }
;     }
; #pragma unroll
;     for (int r = 0; r < R; ++r)
; #pragma unroll
;         for (int j = 0; j < 2; ++j) { const int c = 8 * lane + 512 * j;
;             if (final_out) { *(f32x4*)(final_out + (size_t)(row0 + r) * DM + c) = h[r][j][0]; *(f32x4*)(final_out + (size_t)(row0 + r) * DM + c + 4) = h[r][j][1]; }
;             else { u32x4 t; t.x = pkh2(h[r][j][0][0], h[r][j][0][1]); t.y = pkh2(h[r][j][0][2], h[r][j][0][3]); t.z = pkh2(h[r][j][1][0], h[r][j][1][1]); t.w = pkh2(h[r][j][1][2], h[r][j][1][3]);
;                 *(u32x4*)(hout + (size_t)(row0 + r) * DM + c) = t; } }
;     if (U) {
;         f32x4 gp[2][2], sc1[2][2], sh[2][2];
; #pragma unroll
;         for (int j = 0; j < 2; ++j)
; #pragma unroll
;             for (int k = 0; k < 2; ++k) { const int c = 8 * lane + 512 * j + 4 * k; gp[j][k] = *(const f32x4*)(gpre + c); sc1[j][k] = *(const f32x4*)(scale + (size_t)mrow * 9216 + c) + 1.0f; sh[j][k] = *(const f32x4*)(shift + (size_t)mrow * 9216 + c); }
; #pragma unroll
;         for (int r = 0; r < R; ++r) {
;             float ss = 0.f;
; #pragma unroll
;             for (int j = 0; j < 2; ++j)
; #pragma unroll
	s_nop 1
	v_add_f32_dpp v140, v140, v140 row_ror:8 row_mask:0xf bank_mask:0xf
	s_nop 1
	v_add_f32_dpp v140, v140, v140 row_bcast:15 row_mask:0xa bank_mask:0xf
	s_nop 1
	v_add_f32_dpp v140, v140, v140 row_bcast:31 row_mask:0xc bank_mask:0xf
	s_nop 1
	v_fmamk_f32 v140, v140, 0x3a800000, v224
	v_rsq_f32_e32 v140, v140
	s_nop 0
	v_readlane_b32 s6, v140, 63
	s_nop 1
	v_pk_mul_f32 v[198:199], v[198:199], s[6:7] op_sel_hi:[1,0]
	v_pk_mul_f32 v[200:201], v[200:201], s[6:7] op_sel_hi:[1,0]
	v_pk_mul_f32 v[202:203], v[202:203], s[6:7] op_sel_hi:[1,0]
	v_pk_mul_f32 v[204:205], v[204:205], s[6:7] op_sel_hi:[1,0]
	v_pk_mul_f32 v[206:207], v[206:207], s[6:7] op_sel_hi:[1,0]
	v_pk_mul_f32 v[208:209], v[208:209], s[6:7] op_sel_hi:[1,0]
	v_pk_mul_f32 v[210:211], v[210:211], s[6:7] op_sel_hi:[1,0]
	v_pk_mul_f32 v[212:213], v[212:213], s[6:7] op_sel_hi:[1,0]
	v_pk_mul_f32 v[198:199], v[16:17], v[198:199]
	v_pk_mul_f32 v[200:201], v[18:19], v[200:201]
	v_pk_mul_f32 v[202:203], v[20:21], v[202:203]
	v_pk_mul_f32 v[204:205], v[22:23], v[204:205]
	v_pk_mul_f32 v[206:207], v[24:25], v[206:207]
	v_pk_mul_f32 v[208:209], v[26:27], v[208:209]
	v_pk_mul_f32 v[210:211], v[28:29], v[210:211]
	v_pk_mul_f32 v[212:213], v[30:31], v[212:213]
	v_pk_fma_f32 v[198:199], v[32:33], v[198:199], v[48:49]
	v_pk_fma_f32 v[200:201], v[34:35], v[200:201], v[50:51]
	v_pk_fma_f32 v[202:203], v[36:37], v[202:203], v[52:53]
	v_pk_fma_f32 v[204:205], v[38:39], v[204:205], v[54:55]
	v_pk_fma_f32 v[206:207], v[40:41], v[206:207], v[56:57]
	v_pk_fma_f32 v[208:209], v[42:43], v[208:209], v[58:59]
	v_pk_fma_f32 v[210:211], v[44:45], v[210:211], v[60:61]
	v_pk_fma_f32 v[212:213], v[46:47], v[212:213], v[62:63]
	v_cvt_pk_bf16_f32 v230, v198, v199
	v_cvt_pk_bf16_f32 v231, v200, v201
	v_cvt_pk_bf16_f32 v232, v202, v203
	v_cvt_pk_bf16_f32 v233, v204, v205
	v_cvt_pk_bf16_f32 v234, v206, v207
	v_cvt_pk_bf16_f32 v235, v208, v209
	v_cvt_pk_bf16_f32 v236, v210, v211
	v_cvt_pk_bf16_f32 v237, v212, v213
	global_store_dwordx4 v185, v[230:233], s[44:45] offset:-4096
	global_store_dwordx4 v185, v[234:237], s[44:45] offset:-3072
	s_waitcnt vmcnt(28)
	v_lshlrev_b32_e32 v116, 16, v156
	v_and_b32_e32 v117, 0xffff0000, v156
	v_lshlrev_b32_e32 v118, 16, v157
	v_and_b32_e32 v119, 0xffff0000, v157
	v_lshlrev_b32_e32 v120, 16, v158
	v_and_b32_e32 v121, 0xffff0000, v158
	v_lshlrev_b32_e32 v122, 16, v159
	v_and_b32_e32 v123, 0xffff0000, v159
	v_lshlrev_b32_e32 v124, 16, v160
	v_and_b32_e32 v125, 0xffff0000, v160
	v_lshlrev_b32_e32 v126, 16, v161
	v_and_b32_e32 v127, 0xffff0000, v161
	v_lshlrev_b32_e32 v128, 16, v162
	v_and_b32_e32 v129, 0xffff0000, v162
	v_lshlrev_b32_e32 v130, 16, v163
	v_and_b32_e32 v131, 0xffff0000, v163
	v_cvt_f32_f16_e32 v198, v72
	v_cvt_f32_f16_sdwa v199, v72 dst_sel:DWORD dst_unused:UNUSED_PAD src0_sel:WORD_1
	v_cvt_f32_f16_e32 v200, v73
	v_cvt_f32_f16_sdwa v201, v73 dst_sel:DWORD dst_unused:UNUSED_PAD src0_sel:WORD_1
	v_cvt_f32_f16_e32 v202, v74
	v_cvt_f32_f16_sdwa v203, v74 dst_sel:DWORD dst_unused:UNUSED_PAD src0_sel:WORD_1
	v_cvt_f32_f16_e32 v204, v75
	v_cvt_f32_f16_sdwa v205, v75 dst_sel:DWORD dst_unused:UNUSED_PAD src0_sel:WORD_1
	v_cvt_f32_f16_e32 v206, v76
	v_cvt_f32_f16_sdwa v207, v76 dst_sel:DWORD dst_unused:UNUSED_PAD src0_sel:WORD_1
	v_cvt_f32_f16_e32 v208, v77
	v_cvt_f32_f16_sdwa v209, v77 dst_sel:DWORD dst_unused:UNUSED_PAD src0_sel:WORD_1
	v_cvt_f32_f16_e32 v210, v78
	v_cvt_f32_f16_sdwa v211, v78 dst_sel:DWORD dst_unused:UNUSED_PAD src0_sel:WORD_1
	v_cvt_f32_f16_e32 v212, v79
	v_cvt_f32_f16_sdwa v213, v79 dst_sel:DWORD dst_unused:UNUSED_PAD src0_sel:WORD_1
	global_load_dwordx4 v[72:75], v186, s[42:43] offset:-2048
	global_load_dwordx4 v[76:79], v186, s[42:43] offset:-1024
	global_load_dwordx4 v[156:159], v186, s[44:45] offset:-2048
	global_load_dwordx4 v[160:163], v186, s[44:45] offset:-1024
	v_pk_mul_f32 v[140:141], v[116:117], v[116:117]
	v_pk_fma_f32 v[140:141], v[118:119], v[118:119], v[140:141]
	v_pk_fma_f32 v[140:141], v[120:121], v[120:121], v[140:141]
	v_pk_fma_f32 v[140:141], v[122:123], v[122:123], v[140:141]
	v_pk_fma_f32 v[140:141], v[124:125], v[124:125], v[140:141]
	v_pk_fma_f32 v[140:141], v[126:127], v[126:127], v[140:141]
	v_pk_fma_f32 v[140:141], v[128:129], v[128:129], v[140:141]
	v_pk_fma_f32 v[140:141], v[130:131], v[130:131], v[140:141]
	v_add_f32_e32 v140, v140, v141
	s_nop 1
	v_add_f32_dpp v140, v140, v140 quad_perm:[1,0,3,2] row_mask:0xf bank_mask:0xf
	s_nop 1
	v_add_f32_dpp v140, v140, v140 quad_perm:[2,3,0,1] row_mask:0xf bank_mask:0xf
	s_nop 1
	v_add_f32_dpp v140, v140, v140 row_ror:4 row_mask:0xf bank_mask:0xf
	s_nop 1
	v_add_f32_dpp v140, v140, v140 row_ror:8 row_mask:0xf bank_mask:0xf
	s_nop 1
	v_add_f32_dpp v140, v140, v140 row_bcast:15 row_mask:0xa bank_mask:0xf
	s_nop 1
	v_add_f32_dpp v140, v140, v140 row_bcast:31 row_mask:0xc bank_mask:0xf
	s_nop 1
	v_fmamk_f32 v140, v140, 0x3a800000, v224
	v_rsq_f32_e32 v140, v140
	s_nop 0
	v_mul_f32_e32 v140, v144, v140
	s_nop 0
	v_readlane_b32 s4, v140, 63
	s_nop 1
	v_pk_mul_f32 v[116:117], v[116:117], s[4:5] op_sel_hi:[1,0]
	v_pk_mul_f32 v[118:119], v[118:119], s[4:5] op_sel_hi:[1,0]
	v_pk_mul_f32 v[120:121], v[120:121], s[4:5] op_sel_hi:[1,0]
	v_pk_mul_f32 v[122:123], v[122:123], s[4:5] op_sel_hi:[1,0]
	v_pk_mul_f32 v[124:125], v[124:125], s[4:5] op_sel_hi:[1,0]
	v_pk_mul_f32 v[126:127], v[126:127], s[4:5] op_sel_hi:[1,0]
	v_pk_mul_f32 v[128:129], v[128:129], s[4:5] op_sel_hi:[1,0]
	v_pk_mul_f32 v[130:131], v[130:131], s[4:5] op_sel_hi:[1,0]
	v_pk_fma_f32 v[198:199], v[0:1], v[116:117], v[198:199]
	v_pk_fma_f32 v[200:201], v[2:3], v[118:119], v[200:201]
	v_pk_fma_f32 v[202:203], v[4:5], v[120:121], v[202:203]
; __device__ __forceinline__ unsigned pk2(float lo, float hi) { return pg8::cvt_pk_bf16(lo, hi); }
; template <int R, bool SRCB> ...
;     ...
;             const float rr = __builtin_amdgcn_rsqf(wave_sum(ss) * (1.0f / DM) + 1e-6f) * w;
; #pragma unroll
;             for (int j = 0; j < 2; ++j)
; #pragma unroll
;                 for (int k = 0; k < 2; ++k) h[r][j][k] = h[r][j][k] + gg[j][k] * (y[j][k] * rr);
;         }
;     }
; #pragma unroll
;     for (int r = 0; r < R; ++r)
; #pragma unroll
;         for (int j = 0; j < 2; ++j) { const int c = 8 * lane + 512 * j;
;             if (final_out) { *(f32x4*)(final_out + (size_t)(row0 + r) * DM + c) = h[r][j][0]; *(f32x4*)(final_out + (size_t)(row0 + r) * DM + c + 4) = h[r][j][1]; }
;             else { u32x4 t; t.x = pkh2(h[r][j][0][0], h[r][j][0][1]); t.y = pkh2(h[r][j][0][2], h[r][j][0][3]); t.z = pkh2(h[r][j][1][0], h[r][j][1][1]); t.w = pkh2(h[r][j][1][2], h[r][j][1][3]);
;                 *(u32x4*)(hout + (size_t)(row0 + r) * DM + c) = t; } }
;     if (U) {
;         f32x4 gp[2][2], sc1[2][2], sh[2][2];
; #pragma unroll
;         for (int j = 0; j < 2; ++j)
; #pragma unroll
;             for (int k = 0; k < 2; ++k) { const int c = 8 * lane + 512 * j + 4 * k; gp[j][k] = *(const f32x4*)(gpre + c); sc1[j][k] = *(const f32x4*)(scale + (size_t)mrow * 9216 + c) + 1.0f; sh[j][k] = *(const f32x4*)(shift + (size_t)mrow * 9216 + c); }
; #pragma unroll
;         for (int r = 0; r < R; ++r) {
;             float ss = 0.f;
; #pragma unroll
;             for (int j = 0; j < 2; ++j)
; #pragma unroll
;                 for (int k = 0; k < 2; ++k) ss += (h[r][j][k][0] * h[r][j][k][0] + h[r][j][k][1] * h[r][j][k][1]) + (h[r][j][k][2] * h[r][j][k][2] + h[r][j][k][3] * h[r][j][k][3]);
;             const float rr = __builtin_amdgcn_rsqf(wave_sum(ss) * (1.0f / DM) + 1e-6f);
; #pragma unroll
;             for (int j = 0; j < 2; ++j) { const f32x4 v0 = (h[r][j][0] * rr * gp[j][0]) * sc1[j][0] + sh[j][0], v1 = (h[r][j][1] * rr * gp[j][1]) * sc1[j][1] + sh[j][1];
;                 u32x4 t; t.x = pk2(v0[0], v0[1]); t.y = pk2(v0[2], v0[3]); t.z = pk2(v1[0], v1[1]); t.w = pk2(v1[2], v1[3]);
;                 *(u32x4*)(U + (size_t)(row0 + r) * DM + 8 * lane + 512 * j) = t; }
	v_pk_fma_f32 v[204:205], v[6:7], v[122:123], v[204:205]
	v_pk_fma_f32 v[206:207], v[8:9], v[124:125], v[206:207]
	v_pk_fma_f32 v[208:209], v[10:11], v[126:127], v[208:209]
	v_pk_fma_f32 v[210:211], v[12:13], v[128:129], v[210:211]
	v_pk_fma_f32 v[212:213], v[14:15], v[130:131], v[212:213]
	v_cvt_f16_f32_e32 v132, v198
	v_cvt_f16_f32_e32 v133, v200
	v_cvt_f16_f32_e32 v134, v202
	v_cvt_f16_f32_e32 v135, v204
	v_cvt_f16_f32_e32 v136, v206
	v_cvt_f16_f32_e32 v137, v208
	v_cvt_f16_f32_e32 v138, v210
	v_cvt_f16_f32_e32 v139, v212
	v_cvt_f16_f32_sdwa v132, v199 dst_sel:WORD_1 dst_unused:UNUSED_PRESERVE src0_sel:DWORD
	v_cvt_f16_f32_sdwa v133, v201 dst_sel:WORD_1 dst_unused:UNUSED_PRESERVE src0_sel:DWORD
	v_cvt_f16_f32_sdwa v134, v203 dst_sel:WORD_1 dst_unused:UNUSED_PRESERVE src0_sel:DWORD
	v_cvt_f16_f32_sdwa v135, v205 dst_sel:WORD_1 dst_unused:UNUSED_PRESERVE src0_sel:DWORD
	v_cvt_f16_f32_sdwa v136, v207 dst_sel:WORD_1 dst_unused:UNUSED_PRESERVE src0_sel:DWORD
	v_cvt_f16_f32_sdwa v137, v209 dst_sel:WORD_1 dst_unused:UNUSED_PRESERVE src0_sel:DWORD
	v_cvt_f16_f32_sdwa v138, v211 dst_sel:WORD_1 dst_unused:UNUSED_PRESERVE src0_sel:DWORD
	v_cvt_f16_f32_sdwa v139, v213 dst_sel:WORD_1 dst_unused:UNUSED_PRESERVE src0_sel:DWORD
	s_nop 0
	global_store_dwordx4 v185, v[132:135], s[42:43] offset:-2048
	global_store_dwordx4 v185, v[136:139], s[42:43] offset:-1024
	v_pk_mul_f32 v[140:141], v[198:199], v[198:199]
	v_pk_fma_f32 v[140:141], v[200:201], v[200:201], v[140:141]
	v_pk_fma_f32 v[140:141], v[202:203], v[202:203], v[140:141]
	v_pk_fma_f32 v[140:141], v[204:205], v[204:205], v[140:141]
	v_pk_fma_f32 v[140:141], v[206:207], v[206:207], v[140:141]
	v_pk_fma_f32 v[140:141], v[208:209], v[208:209], v[140:141]
	v_pk_fma_f32 v[140:141], v[210:211], v[210:211], v[140:141]
	v_pk_fma_f32 v[140:141], v[212:213], v[212:213], v[140:141]
	v_add_f32_e32 v140, v140, v141
	s_nop 1
	v_add_f32_dpp v140, v140, v140 quad_perm:[1,0,3,2] row_mask:0xf bank_mask:0xf
	s_nop 1
	v_add_f32_dpp v140, v140, v140 quad_perm:[2,3,0,1] row_mask:0xf bank_mask:0xf
	s_nop 1
	v_add_f32_dpp v140, v140, v140 row_ror:4 row_mask:0xf bank_mask:0xf
	s_nop 1
	v_add_f32_dpp v140, v140, v140 row_ror:8 row_mask:0xf bank_mask:0xf
	s_nop 1
	v_add_f32_dpp v140, v140, v140 row_bcast:15 row_mask:0xa bank_mask:0xf
	s_nop 1
	v_add_f32_dpp v140, v140, v140 row_bcast:31 row_mask:0xc bank_mask:0xf
	s_nop 1
	v_fmamk_f32 v140, v140, 0x3a800000, v224
	v_rsq_f32_e32 v140, v140
	s_nop 0
	v_readlane_b32 s6, v140, 63
	s_nop 1
	v_pk_mul_f32 v[198:199], v[198:199], s[6:7] op_sel_hi:[1,0]
	v_pk_mul_f32 v[200:201], v[200:201], s[6:7] op_sel_hi:[1,0]
	v_pk_mul_f32 v[202:203], v[202:203], s[6:7] op_sel_hi:[1,0]
	v_pk_mul_f32 v[204:205], v[204:205], s[6:7] op_sel_hi:[1,0]
	v_pk_mul_f32 v[206:207], v[206:207], s[6:7] op_sel_hi:[1,0]
	v_pk_mul_f32 v[208:209], v[208:209], s[6:7] op_sel_hi:[1,0]
	v_pk_mul_f32 v[210:211], v[210:211], s[6:7] op_sel_hi:[1,0]
	v_pk_mul_f32 v[212:213], v[212:213], s[6:7] op_sel_hi:[1,0]
	v_pk_mul_f32 v[198:199], v[16:17], v[198:199]
	v_pk_mul_f32 v[200:201], v[18:19], v[200:201]
	v_pk_mul_f32 v[202:203], v[20:21], v[202:203]
	v_pk_mul_f32 v[204:205], v[22:23], v[204:205]
	v_pk_mul_f32 v[206:207], v[24:25], v[206:207]
	v_pk_mul_f32 v[208:209], v[26:27], v[208:209]
	v_pk_mul_f32 v[210:211], v[28:29], v[210:211]
	v_pk_mul_f32 v[212:213], v[30:31], v[212:213]
	v_pk_fma_f32 v[198:199], v[32:33], v[198:199], v[48:49]
	v_pk_fma_f32 v[200:201], v[34:35], v[200:201], v[50:51]
	v_pk_fma_f32 v[202:203], v[36:37], v[202:203], v[52:53]
	v_pk_fma_f32 v[204:205], v[38:39], v[204:205], v[54:55]
	v_pk_fma_f32 v[206:207], v[40:41], v[206:207], v[56:57]
	v_pk_fma_f32 v[208:209], v[42:43], v[208:209], v[58:59]
	v_pk_fma_f32 v[210:211], v[44:45], v[210:211], v[60:61]
	v_pk_fma_f32 v[212:213], v[46:47], v[212:213], v[62:63]
	v_cvt_pk_bf16_f32 v230, v198, v199
	v_cvt_pk_bf16_f32 v231, v200, v201
	v_cvt_pk_bf16_f32 v232, v202, v203
	v_cvt_pk_bf16_f32 v233, v204, v205
	v_cvt_pk_bf16_f32 v234, v206, v207
	v_cvt_pk_bf16_f32 v235, v208, v209
	v_cvt_pk_bf16_f32 v236, v210, v211
	v_cvt_pk_bf16_f32 v237, v212, v213
	global_store_dwordx4 v185, v[230:233], s[44:45] offset:-2048
	global_store_dwordx4 v185, v[234:237], s[44:45] offset:-1024
	s_waitcnt vmcnt(28)
; template <int R, bool SRCB> ...
;     ...
;         for (int r = 0; r < R; ++r) {
;             f32x4 y[2][2]; float ss = 0.f;
; #pragma unroll
;             for (int j = 0; j < 2; ++j) { const u32x4 t = yr[r][j];
;                 y[j][0] = (f32x4){bf_lo(t.x), bf_hi(t.x), bf_lo(t.y), bf_hi(t.y)}; y[j][1] = (f32x4){bf_lo(t.z), bf_hi(t.z), bf_lo(t.w), bf_hi(t.w)};
;                 if (R == 1 && YP) {
; #pragma unroll
;                     for (int k = 0; k < 2; ++k) { const float* pp = YP + (size_t)(row0 - M_LAT) * DM + 8 * lane + 512 * j + 4 * k; f32x4 s = *(const f32x4*)pp;
; #pragma unroll
;                         for (int q = 1; q < pg8::NSL; ++q) s = s + *(const f32x4*)(pp + (size_t)q * 2048 * DM);
;                         y[j][k] = s; } }
; #pragma unroll
;                 for (int k = 0; k < 2; ++k) ss += (y[j][k][0] * y[j][k][0] + y[j][k][1] * y[j][k][1]) + (y[j][k][2] * y[j][k][2] + y[j][k][3] * y[j][k][3]); }
;             const float rr = __builtin_amdgcn_rsqf(wave_sum(ss) * (1.0f / DM) + 1e-6f) * w;
; #pragma unroll
;             for (int j = 0; j < 2; ++j)
; #pragma unroll
;                 for (int k = 0; k < 2; ++k) h[r][j][k] = h[r][j][k] + gg[j][k] * (y[j][k] * rr);
;         }
;     }
; #pragma unroll
;     for (int r = 0; r < R; ++r)
; #pragma unroll
;         for (int j = 0; j < 2; ++j) { const int c = 8 * lane + 512 * j;
;             if (final_out) { *(f32x4*)(final_out + (size_t)(row0 + r) * DM + c) = h[r][j][0]; *(f32x4*)(final_out + (size_t)(row0 + r) * DM + c + 4) = h[r][j][1]; }
;             else { u32x4 t; t.x = pkh2(h[r][j][0][0], h[r][j][0][1]); t.y = pkh2(h[r][j][0][2], h[r][j][0][3]); t.z = pkh2(h[r][j][1][0], h[r][j][1][1]); t.w = pkh2(h[r][j][1][2], h[r][j][1][3]);
;                 *(u32x4*)(hout + (size_t)(row0 + r) * DM + c) = t; } }
;     if (U) {
;         f32x4 gp[2][2], sc1[2][2], sh[2][2];
; #pragma unroll
;         for (int j = 0; j < 2; ++j)
; #pragma unroll
;             for (int k = 0; k < 2; ++k) { const int c = 8 * lane + 512 * j + 4 * k; gp[j][k] = *(const f32x4*)(gpre + c); sc1[j][k] = *(const f32x4*)(scale + (size_t)mrow * 9216 + c) + 1.0f; sh[j][k] = *(const f32x4*)(shift + (size_t)mrow * 9216 + c); }
; #pragma unroll
;         for (int r = 0; r < R; ++r) {
;             float ss = 0.f;
; #pragma unroll
;             for (int j = 0; j < 2; ++j)
; #pragma unroll
	v_lshlrev_b32_e32 v116, 16, v164
	v_and_b32_e32 v117, 0xffff0000, v164
	v_lshlrev_b32_e32 v118, 16, v165
	v_and_b32_e32 v119, 0xffff0000, v165
	v_lshlrev_b32_e32 v120, 16, v166
	v_and_b32_e32 v121, 0xffff0000, v166
	v_lshlrev_b32_e32 v122, 16, v167
	v_and_b32_e32 v123, 0xffff0000, v167
	v_lshlrev_b32_e32 v124, 16, v168
	v_and_b32_e32 v125, 0xffff0000, v168
	v_lshlrev_b32_e32 v126, 16, v169
	v_and_b32_e32 v127, 0xffff0000, v169
	v_lshlrev_b32_e32 v128, 16, v170
	v_and_b32_e32 v129, 0xffff0000, v170
	v_lshlrev_b32_e32 v130, 16, v171
	v_and_b32_e32 v131, 0xffff0000, v171
	v_cvt_f32_f16_e32 v198, v80
	v_cvt_f32_f16_sdwa v199, v80 dst_sel:DWORD dst_unused:UNUSED_PAD src0_sel:WORD_1
	v_cvt_f32_f16_e32 v200, v81
	v_cvt_f32_f16_sdwa v201, v81 dst_sel:DWORD dst_unused:UNUSED_PAD src0_sel:WORD_1
	v_cvt_f32_f16_e32 v202, v82
	v_cvt_f32_f16_sdwa v203, v82 dst_sel:DWORD dst_unused:UNUSED_PAD src0_sel:WORD_1
	v_cvt_f32_f16_e32 v204, v83
	v_cvt_f32_f16_sdwa v205, v83 dst_sel:DWORD dst_unused:UNUSED_PAD src0_sel:WORD_1
	v_cvt_f32_f16_e32 v206, v84
	v_cvt_f32_f16_sdwa v207, v84 dst_sel:DWORD dst_unused:UNUSED_PAD src0_sel:WORD_1
	v_cvt_f32_f16_e32 v208, v85
	v_cvt_f32_f16_sdwa v209, v85 dst_sel:DWORD dst_unused:UNUSED_PAD src0_sel:WORD_1
	v_cvt_f32_f16_e32 v210, v86
	v_cvt_f32_f16_sdwa v211, v86 dst_sel:DWORD dst_unused:UNUSED_PAD src0_sel:WORD_1
	v_cvt_f32_f16_e32 v212, v87
	v_cvt_f32_f16_sdwa v213, v87 dst_sel:DWORD dst_unused:UNUSED_PAD src0_sel:WORD_1
	global_load_dwordx4 v[80:83], v186, s[42:43] offset:0
	global_load_dwordx4 v[84:87], v186, s[42:43] offset:1024
	global_load_dwordx4 v[164:167], v186, s[44:45] offset:0
	global_load_dwordx4 v[168:171], v186, s[44:45] offset:1024
	v_pk_mul_f32 v[140:141], v[116:117], v[116:117]
	v_pk_fma_f32 v[140:141], v[118:119], v[118:119], v[140:141]
	v_pk_fma_f32 v[140:141], v[120:121], v[120:121], v[140:141]
	v_pk_fma_f32 v[140:141], v[122:123], v[122:123], v[140:141]
	v_pk_fma_f32 v[140:141], v[124:125], v[124:125], v[140:141]
	v_pk_fma_f32 v[140:141], v[126:127], v[126:127], v[140:141]
	v_pk_fma_f32 v[140:141], v[128:129], v[128:129], v[140:141]
	v_pk_fma_f32 v[140:141], v[130:131], v[130:131], v[140:141]
	v_add_f32_e32 v140, v140, v141
	s_nop 1
	v_add_f32_dpp v140, v140, v140 quad_perm:[1,0,3,2] row_mask:0xf bank_mask:0xf
	s_nop 1
	v_add_f32_dpp v140, v140, v140 quad_perm:[2,3,0,1] row_mask:0xf bank_mask:0xf
	s_nop 1
	v_add_f32_dpp v140, v140, v140 row_ror:4 row_mask:0xf bank_mask:0xf
	s_nop 1
	v_add_f32_dpp v140, v140, v140 row_ror:8 row_mask:0xf bank_mask:0xf
	s_nop 1
	v_add_f32_dpp v140, v140, v140 row_bcast:15 row_mask:0xa bank_mask:0xf
	s_nop 1
	v_add_f32_dpp v140, v140, v140 row_bcast:31 row_mask:0xc bank_mask:0xf
	s_nop 1
	v_fmamk_f32 v140, v140, 0x3a800000, v224
	v_rsq_f32_e32 v140, v140
	s_nop 0
	v_mul_f32_e32 v140, v144, v140
	s_nop 0
	v_readlane_b32 s4, v140, 63
	s_nop 1
	v_pk_mul_f32 v[116:117], v[116:117], s[4:5] op_sel_hi:[1,0]
	v_pk_mul_f32 v[118:119], v[118:119], s[4:5] op_sel_hi:[1,0]
	v_pk_mul_f32 v[120:121], v[120:121], s[4:5] op_sel_hi:[1,0]
	v_pk_mul_f32 v[122:123], v[122:123], s[4:5] op_sel_hi:[1,0]
	v_pk_mul_f32 v[124:125], v[124:125], s[4:5] op_sel_hi:[1,0]
	v_pk_mul_f32 v[126:127], v[126:127], s[4:5] op_sel_hi:[1,0]
	v_pk_mul_f32 v[128:129], v[128:129], s[4:5] op_sel_hi:[1,0]
	v_pk_mul_f32 v[130:131], v[130:131], s[4:5] op_sel_hi:[1,0]
	v_pk_fma_f32 v[198:199], v[0:1], v[116:117], v[198:199]
	v_pk_fma_f32 v[200:201], v[2:3], v[118:119], v[200:201]
	v_pk_fma_f32 v[202:203], v[4:5], v[120:121], v[202:203]
	v_pk_fma_f32 v[204:205], v[6:7], v[122:123], v[204:205]
	v_pk_fma_f32 v[206:207], v[8:9], v[124:125], v[206:207]
	v_pk_fma_f32 v[208:209], v[10:11], v[126:127], v[208:209]
	v_pk_fma_f32 v[210:211], v[12:13], v[128:129], v[210:211]
	v_pk_fma_f32 v[212:213], v[14:15], v[130:131], v[212:213]
	v_cvt_f16_f32_e32 v132, v198
	v_cvt_f16_f32_e32 v133, v200
	v_cvt_f16_f32_e32 v134, v202
	v_cvt_f16_f32_e32 v135, v204
	v_cvt_f16_f32_e32 v136, v206
	v_cvt_f16_f32_e32 v137, v208
	v_cvt_f16_f32_e32 v138, v210
	v_cvt_f16_f32_e32 v139, v212
	v_cvt_f16_f32_sdwa v132, v199 dst_sel:WORD_1 dst_unused:UNUSED_PRESERVE src0_sel:DWORD
	v_cvt_f16_f32_sdwa v133, v201 dst_sel:WORD_1 dst_unused:UNUSED_PRESERVE src0_sel:DWORD
	v_cvt_f16_f32_sdwa v134, v203 dst_sel:WORD_1 dst_unused:UNUSED_PRESERVE src0_sel:DWORD
	v_cvt_f16_f32_sdwa v135, v205 dst_sel:WORD_1 dst_unused:UNUSED_PRESERVE src0_sel:DWORD
	v_cvt_f16_f32_sdwa v136, v207 dst_sel:WORD_1 dst_unused:UNUSED_PRESERVE src0_sel:DWORD
	v_cvt_f16_f32_sdwa v137, v209 dst_sel:WORD_1 dst_unused:UNUSED_PRESERVE src0_sel:DWORD
	v_cvt_f16_f32_sdwa v138, v211 dst_sel:WORD_1 dst_unused:UNUSED_PRESERVE src0_sel:DWORD
	v_cvt_f16_f32_sdwa v139, v213 dst_sel:WORD_1 dst_unused:UNUSED_PRESERVE src0_sel:DWORD
	s_nop 0
	global_store_dwordx4 v185, v[132:135], s[42:43] offset:0
	global_store_dwordx4 v185, v[136:139], s[42:43] offset:1024
	v_pk_mul_f32 v[140:141], v[198:199], v[198:199]
	v_pk_fma_f32 v[140:141], v[200:201], v[200:201], v[140:141]
	v_pk_fma_f32 v[140:141], v[202:203], v[202:203], v[140:141]
	v_pk_fma_f32 v[140:141], v[204:205], v[204:205], v[140:141]
	v_pk_fma_f32 v[140:141], v[206:207], v[206:207], v[140:141]
	v_pk_fma_f32 v[140:141], v[208:209], v[208:209], v[140:141]
	v_pk_fma_f32 v[140:141], v[210:211], v[210:211], v[140:141]
	v_pk_fma_f32 v[140:141], v[212:213], v[212:213], v[140:141]
	v_add_f32_e32 v140, v140, v141
	s_nop 1
	v_add_f32_dpp v140, v140, v140 quad_perm:[1,0,3,2] row_mask:0xf bank_mask:0xf
	s_nop 1
	v_add_f32_dpp v140, v140, v140 quad_perm:[2,3,0,1] row_mask:0xf bank_mask:0xf
	s_nop 1
	v_add_f32_dpp v140, v140, v140 row_ror:4 row_mask:0xf bank_mask:0xf
; template <int R, bool SRCB> ...
;     ...
;         for (int r = 0; r < R; ++r) {
;             f32x4 y[2][2]; float ss = 0.f;
; #pragma unroll
;             for (int j = 0; j < 2; ++j) { const u32x4 t = yr[r][j];
;                 y[j][0] = (f32x4){bf_lo(t.x), bf_hi(t.x), bf_lo(t.y), bf_hi(t.y)}; y[j][1] = (f32x4){bf_lo(t.z), bf_hi(t.z), bf_lo(t.w), bf_hi(t.w)};
;                 if (R == 1 && YP) {
; #pragma unroll
;                     for (int k = 0; k < 2; ++k) { const float* pp = YP + (size_t)(row0 - M_LAT) * DM + 8 * lane + 512 * j + 4 * k; f32x4 s = *(const f32x4*)pp;
; #pragma unroll
;                         for (int q = 1; q < pg8::NSL; ++q) s = s + *(const f32x4*)(pp + (size_t)q * 2048 * DM);
;                         y[j][k] = s; } }
; #pragma unroll
;                 for (int k = 0; k < 2; ++k) ss += (y[j][k][0] * y[j][k][0] + y[j][k][1] * y[j][k][1]) + (y[j][k][2] * y[j][k][2] + y[j][k][3] * y[j][k][3]); }
;             const float rr = __builtin_amdgcn_rsqf(wave_sum(ss) * (1.0f / DM) + 1e-6f) * w;
; #pragma unroll
;             for (int j = 0; j < 2; ++j)
; #pragma unroll
;                 for (int k = 0; k < 2; ++k) h[r][j][k] = h[r][j][k] + gg[j][k] * (y[j][k] * rr);
;         }
;     }
; #pragma unroll
;     for (int r = 0; r < R; ++r)
; #pragma unroll
;         for (int j = 0; j < 2; ++j) { const int c = 8 * lane + 512 * j;
;             if (final_out) { *(f32x4*)(final_out + (size_t)(row0 + r) * DM + c) = h[r][j][0]; *(f32x4*)(final_out + (size_t)(row0 + r) * DM + c + 4) = h[r][j][1]; }
;             else { u32x4 t; t.x = pkh2(h[r][j][0][0], h[r][j][0][1]); t.y = pkh2(h[r][j][0][2], h[r][j][0][3]); t.z = pkh2(h[r][j][1][0], h[r][j][1][1]); t.w = pkh2(h[r][j][1][2], h[r][j][1][3]);
;                 *(u32x4*)(hout + (size_t)(row0 + r) * DM + c) = t; } }
;     if (U) {
;         f32x4 gp[2][2], sc1[2][2], sh[2][2];
; #pragma unroll
;         for (int j = 0; j < 2; ++j)
; #pragma unroll
;             for (int k = 0; k < 2; ++k) { const int c = 8 * lane + 512 * j + 4 * k; gp[j][k] = *(const f32x4*)(gpre + c); sc1[j][k] = *(const f32x4*)(scale + (size_t)mrow * 9216 + c) + 1.0f; sh[j][k] = *(const f32x4*)(shift + (size_t)mrow * 9216 + c); }
; #pragma unroll
;         for (int r = 0; r < R; ++r) {
;             float ss = 0.f;
; #pragma unroll
;             for (int j = 0; j < 2; ++j)
; #pragma unroll
	s_nop 1
	v_add_f32_dpp v140, v140, v140 row_ror:8 row_mask:0xf bank_mask:0xf
	s_nop 1
	v_add_f32_dpp v140, v140, v140 row_bcast:15 row_mask:0xa bank_mask:0xf
	s_nop 1
	v_add_f32_dpp v140, v140, v140 row_bcast:31 row_mask:0xc bank_mask:0xf
	s_nop 1
	v_fmamk_f32 v140, v140, 0x3a800000, v224
	v_rsq_f32_e32 v140, v140
	s_nop 0
	v_readlane_b32 s6, v140, 63
	s_nop 1
	v_pk_mul_f32 v[198:199], v[198:199], s[6:7] op_sel_hi:[1,0]
	v_pk_mul_f32 v[200:201], v[200:201], s[6:7] op_sel_hi:[1,0]
	v_pk_mul_f32 v[202:203], v[202:203], s[6:7] op_sel_hi:[1,0]
	v_pk_mul_f32 v[204:205], v[204:205], s[6:7] op_sel_hi:[1,0]
	v_pk_mul_f32 v[206:207], v[206:207], s[6:7] op_sel_hi:[1,0]
	v_pk_mul_f32 v[208:209], v[208:209], s[6:7] op_sel_hi:[1,0]
	v_pk_mul_f32 v[210:211], v[210:211], s[6:7] op_sel_hi:[1,0]
	v_pk_mul_f32 v[212:213], v[212:213], s[6:7] op_sel_hi:[1,0]
	v_pk_mul_f32 v[198:199], v[16:17], v[198:199]
	v_pk_mul_f32 v[200:201], v[18:19], v[200:201]
	v_pk_mul_f32 v[202:203], v[20:21], v[202:203]
	v_pk_mul_f32 v[204:205], v[22:23], v[204:205]
	v_pk_mul_f32 v[206:207], v[24:25], v[206:207]
	v_pk_mul_f32 v[208:209], v[26:27], v[208:209]
	v_pk_mul_f32 v[210:211], v[28:29], v[210:211]
	v_pk_mul_f32 v[212:213], v[30:31], v[212:213]
	v_pk_fma_f32 v[198:199], v[32:33], v[198:199], v[48:49]
	v_pk_fma_f32 v[200:201], v[34:35], v[200:201], v[50:51]
	v_pk_fma_f32 v[202:203], v[36:37], v[202:203], v[52:53]
	v_pk_fma_f32 v[204:205], v[38:39], v[204:205], v[54:55]
	v_pk_fma_f32 v[206:207], v[40:41], v[206:207], v[56:57]
	v_pk_fma_f32 v[208:209], v[42:43], v[208:209], v[58:59]
	v_pk_fma_f32 v[210:211], v[44:45], v[210:211], v[60:61]
	v_pk_fma_f32 v[212:213], v[46:47], v[212:213], v[62:63]
	v_cvt_pk_bf16_f32 v230, v198, v199
	v_cvt_pk_bf16_f32 v231, v200, v201
	v_cvt_pk_bf16_f32 v232, v202, v203
	v_cvt_pk_bf16_f32 v233, v204, v205
	v_cvt_pk_bf16_f32 v234, v206, v207
	v_cvt_pk_bf16_f32 v235, v208, v209
	v_cvt_pk_bf16_f32 v236, v210, v211
	v_cvt_pk_bf16_f32 v237, v212, v213
	global_store_dwordx4 v185, v[230:233], s[44:45] offset:0
	global_store_dwordx4 v185, v[234:237], s[44:45] offset:1024
	s_waitcnt vmcnt(28)
	v_lshlrev_b32_e32 v116, 16, v172
	v_and_b32_e32 v117, 0xffff0000, v172
	v_lshlrev_b32_e32 v118, 16, v173
	v_and_b32_e32 v119, 0xffff0000, v173
	v_lshlrev_b32_e32 v120, 16, v174
	v_and_b32_e32 v121, 0xffff0000, v174
	v_lshlrev_b32_e32 v122, 16, v175
	v_and_b32_e32 v123, 0xffff0000, v175
	v_lshlrev_b32_e32 v124, 16, v176
	v_and_b32_e32 v125, 0xffff0000, v176
	v_lshlrev_b32_e32 v126, 16, v177
	v_and_b32_e32 v127, 0xffff0000, v177
	v_lshlrev_b32_e32 v128, 16, v178
	v_and_b32_e32 v129, 0xffff0000, v178
	v_lshlrev_b32_e32 v130, 16, v179
	v_and_b32_e32 v131, 0xffff0000, v179
	v_cvt_f32_f16_e32 v198, v88
	v_cvt_f32_f16_sdwa v199, v88 dst_sel:DWORD dst_unused:UNUSED_PAD src0_sel:WORD_1
	v_cvt_f32_f16_e32 v200, v89
	v_cvt_f32_f16_sdwa v201, v89 dst_sel:DWORD dst_unused:UNUSED_PAD src0_sel:WORD_1
	v_cvt_f32_f16_e32 v202, v90
	v_cvt_f32_f16_sdwa v203, v90 dst_sel:DWORD dst_unused:UNUSED_PAD src0_sel:WORD_1
	v_cvt_f32_f16_e32 v204, v91
	v_cvt_f32_f16_sdwa v205, v91 dst_sel:DWORD dst_unused:UNUSED_PAD src0_sel:WORD_1
	v_cvt_f32_f16_e32 v206, v92
	v_cvt_f32_f16_sdwa v207, v92 dst_sel:DWORD dst_unused:UNUSED_PAD src0_sel:WORD_1
	v_cvt_f32_f16_e32 v208, v93
	v_cvt_f32_f16_sdwa v209, v93 dst_sel:DWORD dst_unused:UNUSED_PAD src0_sel:WORD_1
	v_cvt_f32_f16_e32 v210, v94
	v_cvt_f32_f16_sdwa v211, v94 dst_sel:DWORD dst_unused:UNUSED_PAD src0_sel:WORD_1
	v_cvt_f32_f16_e32 v212, v95
	v_cvt_f32_f16_sdwa v213, v95 dst_sel:DWORD dst_unused:UNUSED_PAD src0_sel:WORD_1
	global_load_dwordx4 v[88:91], v186, s[42:43] offset:2048
	global_load_dwordx4 v[92:95], v186, s[42:43] offset:3072
	global_load_dwordx4 v[172:175], v186, s[44:45] offset:2048
	global_load_dwordx4 v[176:179], v186, s[44:45] offset:3072
	v_pk_mul_f32 v[140:141], v[116:117], v[116:117]
	v_pk_fma_f32 v[140:141], v[118:119], v[118:119], v[140:141]
	v_pk_fma_f32 v[140:141], v[120:121], v[120:121], v[140:141]
	v_pk_fma_f32 v[140:141], v[122:123], v[122:123], v[140:141]
	v_pk_fma_f32 v[140:141], v[124:125], v[124:125], v[140:141]
	v_pk_fma_f32 v[140:141], v[126:127], v[126:127], v[140:141]
	v_pk_fma_f32 v[140:141], v[128:129], v[128:129], v[140:141]
	v_pk_fma_f32 v[140:141], v[130:131], v[130:131], v[140:141]
	v_add_f32_e32 v140, v140, v141
	s_nop 1
	v_add_f32_dpp v140, v140, v140 quad_perm:[1,0,3,2] row_mask:0xf bank_mask:0xf
	s_nop 1
	v_add_f32_dpp v140, v140, v140 quad_perm:[2,3,0,1] row_mask:0xf bank_mask:0xf
	s_nop 1
	v_add_f32_dpp v140, v140, v140 row_ror:4 row_mask:0xf bank_mask:0xf
	s_nop 1
	v_add_f32_dpp v140, v140, v140 row_ror:8 row_mask:0xf bank_mask:0xf
	s_nop 1
	v_add_f32_dpp v140, v140, v140 row_bcast:15 row_mask:0xa bank_mask:0xf
	s_nop 1
	v_add_f32_dpp v140, v140, v140 row_bcast:31 row_mask:0xc bank_mask:0xf
	s_nop 1
	v_fmamk_f32 v140, v140, 0x3a800000, v224
	v_rsq_f32_e32 v140, v140
	s_nop 0
	v_mul_f32_e32 v140, v144, v140
	s_nop 0
	v_readlane_b32 s4, v140, 63
	s_nop 1
	v_pk_mul_f32 v[116:117], v[116:117], s[4:5] op_sel_hi:[1,0]
	v_pk_mul_f32 v[118:119], v[118:119], s[4:5] op_sel_hi:[1,0]
	v_pk_mul_f32 v[120:121], v[120:121], s[4:5] op_sel_hi:[1,0]
	v_pk_mul_f32 v[122:123], v[122:123], s[4:5] op_sel_hi:[1,0]
	v_pk_mul_f32 v[124:125], v[124:125], s[4:5] op_sel_hi:[1,0]
	v_pk_mul_f32 v[126:127], v[126:127], s[4:5] op_sel_hi:[1,0]
	v_pk_mul_f32 v[128:129], v[128:129], s[4:5] op_sel_hi:[1,0]
	v_pk_mul_f32 v[130:131], v[130:131], s[4:5] op_sel_hi:[1,0]
	v_pk_fma_f32 v[198:199], v[0:1], v[116:117], v[198:199]
	v_pk_fma_f32 v[200:201], v[2:3], v[118:119], v[200:201]
	v_pk_fma_f32 v[202:203], v[4:5], v[120:121], v[202:203]
; __device__ __forceinline__ unsigned pk2(float lo, float hi) { return pg8::cvt_pk_bf16(lo, hi); }
; template <int R, bool SRCB> ...
;     ...
;             const float rr = __builtin_amdgcn_rsqf(wave_sum(ss) * (1.0f / DM) + 1e-6f) * w;
; #pragma unroll
;             for (int j = 0; j < 2; ++j)
; #pragma unroll
;                 for (int k = 0; k < 2; ++k) h[r][j][k] = h[r][j][k] + gg[j][k] * (y[j][k] * rr);
;         }
;     }
; #pragma unroll
;     for (int r = 0; r < R; ++r)
; #pragma unroll
;         for (int j = 0; j < 2; ++j) { const int c = 8 * lane + 512 * j;
;             if (final_out) { *(f32x4*)(final_out + (size_t)(row0 + r) * DM + c) = h[r][j][0]; *(f32x4*)(final_out + (size_t)(row0 + r) * DM + c + 4) = h[r][j][1]; }
;             else { u32x4 t; t.x = pkh2(h[r][j][0][0], h[r][j][0][1]); t.y = pkh2(h[r][j][0][2], h[r][j][0][3]); t.z = pkh2(h[r][j][1][0], h[r][j][1][1]); t.w = pkh2(h[r][j][1][2], h[r][j][1][3]);
;                 *(u32x4*)(hout + (size_t)(row0 + r) * DM + c) = t; } }
;     if (U) {
;         f32x4 gp[2][2], sc1[2][2], sh[2][2];
; #pragma unroll
;         for (int j = 0; j < 2; ++j)
; #pragma unroll
;             for (int k = 0; k < 2; ++k) { const int c = 8 * lane + 512 * j + 4 * k; gp[j][k] = *(const f32x4*)(gpre + c); sc1[j][k] = *(const f32x4*)(scale + (size_t)mrow * 9216 + c) + 1.0f; sh[j][k] = *(const f32x4*)(shift + (size_t)mrow * 9216 + c); }
; #pragma unroll
;         for (int r = 0; r < R; ++r) {
;             float ss = 0.f;
; #pragma unroll
;             for (int j = 0; j < 2; ++j)
; #pragma unroll
;                 for (int k = 0; k < 2; ++k) ss += (h[r][j][k][0] * h[r][j][k][0] + h[r][j][k][1] * h[r][j][k][1]) + (h[r][j][k][2] * h[r][j][k][2] + h[r][j][k][3] * h[r][j][k][3]);
;             const float rr = __builtin_amdgcn_rsqf(wave_sum(ss) * (1.0f / DM) + 1e-6f);
; #pragma unroll
;             for (int j = 0; j < 2; ++j) { const f32x4 v0 = (h[r][j][0] * rr * gp[j][0]) * sc1[j][0] + sh[j][0], v1 = (h[r][j][1] * rr * gp[j][1]) * sc1[j][1] + sh[j][1];
;                 u32x4 t; t.x = pk2(v0[0], v0[1]); t.y = pk2(v0[2], v0[3]); t.z = pk2(v1[0], v1[1]); t.w = pk2(v1[2], v1[3]);
;                 *(u32x4*)(U + (size_t)(row0 + r) * DM + 8 * lane + 512 * j) = t; }
	v_pk_fma_f32 v[204:205], v[6:7], v[122:123], v[204:205]
	v_pk_fma_f32 v[206:207], v[8:9], v[124:125], v[206:207]
	v_pk_fma_f32 v[208:209], v[10:11], v[126:127], v[208:209]
	v_pk_fma_f32 v[210:211], v[12:13], v[128:129], v[210:211]
	v_pk_fma_f32 v[212:213], v[14:15], v[130:131], v[212:213]
	v_cvt_f16_f32_e32 v132, v198
	v_cvt_f16_f32_e32 v133, v200
	v_cvt_f16_f32_e32 v134, v202
	v_cvt_f16_f32_e32 v135, v204
	v_cvt_f16_f32_e32 v136, v206
	v_cvt_f16_f32_e32 v137, v208
	v_cvt_f16_f32_e32 v138, v210
	v_cvt_f16_f32_e32 v139, v212
	v_cvt_f16_f32_sdwa v132, v199 dst_sel:WORD_1 dst_unused:UNUSED_PRESERVE src0_sel:DWORD
	v_cvt_f16_f32_sdwa v133, v201 dst_sel:WORD_1 dst_unused:UNUSED_PRESERVE src0_sel:DWORD
	v_cvt_f16_f32_sdwa v134, v203 dst_sel:WORD_1 dst_unused:UNUSED_PRESERVE src0_sel:DWORD
	v_cvt_f16_f32_sdwa v135, v205 dst_sel:WORD_1 dst_unused:UNUSED_PRESERVE src0_sel:DWORD
	v_cvt_f16_f32_sdwa v136, v207 dst_sel:WORD_1 dst_unused:UNUSED_PRESERVE src0_sel:DWORD
	v_cvt_f16_f32_sdwa v137, v209 dst_sel:WORD_1 dst_unused:UNUSED_PRESERVE src0_sel:DWORD
	v_cvt_f16_f32_sdwa v138, v211 dst_sel:WORD_1 dst_unused:UNUSED_PRESERVE src0_sel:DWORD
	v_cvt_f16_f32_sdwa v139, v213 dst_sel:WORD_1 dst_unused:UNUSED_PRESERVE src0_sel:DWORD
	s_nop 0
	global_store_dwordx4 v185, v[132:135], s[42:43] offset:2048
	global_store_dwordx4 v185, v[136:139], s[42:43] offset:3072
	v_pk_mul_f32 v[140:141], v[198:199], v[198:199]
	v_pk_fma_f32 v[140:141], v[200:201], v[200:201], v[140:141]
	v_pk_fma_f32 v[140:141], v[202:203], v[202:203], v[140:141]
	v_pk_fma_f32 v[140:141], v[204:205], v[204:205], v[140:141]
	v_pk_fma_f32 v[140:141], v[206:207], v[206:207], v[140:141]
	v_pk_fma_f32 v[140:141], v[208:209], v[208:209], v[140:141]
	v_pk_fma_f32 v[140:141], v[210:211], v[210:211], v[140:141]
	v_pk_fma_f32 v[140:141], v[212:213], v[212:213], v[140:141]
	v_add_f32_e32 v140, v140, v141
	s_nop 1
	v_add_f32_dpp v140, v140, v140 quad_perm:[1,0,3,2] row_mask:0xf bank_mask:0xf
	s_nop 1
	v_add_f32_dpp v140, v140, v140 quad_perm:[2,3,0,1] row_mask:0xf bank_mask:0xf
	s_nop 1
	v_add_f32_dpp v140, v140, v140 row_ror:4 row_mask:0xf bank_mask:0xf
	s_nop 1
	v_add_f32_dpp v140, v140, v140 row_ror:8 row_mask:0xf bank_mask:0xf
	s_nop 1
	v_add_f32_dpp v140, v140, v140 row_bcast:15 row_mask:0xa bank_mask:0xf
	s_nop 1
	v_add_f32_dpp v140, v140, v140 row_bcast:31 row_mask:0xc bank_mask:0xf
	s_nop 1
	v_fmamk_f32 v140, v140, 0x3a800000, v224
	v_rsq_f32_e32 v140, v140
	s_nop 0
	v_readlane_b32 s6, v140, 63
	s_nop 1
	v_pk_mul_f32 v[198:199], v[198:199], s[6:7] op_sel_hi:[1,0]
	v_pk_mul_f32 v[200:201], v[200:201], s[6:7] op_sel_hi:[1,0]
	v_pk_mul_f32 v[202:203], v[202:203], s[6:7] op_sel_hi:[1,0]
	v_pk_mul_f32 v[204:205], v[204:205], s[6:7] op_sel_hi:[1,0]
	v_pk_mul_f32 v[206:207], v[206:207], s[6:7] op_sel_hi:[1,0]
	v_pk_mul_f32 v[208:209], v[208:209], s[6:7] op_sel_hi:[1,0]
	v_pk_mul_f32 v[210:211], v[210:211], s[6:7] op_sel_hi:[1,0]
	v_pk_mul_f32 v[212:213], v[212:213], s[6:7] op_sel_hi:[1,0]
	v_pk_mul_f32 v[198:199], v[16:17], v[198:199]
	v_pk_mul_f32 v[200:201], v[18:19], v[200:201]
	v_pk_mul_f32 v[202:203], v[20:21], v[202:203]
	v_pk_mul_f32 v[204:205], v[22:23], v[204:205]
	v_pk_mul_f32 v[206:207], v[24:25], v[206:207]
	v_pk_mul_f32 v[208:209], v[26:27], v[208:209]
	v_pk_mul_f32 v[210:211], v[28:29], v[210:211]
	v_pk_mul_f32 v[212:213], v[30:31], v[212:213]
	v_pk_fma_f32 v[198:199], v[32:33], v[198:199], v[48:49]
	v_pk_fma_f32 v[200:201], v[34:35], v[200:201], v[50:51]
	v_pk_fma_f32 v[202:203], v[36:37], v[202:203], v[52:53]
	v_pk_fma_f32 v[204:205], v[38:39], v[204:205], v[54:55]
	v_pk_fma_f32 v[206:207], v[40:41], v[206:207], v[56:57]
	v_pk_fma_f32 v[208:209], v[42:43], v[208:209], v[58:59]
	v_pk_fma_f32 v[210:211], v[44:45], v[210:211], v[60:61]
	v_pk_fma_f32 v[212:213], v[46:47], v[212:213], v[62:63]
	v_cvt_pk_bf16_f32 v230, v198, v199
	v_cvt_pk_bf16_f32 v231, v200, v201
	v_cvt_pk_bf16_f32 v232, v202, v203
	v_cvt_pk_bf16_f32 v233, v204, v205
	v_cvt_pk_bf16_f32 v234, v206, v207
	v_cvt_pk_bf16_f32 v235, v208, v209
	v_cvt_pk_bf16_f32 v236, v210, v211
	v_cvt_pk_bf16_f32 v237, v212, v213
	global_store_dwordx4 v185, v[230:233], s[44:45] offset:2048
	global_store_dwordx4 v185, v[234:237], s[44:45] offset:3072
	s_waitcnt vmcnt(28)
; template <int R, bool SRCB> ...
;     ...
;         for (int r = 0; r < R; ++r) {
;             f32x4 y[2][2]; float ss = 0.f;
; #pragma unroll
;             for (int j = 0; j < 2; ++j) { const u32x4 t = yr[r][j];
;                 y[j][0] = (f32x4){bf_lo(t.x), bf_hi(t.x), bf_lo(t.y), bf_hi(t.y)}; y[j][1] = (f32x4){bf_lo(t.z), bf_hi(t.z), bf_lo(t.w), bf_hi(t.w)};
;                 if (R == 1 && YP) {
; #pragma unroll
;                     for (int k = 0; k < 2; ++k) { const float* pp = YP + (size_t)(row0 - M_LAT) * DM + 8 * lane + 512 * j + 4 * k; f32x4 s = *(const f32x4*)pp;
; #pragma unroll
;                         for (int q = 1; q < pg8::NSL; ++q) s = s + *(const f32x4*)(pp + (size_t)q * 2048 * DM);
;                         y[j][k] = s; } }
; #pragma unroll
;                 for (int k = 0; k < 2; ++k) ss += (y[j][k][0] * y[j][k][0] + y[j][k][1] * y[j][k][1]) + (y[j][k][2] * y[j][k][2] + y[j][k][3] * y[j][k][3]); }
;             const float rr = __builtin_amdgcn_rsqf(wave_sum(ss) * (1.0f / DM) + 1e-6f) * w;
; #pragma unroll
;             for (int j = 0; j < 2; ++j)
; #pragma unroll
;                 for (int k = 0; k < 2; ++k) h[r][j][k] = h[r][j][k] + gg[j][k] * (y[j][k] * rr);
;         }
;     }
; #pragma unroll
;     for (int r = 0; r < R; ++r)
; #pragma unroll
;         for (int j = 0; j < 2; ++j) { const int c = 8 * lane + 512 * j;
;             if (final_out) { *(f32x4*)(final_out + (size_t)(row0 + r) * DM + c) = h[r][j][0]; *(f32x4*)(final_out + (size_t)(row0 + r) * DM + c + 4) = h[r][j][1]; }
;             else { u32x4 t; t.x = pkh2(h[r][j][0][0], h[r][j][0][1]); t.y = pkh2(h[r][j][0][2], h[r][j][0][3]); t.z = pkh2(h[r][j][1][0], h[r][j][1][1]); t.w = pkh2(h[r][j][1][2], h[r][j][1][3]);
;                 *(u32x4*)(hout + (size_t)(row0 + r) * DM + c) = t; } }
;     if (U) {
;         f32x4 gp[2][2], sc1[2][2], sh[2][2];
; #pragma unroll
;         for (int j = 0; j < 2; ++j)
; #pragma unroll
;             for (int k = 0; k < 2; ++k) { const int c = 8 * lane + 512 * j + 4 * k; gp[j][k] = *(const f32x4*)(gpre + c); sc1[j][k] = *(const f32x4*)(scale + (size_t)mrow * 9216 + c) + 1.0f; sh[j][k] = *(const f32x4*)(shift + (size_t)mrow * 9216 + c); }
; #pragma unroll
;         for (int r = 0; r < R; ++r) {
;             float ss = 0.f;
; #pragma unroll
;             for (int j = 0; j < 2; ++j)
; #pragma unroll
	v_lshlrev_b32_e32 v116, 16, v148
	v_and_b32_e32 v117, 0xffff0000, v148
	v_lshlrev_b32_e32 v118, 16, v149
	v_and_b32_e32 v119, 0xffff0000, v149
	v_lshlrev_b32_e32 v120, 16, v150
	v_and_b32_e32 v121, 0xffff0000, v150
	v_lshlrev_b32_e32 v122, 16, v151
	v_and_b32_e32 v123, 0xffff0000, v151
	v_lshlrev_b32_e32 v124, 16, v152
	v_and_b32_e32 v125, 0xffff0000, v152
	v_lshlrev_b32_e32 v126, 16, v153
	v_and_b32_e32 v127, 0xffff0000, v153
	v_lshlrev_b32_e32 v128, 16, v154
	v_and_b32_e32 v129, 0xffff0000, v154
	v_lshlrev_b32_e32 v130, 16, v155
	v_and_b32_e32 v131, 0xffff0000, v155
	v_cvt_f32_f16_e32 v198, v64
	v_cvt_f32_f16_sdwa v199, v64 dst_sel:DWORD dst_unused:UNUSED_PAD src0_sel:WORD_1
	v_cvt_f32_f16_e32 v200, v65
	v_cvt_f32_f16_sdwa v201, v65 dst_sel:DWORD dst_unused:UNUSED_PAD src0_sel:WORD_1
	v_cvt_f32_f16_e32 v202, v66
	v_cvt_f32_f16_sdwa v203, v66 dst_sel:DWORD dst_unused:UNUSED_PAD src0_sel:WORD_1
	v_cvt_f32_f16_e32 v204, v67
	v_cvt_f32_f16_sdwa v205, v67 dst_sel:DWORD dst_unused:UNUSED_PAD src0_sel:WORD_1
	v_cvt_f32_f16_e32 v206, v68
	v_cvt_f32_f16_sdwa v207, v68 dst_sel:DWORD dst_unused:UNUSED_PAD src0_sel:WORD_1
	v_cvt_f32_f16_e32 v208, v69
	v_cvt_f32_f16_sdwa v209, v69 dst_sel:DWORD dst_unused:UNUSED_PAD src0_sel:WORD_1
	v_cvt_f32_f16_e32 v210, v70
	v_cvt_f32_f16_sdwa v211, v70 dst_sel:DWORD dst_unused:UNUSED_PAD src0_sel:WORD_1
	v_cvt_f32_f16_e32 v212, v71
	v_cvt_f32_f16_sdwa v213, v71 dst_sel:DWORD dst_unused:UNUSED_PAD src0_sel:WORD_1
	global_load_dwordx4 v[64:67], v187, s[42:43] offset:-4096
	global_load_dwordx4 v[68:71], v187, s[42:43] offset:-3072
	global_load_dwordx4 v[148:151], v187, s[44:45] offset:-4096
	global_load_dwordx4 v[152:155], v187, s[44:45] offset:-3072
	v_pk_mul_f32 v[140:141], v[116:117], v[116:117]
	v_pk_fma_f32 v[140:141], v[118:119], v[118:119], v[140:141]
	v_pk_fma_f32 v[140:141], v[120:121], v[120:121], v[140:141]
	v_pk_fma_f32 v[140:141], v[122:123], v[122:123], v[140:141]
	v_pk_fma_f32 v[140:141], v[124:125], v[124:125], v[140:141]
	v_pk_fma_f32 v[140:141], v[126:127], v[126:127], v[140:141]
	v_pk_fma_f32 v[140:141], v[128:129], v[128:129], v[140:141]
	v_pk_fma_f32 v[140:141], v[130:131], v[130:131], v[140:141]
	v_add_f32_e32 v140, v140, v141
	s_nop 1
	v_add_f32_dpp v140, v140, v140 quad_perm:[1,0,3,2] row_mask:0xf bank_mask:0xf
	s_nop 1
	v_add_f32_dpp v140, v140, v140 quad_perm:[2,3,0,1] row_mask:0xf bank_mask:0xf
	s_nop 1
	v_add_f32_dpp v140, v140, v140 row_ror:4 row_mask:0xf bank_mask:0xf
	s_nop 1
	v_add_f32_dpp v140, v140, v140 row_ror:8 row_mask:0xf bank_mask:0xf
	s_nop 1
	v_add_f32_dpp v140, v140, v140 row_bcast:15 row_mask:0xa bank_mask:0xf
	s_nop 1
	v_add_f32_dpp v140, v140, v140 row_bcast:31 row_mask:0xc bank_mask:0xf
	s_nop 1
	v_fmamk_f32 v140, v140, 0x3a800000, v224
	v_rsq_f32_e32 v140, v140
	s_nop 0
	v_mul_f32_e32 v140, v144, v140
	s_nop 0
	v_readlane_b32 s4, v140, 63
	s_nop 1
	v_pk_mul_f32 v[116:117], v[116:117], s[4:5] op_sel_hi:[1,0]
	v_pk_mul_f32 v[118:119], v[118:119], s[4:5] op_sel_hi:[1,0]
	v_pk_mul_f32 v[120:121], v[120:121], s[4:5] op_sel_hi:[1,0]
	v_pk_mul_f32 v[122:123], v[122:123], s[4:5] op_sel_hi:[1,0]
	v_pk_mul_f32 v[124:125], v[124:125], s[4:5] op_sel_hi:[1,0]
	v_pk_mul_f32 v[126:127], v[126:127], s[4:5] op_sel_hi:[1,0]
	v_pk_mul_f32 v[128:129], v[128:129], s[4:5] op_sel_hi:[1,0]
	v_pk_mul_f32 v[130:131], v[130:131], s[4:5] op_sel_hi:[1,0]
	v_pk_fma_f32 v[198:199], v[0:1], v[116:117], v[198:199]
	v_pk_fma_f32 v[200:201], v[2:3], v[118:119], v[200:201]
	v_pk_fma_f32 v[202:203], v[4:5], v[120:121], v[202:203]
	v_pk_fma_f32 v[204:205], v[6:7], v[122:123], v[204:205]
	v_pk_fma_f32 v[206:207], v[8:9], v[124:125], v[206:207]
	v_pk_fma_f32 v[208:209], v[10:11], v[126:127], v[208:209]
	v_pk_fma_f32 v[210:211], v[12:13], v[128:129], v[210:211]
	v_pk_fma_f32 v[212:213], v[14:15], v[130:131], v[212:213]
	v_cvt_f16_f32_e32 v132, v198
	v_cvt_f16_f32_e32 v133, v200
	v_cvt_f16_f32_e32 v134, v202
	v_cvt_f16_f32_e32 v135, v204
	v_cvt_f16_f32_e32 v136, v206
	v_cvt_f16_f32_e32 v137, v208
	v_cvt_f16_f32_e32 v138, v210
	v_cvt_f16_f32_e32 v139, v212
	v_cvt_f16_f32_sdwa v132, v199 dst_sel:WORD_1 dst_unused:UNUSED_PRESERVE src0_sel:DWORD
	v_cvt_f16_f32_sdwa v133, v201 dst_sel:WORD_1 dst_unused:UNUSED_PRESERVE src0_sel:DWORD
	v_cvt_f16_f32_sdwa v134, v203 dst_sel:WORD_1 dst_unused:UNUSED_PRESERVE src0_sel:DWORD
	v_cvt_f16_f32_sdwa v135, v205 dst_sel:WORD_1 dst_unused:UNUSED_PRESERVE src0_sel:DWORD
	v_cvt_f16_f32_sdwa v136, v207 dst_sel:WORD_1 dst_unused:UNUSED_PRESERVE src0_sel:DWORD
	v_cvt_f16_f32_sdwa v137, v209 dst_sel:WORD_1 dst_unused:UNUSED_PRESERVE src0_sel:DWORD
	v_cvt_f16_f32_sdwa v138, v211 dst_sel:WORD_1 dst_unused:UNUSED_PRESERVE src0_sel:DWORD
	v_cvt_f16_f32_sdwa v139, v213 dst_sel:WORD_1 dst_unused:UNUSED_PRESERVE src0_sel:DWORD
	s_nop 0
	global_store_dwordx4 v186, v[132:135], s[42:43] offset:-4096
	global_store_dwordx4 v186, v[136:139], s[42:43] offset:-3072
	v_pk_mul_f32 v[140:141], v[198:199], v[198:199]
	v_pk_fma_f32 v[140:141], v[200:201], v[200:201], v[140:141]
	v_pk_fma_f32 v[140:141], v[202:203], v[202:203], v[140:141]
	v_pk_fma_f32 v[140:141], v[204:205], v[204:205], v[140:141]
	v_pk_fma_f32 v[140:141], v[206:207], v[206:207], v[140:141]
	v_pk_fma_f32 v[140:141], v[208:209], v[208:209], v[140:141]
	v_pk_fma_f32 v[140:141], v[210:211], v[210:211], v[140:141]
	v_pk_fma_f32 v[140:141], v[212:213], v[212:213], v[140:141]
	v_add_f32_e32 v140, v140, v141
	s_nop 1
	v_add_f32_dpp v140, v140, v140 quad_perm:[1,0,3,2] row_mask:0xf bank_mask:0xf
	s_nop 1
	v_add_f32_dpp v140, v140, v140 quad_perm:[2,3,0,1] row_mask:0xf bank_mask:0xf
	s_nop 1
	v_add_f32_dpp v140, v140, v140 row_ror:4 row_mask:0xf bank_mask:0xf
; template <int R, bool SRCB> ...
;     ...
;         for (int r = 0; r < R; ++r) {
;             f32x4 y[2][2]; float ss = 0.f;
; #pragma unroll
;             for (int j = 0; j < 2; ++j) { const u32x4 t = yr[r][j];
;                 y[j][0] = (f32x4){bf_lo(t.x), bf_hi(t.x), bf_lo(t.y), bf_hi(t.y)}; y[j][1] = (f32x4){bf_lo(t.z), bf_hi(t.z), bf_lo(t.w), bf_hi(t.w)};
;                 if (R == 1 && YP) {
; #pragma unroll
;                     for (int k = 0; k < 2; ++k) { const float* pp = YP + (size_t)(row0 - M_LAT) * DM + 8 * lane + 512 * j + 4 * k; f32x4 s = *(const f32x4*)pp;
; #pragma unroll
;                         for (int q = 1; q < pg8::NSL; ++q) s = s + *(const f32x4*)(pp + (size_t)q * 2048 * DM);
;                         y[j][k] = s; } }
; #pragma unroll
;                 for (int k = 0; k < 2; ++k) ss += (y[j][k][0] * y[j][k][0] + y[j][k][1] * y[j][k][1]) + (y[j][k][2] * y[j][k][2] + y[j][k][3] * y[j][k][3]); }
;             const float rr = __builtin_amdgcn_rsqf(wave_sum(ss) * (1.0f / DM) + 1e-6f) * w;
; #pragma unroll
;             for (int j = 0; j < 2; ++j)
; #pragma unroll
;                 for (int k = 0; k < 2; ++k) h[r][j][k] = h[r][j][k] + gg[j][k] * (y[j][k] * rr);
;         }
;     }
; #pragma unroll
;     for (int r = 0; r < R; ++r)
; #pragma unroll
;         for (int j = 0; j < 2; ++j) { const int c = 8 * lane + 512 * j;
;             if (final_out) { *(f32x4*)(final_out + (size_t)(row0 + r) * DM + c) = h[r][j][0]; *(f32x4*)(final_out + (size_t)(row0 + r) * DM + c + 4) = h[r][j][1]; }
;             else { u32x4 t; t.x = pkh2(h[r][j][0][0], h[r][j][0][1]); t.y = pkh2(h[r][j][0][2], h[r][j][0][3]); t.z = pkh2(h[r][j][1][0], h[r][j][1][1]); t.w = pkh2(h[r][j][1][2], h[r][j][1][3]);
;                 *(u32x4*)(hout + (size_t)(row0 + r) * DM + c) = t; } }
;     if (U) {
;         f32x4 gp[2][2], sc1[2][2], sh[2][2];
; #pragma unroll
;         for (int j = 0; j < 2; ++j)
; #pragma unroll
;             for (int k = 0; k < 2; ++k) { const int c = 8 * lane + 512 * j + 4 * k; gp[j][k] = *(const f32x4*)(gpre + c); sc1[j][k] = *(const f32x4*)(scale + (size_t)mrow * 9216 + c) + 1.0f; sh[j][k] = *(const f32x4*)(shift + (size_t)mrow * 9216 + c); }
; #pragma unroll
;         for (int r = 0; r < R; ++r) {
;             float ss = 0.f;
; #pragma unroll
;             for (int j = 0; j < 2; ++j)
; #pragma unroll
	s_nop 1
	v_add_f32_dpp v140, v140, v140 row_ror:8 row_mask:0xf bank_mask:0xf
	s_nop 1
	v_add_f32_dpp v140, v140, v140 row_bcast:15 row_mask:0xa bank_mask:0xf
	s_nop 1
	v_add_f32_dpp v140, v140, v140 row_bcast:31 row_mask:0xc bank_mask:0xf
	s_nop 1
	v_fmamk_f32 v140, v140, 0x3a800000, v224
	v_rsq_f32_e32 v140, v140
	s_nop 0
	v_readlane_b32 s6, v140, 63
	s_nop 1
	v_pk_mul_f32 v[198:199], v[198:199], s[6:7] op_sel_hi:[1,0]
	v_pk_mul_f32 v[200:201], v[200:201], s[6:7] op_sel_hi:[1,0]
	v_pk_mul_f32 v[202:203], v[202:203], s[6:7] op_sel_hi:[1,0]
	v_pk_mul_f32 v[204:205], v[204:205], s[6:7] op_sel_hi:[1,0]
	v_pk_mul_f32 v[206:207], v[206:207], s[6:7] op_sel_hi:[1,0]
	v_pk_mul_f32 v[208:209], v[208:209], s[6:7] op_sel_hi:[1,0]
	v_pk_mul_f32 v[210:211], v[210:211], s[6:7] op_sel_hi:[1,0]
	v_pk_mul_f32 v[212:213], v[212:213], s[6:7] op_sel_hi:[1,0]
	v_pk_mul_f32 v[198:199], v[16:17], v[198:199]
	v_pk_mul_f32 v[200:201], v[18:19], v[200:201]
	v_pk_mul_f32 v[202:203], v[20:21], v[202:203]
	v_pk_mul_f32 v[204:205], v[22:23], v[204:205]
	v_pk_mul_f32 v[206:207], v[24:25], v[206:207]
	v_pk_mul_f32 v[208:209], v[26:27], v[208:209]
	v_pk_mul_f32 v[210:211], v[28:29], v[210:211]
	v_pk_mul_f32 v[212:213], v[30:31], v[212:213]
	v_pk_fma_f32 v[198:199], v[32:33], v[198:199], v[48:49]
	v_pk_fma_f32 v[200:201], v[34:35], v[200:201], v[50:51]
	v_pk_fma_f32 v[202:203], v[36:37], v[202:203], v[52:53]
	v_pk_fma_f32 v[204:205], v[38:39], v[204:205], v[54:55]
	v_pk_fma_f32 v[206:207], v[40:41], v[206:207], v[56:57]
	v_pk_fma_f32 v[208:209], v[42:43], v[208:209], v[58:59]
	v_pk_fma_f32 v[210:211], v[44:45], v[210:211], v[60:61]
	v_pk_fma_f32 v[212:213], v[46:47], v[212:213], v[62:63]
	v_cvt_pk_bf16_f32 v230, v198, v199
	v_cvt_pk_bf16_f32 v231, v200, v201
	v_cvt_pk_bf16_f32 v232, v202, v203
	v_cvt_pk_bf16_f32 v233, v204, v205
	v_cvt_pk_bf16_f32 v234, v206, v207
	v_cvt_pk_bf16_f32 v235, v208, v209
	v_cvt_pk_bf16_f32 v236, v210, v211
	v_cvt_pk_bf16_f32 v237, v212, v213
	global_store_dwordx4 v186, v[230:233], s[44:45] offset:-4096
	global_store_dwordx4 v186, v[234:237], s[44:45] offset:-3072
	s_waitcnt vmcnt(28)
	v_lshlrev_b32_e32 v116, 16, v156
	v_and_b32_e32 v117, 0xffff0000, v156
	v_lshlrev_b32_e32 v118, 16, v157
	v_and_b32_e32 v119, 0xffff0000, v157
	v_lshlrev_b32_e32 v120, 16, v158
	v_and_b32_e32 v121, 0xffff0000, v158
	v_lshlrev_b32_e32 v122, 16, v159
	v_and_b32_e32 v123, 0xffff0000, v159
	v_lshlrev_b32_e32 v124, 16, v160
	v_and_b32_e32 v125, 0xffff0000, v160
	v_lshlrev_b32_e32 v126, 16, v161
	v_and_b32_e32 v127, 0xffff0000, v161
	v_lshlrev_b32_e32 v128, 16, v162
	v_and_b32_e32 v129, 0xffff0000, v162
	v_lshlrev_b32_e32 v130, 16, v163
	v_and_b32_e32 v131, 0xffff0000, v163
	v_cvt_f32_f16_e32 v198, v72
	v_cvt_f32_f16_sdwa v199, v72 dst_sel:DWORD dst_unused:UNUSED_PAD src0_sel:WORD_1
	v_cvt_f32_f16_e32 v200, v73
	v_cvt_f32_f16_sdwa v201, v73 dst_sel:DWORD dst_unused:UNUSED_PAD src0_sel:WORD_1
	v_cvt_f32_f16_e32 v202, v74
	v_cvt_f32_f16_sdwa v203, v74 dst_sel:DWORD dst_unused:UNUSED_PAD src0_sel:WORD_1
	v_cvt_f32_f16_e32 v204, v75
	v_cvt_f32_f16_sdwa v205, v75 dst_sel:DWORD dst_unused:UNUSED_PAD src0_sel:WORD_1
	v_cvt_f32_f16_e32 v206, v76
	v_cvt_f32_f16_sdwa v207, v76 dst_sel:DWORD dst_unused:UNUSED_PAD src0_sel:WORD_1
	v_cvt_f32_f16_e32 v208, v77
	v_cvt_f32_f16_sdwa v209, v77 dst_sel:DWORD dst_unused:UNUSED_PAD src0_sel:WORD_1
	v_cvt_f32_f16_e32 v210, v78
	v_cvt_f32_f16_sdwa v211, v78 dst_sel:DWORD dst_unused:UNUSED_PAD src0_sel:WORD_1
	v_cvt_f32_f16_e32 v212, v79
	v_cvt_f32_f16_sdwa v213, v79 dst_sel:DWORD dst_unused:UNUSED_PAD src0_sel:WORD_1
	global_load_dwordx4 v[72:75], v187, s[42:43] offset:-2048
	global_load_dwordx4 v[76:79], v187, s[42:43] offset:-1024
	global_load_dwordx4 v[156:159], v187, s[44:45] offset:-2048
	global_load_dwordx4 v[160:163], v187, s[44:45] offset:-1024
	v_pk_mul_f32 v[140:141], v[116:117], v[116:117]
	v_pk_fma_f32 v[140:141], v[118:119], v[118:119], v[140:141]
	v_pk_fma_f32 v[140:141], v[120:121], v[120:121], v[140:141]
	v_pk_fma_f32 v[140:141], v[122:123], v[122:123], v[140:141]
	v_pk_fma_f32 v[140:141], v[124:125], v[124:125], v[140:141]
	v_pk_fma_f32 v[140:141], v[126:127], v[126:127], v[140:141]
	v_pk_fma_f32 v[140:141], v[128:129], v[128:129], v[140:141]
	v_pk_fma_f32 v[140:141], v[130:131], v[130:131], v[140:141]
	v_add_f32_e32 v140, v140, v141
	s_nop 1
	v_add_f32_dpp v140, v140, v140 quad_perm:[1,0,3,2] row_mask:0xf bank_mask:0xf
	s_nop 1
	v_add_f32_dpp v140, v140, v140 quad_perm:[2,3,0,1] row_mask:0xf bank_mask:0xf
	s_nop 1
	v_add_f32_dpp v140, v140, v140 row_ror:4 row_mask:0xf bank_mask:0xf
	s_nop 1
	v_add_f32_dpp v140, v140, v140 row_ror:8 row_mask:0xf bank_mask:0xf
	s_nop 1
	v_add_f32_dpp v140, v140, v140 row_bcast:15 row_mask:0xa bank_mask:0xf
	s_nop 1
	v_add_f32_dpp v140, v140, v140 row_bcast:31 row_mask:0xc bank_mask:0xf
	s_nop 1
	v_fmamk_f32 v140, v140, 0x3a800000, v224
	v_rsq_f32_e32 v140, v140
	s_nop 0
	v_mul_f32_e32 v140, v144, v140
	s_nop 0
	v_readlane_b32 s4, v140, 63
	s_nop 1
	v_pk_mul_f32 v[116:117], v[116:117], s[4:5] op_sel_hi:[1,0]
	v_pk_mul_f32 v[118:119], v[118:119], s[4:5] op_sel_hi:[1,0]
	v_pk_mul_f32 v[120:121], v[120:121], s[4:5] op_sel_hi:[1,0]
	v_pk_mul_f32 v[122:123], v[122:123], s[4:5] op_sel_hi:[1,0]
	v_pk_mul_f32 v[124:125], v[124:125], s[4:5] op_sel_hi:[1,0]
	v_pk_mul_f32 v[126:127], v[126:127], s[4:5] op_sel_hi:[1,0]
	v_pk_mul_f32 v[128:129], v[128:129], s[4:5] op_sel_hi:[1,0]
	v_pk_mul_f32 v[130:131], v[130:131], s[4:5] op_sel_hi:[1,0]
	v_pk_fma_f32 v[198:199], v[0:1], v[116:117], v[198:199]
	v_pk_fma_f32 v[200:201], v[2:3], v[118:119], v[200:201]
	v_pk_fma_f32 v[202:203], v[4:5], v[120:121], v[202:203]
; __device__ __forceinline__ unsigned pk2(float lo, float hi) { return pg8::cvt_pk_bf16(lo, hi); }
; template <int R, bool SRCB> ...
;     ...
;             const float rr = __builtin_amdgcn_rsqf(wave_sum(ss) * (1.0f / DM) + 1e-6f) * w;
; #pragma unroll
;             for (int j = 0; j < 2; ++j)
; #pragma unroll
;                 for (int k = 0; k < 2; ++k) h[r][j][k] = h[r][j][k] + gg[j][k] * (y[j][k] * rr);
;         }
;     }
; #pragma unroll
;     for (int r = 0; r < R; ++r)
; #pragma unroll
;         for (int j = 0; j < 2; ++j) { const int c = 8 * lane + 512 * j;
;             if (final_out) { *(f32x4*)(final_out + (size_t)(row0 + r) * DM + c) = h[r][j][0]; *(f32x4*)(final_out + (size_t)(row0 + r) * DM + c + 4) = h[r][j][1]; }
;             else { u32x4 t; t.x = pkh2(h[r][j][0][0], h[r][j][0][1]); t.y = pkh2(h[r][j][0][2], h[r][j][0][3]); t.z = pkh2(h[r][j][1][0], h[r][j][1][1]); t.w = pkh2(h[r][j][1][2], h[r][j][1][3]);
;                 *(u32x4*)(hout + (size_t)(row0 + r) * DM + c) = t; } }
;     if (U) {
;         f32x4 gp[2][2], sc1[2][2], sh[2][2];
; #pragma unroll
;         for (int j = 0; j < 2; ++j)
; #pragma unroll
;             for (int k = 0; k < 2; ++k) { const int c = 8 * lane + 512 * j + 4 * k; gp[j][k] = *(const f32x4*)(gpre + c); sc1[j][k] = *(const f32x4*)(scale + (size_t)mrow * 9216 + c) + 1.0f; sh[j][k] = *(const f32x4*)(shift + (size_t)mrow * 9216 + c); }
; #pragma unroll
;         for (int r = 0; r < R; ++r) {
;             float ss = 0.f;
; #pragma unroll
;             for (int j = 0; j < 2; ++j)
; #pragma unroll
;                 for (int k = 0; k < 2; ++k) ss += (h[r][j][k][0] * h[r][j][k][0] + h[r][j][k][1] * h[r][j][k][1]) + (h[r][j][k][2] * h[r][j][k][2] + h[r][j][k][3] * h[r][j][k][3]);
;             const float rr = __builtin_amdgcn_rsqf(wave_sum(ss) * (1.0f / DM) + 1e-6f);
; #pragma unroll
;             for (int j = 0; j < 2; ++j) { const f32x4 v0 = (h[r][j][0] * rr * gp[j][0]) * sc1[j][0] + sh[j][0], v1 = (h[r][j][1] * rr * gp[j][1]) * sc1[j][1] + sh[j][1];
;                 u32x4 t; t.x = pk2(v0[0], v0[1]); t.y = pk2(v0[2], v0[3]); t.z = pk2(v1[0], v1[1]); t.w = pk2(v1[2], v1[3]);
;                 *(u32x4*)(U + (size_t)(row0 + r) * DM + 8 * lane + 512 * j) = t; }
	v_pk_fma_f32 v[204:205], v[6:7], v[122:123], v[204:205]
	v_pk_fma_f32 v[206:207], v[8:9], v[124:125], v[206:207]
	v_pk_fma_f32 v[208:209], v[10:11], v[126:127], v[208:209]
	v_pk_fma_f32 v[210:211], v[12:13], v[128:129], v[210:211]
	v_pk_fma_f32 v[212:213], v[14:15], v[130:131], v[212:213]
	v_cvt_f16_f32_e32 v132, v198
	v_cvt_f16_f32_e32 v133, v200
	v_cvt_f16_f32_e32 v134, v202
	v_cvt_f16_f32_e32 v135, v204
	v_cvt_f16_f32_e32 v136, v206
	v_cvt_f16_f32_e32 v137, v208
	v_cvt_f16_f32_e32 v138, v210
	v_cvt_f16_f32_e32 v139, v212
	v_cvt_f16_f32_sdwa v132, v199 dst_sel:WORD_1 dst_unused:UNUSED_PRESERVE src0_sel:DWORD
	v_cvt_f16_f32_sdwa v133, v201 dst_sel:WORD_1 dst_unused:UNUSED_PRESERVE src0_sel:DWORD
	v_cvt_f16_f32_sdwa v134, v203 dst_sel:WORD_1 dst_unused:UNUSED_PRESERVE src0_sel:DWORD
	v_cvt_f16_f32_sdwa v135, v205 dst_sel:WORD_1 dst_unused:UNUSED_PRESERVE src0_sel:DWORD
	v_cvt_f16_f32_sdwa v136, v207 dst_sel:WORD_1 dst_unused:UNUSED_PRESERVE src0_sel:DWORD
	v_cvt_f16_f32_sdwa v137, v209 dst_sel:WORD_1 dst_unused:UNUSED_PRESERVE src0_sel:DWORD
	v_cvt_f16_f32_sdwa v138, v211 dst_sel:WORD_1 dst_unused:UNUSED_PRESERVE src0_sel:DWORD
	v_cvt_f16_f32_sdwa v139, v213 dst_sel:WORD_1 dst_unused:UNUSED_PRESERVE src0_sel:DWORD
	s_nop 0
	global_store_dwordx4 v186, v[132:135], s[42:43] offset:-2048
	global_store_dwordx4 v186, v[136:139], s[42:43] offset:-1024
	v_pk_mul_f32 v[140:141], v[198:199], v[198:199]
	v_pk_fma_f32 v[140:141], v[200:201], v[200:201], v[140:141]
	v_pk_fma_f32 v[140:141], v[202:203], v[202:203], v[140:141]
	v_pk_fma_f32 v[140:141], v[204:205], v[204:205], v[140:141]
	v_pk_fma_f32 v[140:141], v[206:207], v[206:207], v[140:141]
	v_pk_fma_f32 v[140:141], v[208:209], v[208:209], v[140:141]
	v_pk_fma_f32 v[140:141], v[210:211], v[210:211], v[140:141]
	v_pk_fma_f32 v[140:141], v[212:213], v[212:213], v[140:141]
	v_add_f32_e32 v140, v140, v141
	s_nop 1
	v_add_f32_dpp v140, v140, v140 quad_perm:[1,0,3,2] row_mask:0xf bank_mask:0xf
	s_nop 1
	v_add_f32_dpp v140, v140, v140 quad_perm:[2,3,0,1] row_mask:0xf bank_mask:0xf
	s_nop 1
	v_add_f32_dpp v140, v140, v140 row_ror:4 row_mask:0xf bank_mask:0xf
	s_nop 1
	v_add_f32_dpp v140, v140, v140 row_ror:8 row_mask:0xf bank_mask:0xf
	s_nop 1
	v_add_f32_dpp v140, v140, v140 row_bcast:15 row_mask:0xa bank_mask:0xf
	s_nop 1
	v_add_f32_dpp v140, v140, v140 row_bcast:31 row_mask:0xc bank_mask:0xf
	s_nop 1
	v_fmamk_f32 v140, v140, 0x3a800000, v224
	v_rsq_f32_e32 v140, v140
	s_nop 0
	v_readlane_b32 s6, v140, 63
	s_nop 1
	v_pk_mul_f32 v[198:199], v[198:199], s[6:7] op_sel_hi:[1,0]
	v_pk_mul_f32 v[200:201], v[200:201], s[6:7] op_sel_hi:[1,0]
	v_pk_mul_f32 v[202:203], v[202:203], s[6:7] op_sel_hi:[1,0]
	v_pk_mul_f32 v[204:205], v[204:205], s[6:7] op_sel_hi:[1,0]
	v_pk_mul_f32 v[206:207], v[206:207], s[6:7] op_sel_hi:[1,0]
	v_pk_mul_f32 v[208:209], v[208:209], s[6:7] op_sel_hi:[1,0]
	v_pk_mul_f32 v[210:211], v[210:211], s[6:7] op_sel_hi:[1,0]
	v_pk_mul_f32 v[212:213], v[212:213], s[6:7] op_sel_hi:[1,0]
	v_pk_mul_f32 v[198:199], v[16:17], v[198:199]
	v_pk_mul_f32 v[200:201], v[18:19], v[200:201]
	v_pk_mul_f32 v[202:203], v[20:21], v[202:203]
	v_pk_mul_f32 v[204:205], v[22:23], v[204:205]
	v_pk_mul_f32 v[206:207], v[24:25], v[206:207]
	v_pk_mul_f32 v[208:209], v[26:27], v[208:209]
	v_pk_mul_f32 v[210:211], v[28:29], v[210:211]
	v_pk_mul_f32 v[212:213], v[30:31], v[212:213]
	v_pk_fma_f32 v[198:199], v[32:33], v[198:199], v[48:49]
	v_pk_fma_f32 v[200:201], v[34:35], v[200:201], v[50:51]
	v_pk_fma_f32 v[202:203], v[36:37], v[202:203], v[52:53]
	v_pk_fma_f32 v[204:205], v[38:39], v[204:205], v[54:55]
	v_pk_fma_f32 v[206:207], v[40:41], v[206:207], v[56:57]
	v_pk_fma_f32 v[208:209], v[42:43], v[208:209], v[58:59]
	v_pk_fma_f32 v[210:211], v[44:45], v[210:211], v[60:61]
	v_pk_fma_f32 v[212:213], v[46:47], v[212:213], v[62:63]
	v_cvt_pk_bf16_f32 v230, v198, v199
	v_cvt_pk_bf16_f32 v231, v200, v201
	v_cvt_pk_bf16_f32 v232, v202, v203
	v_cvt_pk_bf16_f32 v233, v204, v205
	v_cvt_pk_bf16_f32 v234, v206, v207
	v_cvt_pk_bf16_f32 v235, v208, v209
	v_cvt_pk_bf16_f32 v236, v210, v211
	v_cvt_pk_bf16_f32 v237, v212, v213
	global_store_dwordx4 v186, v[230:233], s[44:45] offset:-2048
	global_store_dwordx4 v186, v[234:237], s[44:45] offset:-1024
	s_waitcnt vmcnt(28)
; template <int R, bool SRCB> ...
;     ...
;         for (int r = 0; r < R; ++r) {
;             f32x4 y[2][2]; float ss = 0.f;
; #pragma unroll
;             for (int j = 0; j < 2; ++j) { const u32x4 t = yr[r][j];
;                 y[j][0] = (f32x4){bf_lo(t.x), bf_hi(t.x), bf_lo(t.y), bf_hi(t.y)}; y[j][1] = (f32x4){bf_lo(t.z), bf_hi(t.z), bf_lo(t.w), bf_hi(t.w)};
;                 if (R == 1 && YP) {
; #pragma unroll
;                     for (int k = 0; k < 2; ++k) { const float* pp = YP + (size_t)(row0 - M_LAT) * DM + 8 * lane + 512 * j + 4 * k; f32x4 s = *(const f32x4*)pp;
; #pragma unroll
;                         for (int q = 1; q < pg8::NSL; ++q) s = s + *(const f32x4*)(pp + (size_t)q * 2048 * DM);
;                         y[j][k] = s; } }
; #pragma unroll
;                 for (int k = 0; k < 2; ++k) ss += (y[j][k][0] * y[j][k][0] + y[j][k][1] * y[j][k][1]) + (y[j][k][2] * y[j][k][2] + y[j][k][3] * y[j][k][3]); }
;             const float rr = __builtin_amdgcn_rsqf(wave_sum(ss) * (1.0f / DM) + 1e-6f) * w;
; #pragma unroll
;             for (int j = 0; j < 2; ++j)
; #pragma unroll
;                 for (int k = 0; k < 2; ++k) h[r][j][k] = h[r][j][k] + gg[j][k] * (y[j][k] * rr);
;         }
;     }
; #pragma unroll
;     for (int r = 0; r < R; ++r)
; #pragma unroll
;         for (int j = 0; j < 2; ++j) { const int c = 8 * lane + 512 * j;
;             if (final_out) { *(f32x4*)(final_out + (size_t)(row0 + r) * DM + c) = h[r][j][0]; *(f32x4*)(final_out + (size_t)(row0 + r) * DM + c + 4) = h[r][j][1]; }
;             else { u32x4 t; t.x = pkh2(h[r][j][0][0], h[r][j][0][1]); t.y = pkh2(h[r][j][0][2], h[r][j][0][3]); t.z = pkh2(h[r][j][1][0], h[r][j][1][1]); t.w = pkh2(h[r][j][1][2], h[r][j][1][3]);
;                 *(u32x4*)(hout + (size_t)(row0 + r) * DM + c) = t; } }
;     if (U) {
;         f32x4 gp[2][2], sc1[2][2], sh[2][2];
; #pragma unroll
;         for (int j = 0; j < 2; ++j)
; #pragma unroll
;             for (int k = 0; k < 2; ++k) { const int c = 8 * lane + 512 * j + 4 * k; gp[j][k] = *(const f32x4*)(gpre + c); sc1[j][k] = *(const f32x4*)(scale + (size_t)mrow * 9216 + c) + 1.0f; sh[j][k] = *(const f32x4*)(shift + (size_t)mrow * 9216 + c); }
; #pragma unroll
;         for (int r = 0; r < R; ++r) {
;             float ss = 0.f;
; #pragma unroll
;             for (int j = 0; j < 2; ++j)
; #pragma unroll
	v_lshlrev_b32_e32 v116, 16, v164
	v_and_b32_e32 v117, 0xffff0000, v164
	v_lshlrev_b32_e32 v118, 16, v165
	v_and_b32_e32 v119, 0xffff0000, v165
	v_lshlrev_b32_e32 v120, 16, v166
	v_and_b32_e32 v121, 0xffff0000, v166
	v_lshlrev_b32_e32 v122, 16, v167
	v_and_b32_e32 v123, 0xffff0000, v167
	v_lshlrev_b32_e32 v124, 16, v168
	v_and_b32_e32 v125, 0xffff0000, v168
	v_lshlrev_b32_e32 v126, 16, v169
	v_and_b32_e32 v127, 0xffff0000, v169
	v_lshlrev_b32_e32 v128, 16, v170
	v_and_b32_e32 v129, 0xffff0000, v170
	v_lshlrev_b32_e32 v130, 16, v171
	v_and_b32_e32 v131, 0xffff0000, v171
	v_cvt_f32_f16_e32 v198, v80
	v_cvt_f32_f16_sdwa v199, v80 dst_sel:DWORD dst_unused:UNUSED_PAD src0_sel:WORD_1
	v_cvt_f32_f16_e32 v200, v81
	v_cvt_f32_f16_sdwa v201, v81 dst_sel:DWORD dst_unused:UNUSED_PAD src0_sel:WORD_1
	v_cvt_f32_f16_e32 v202, v82
	v_cvt_f32_f16_sdwa v203, v82 dst_sel:DWORD dst_unused:UNUSED_PAD src0_sel:WORD_1
	v_cvt_f32_f16_e32 v204, v83
	v_cvt_f32_f16_sdwa v205, v83 dst_sel:DWORD dst_unused:UNUSED_PAD src0_sel:WORD_1
	v_cvt_f32_f16_e32 v206, v84
	v_cvt_f32_f16_sdwa v207, v84 dst_sel:DWORD dst_unused:UNUSED_PAD src0_sel:WORD_1
	v_cvt_f32_f16_e32 v208, v85
	v_cvt_f32_f16_sdwa v209, v85 dst_sel:DWORD dst_unused:UNUSED_PAD src0_sel:WORD_1
	v_cvt_f32_f16_e32 v210, v86
	v_cvt_f32_f16_sdwa v211, v86 dst_sel:DWORD dst_unused:UNUSED_PAD src0_sel:WORD_1
	v_cvt_f32_f16_e32 v212, v87
	v_cvt_f32_f16_sdwa v213, v87 dst_sel:DWORD dst_unused:UNUSED_PAD src0_sel:WORD_1
	global_load_dwordx4 v[80:83], v187, s[42:43] offset:0
	global_load_dwordx4 v[84:87], v187, s[42:43] offset:1024
	global_load_dwordx4 v[164:167], v187, s[44:45] offset:0
	global_load_dwordx4 v[168:171], v187, s[44:45] offset:1024
	v_pk_mul_f32 v[140:141], v[116:117], v[116:117]
	v_pk_fma_f32 v[140:141], v[118:119], v[118:119], v[140:141]
	v_pk_fma_f32 v[140:141], v[120:121], v[120:121], v[140:141]
	v_pk_fma_f32 v[140:141], v[122:123], v[122:123], v[140:141]
	v_pk_fma_f32 v[140:141], v[124:125], v[124:125], v[140:141]
	v_pk_fma_f32 v[140:141], v[126:127], v[126:127], v[140:141]
	v_pk_fma_f32 v[140:141], v[128:129], v[128:129], v[140:141]
	v_pk_fma_f32 v[140:141], v[130:131], v[130:131], v[140:141]
	v_add_f32_e32 v140, v140, v141
	s_nop 1
	v_add_f32_dpp v140, v140, v140 quad_perm:[1,0,3,2] row_mask:0xf bank_mask:0xf
	s_nop 1
	v_add_f32_dpp v140, v140, v140 quad_perm:[2,3,0,1] row_mask:0xf bank_mask:0xf
	s_nop 1
	v_add_f32_dpp v140, v140, v140 row_ror:4 row_mask:0xf bank_mask:0xf
	s_nop 1
	v_add_f32_dpp v140, v140, v140 row_ror:8 row_mask:0xf bank_mask:0xf
	s_nop 1
	v_add_f32_dpp v140, v140, v140 row_bcast:15 row_mask:0xa bank_mask:0xf
	s_nop 1
	v_add_f32_dpp v140, v140, v140 row_bcast:31 row_mask:0xc bank_mask:0xf
	s_nop 1
	v_fmamk_f32 v140, v140, 0x3a800000, v224
	v_rsq_f32_e32 v140, v140
	s_nop 0
	v_mul_f32_e32 v140, v144, v140
	s_nop 0
	v_readlane_b32 s4, v140, 63
	s_nop 1
	v_pk_mul_f32 v[116:117], v[116:117], s[4:5] op_sel_hi:[1,0]
	v_pk_mul_f32 v[118:119], v[118:119], s[4:5] op_sel_hi:[1,0]
	v_pk_mul_f32 v[120:121], v[120:121], s[4:5] op_sel_hi:[1,0]
	v_pk_mul_f32 v[122:123], v[122:123], s[4:5] op_sel_hi:[1,0]
	v_pk_mul_f32 v[124:125], v[124:125], s[4:5] op_sel_hi:[1,0]
	v_pk_mul_f32 v[126:127], v[126:127], s[4:5] op_sel_hi:[1,0]
	v_pk_mul_f32 v[128:129], v[128:129], s[4:5] op_sel_hi:[1,0]
	v_pk_mul_f32 v[130:131], v[130:131], s[4:5] op_sel_hi:[1,0]
	v_pk_fma_f32 v[198:199], v[0:1], v[116:117], v[198:199]
	v_pk_fma_f32 v[200:201], v[2:3], v[118:119], v[200:201]
	v_pk_fma_f32 v[202:203], v[4:5], v[120:121], v[202:203]
	v_pk_fma_f32 v[204:205], v[6:7], v[122:123], v[204:205]
	v_pk_fma_f32 v[206:207], v[8:9], v[124:125], v[206:207]
	v_pk_fma_f32 v[208:209], v[10:11], v[126:127], v[208:209]
	v_pk_fma_f32 v[210:211], v[12:13], v[128:129], v[210:211]
	v_pk_fma_f32 v[212:213], v[14:15], v[130:131], v[212:213]
	v_cvt_f16_f32_e32 v132, v198
	v_cvt_f16_f32_e32 v133, v200
	v_cvt_f16_f32_e32 v134, v202
	v_cvt_f16_f32_e32 v135, v204
	v_cvt_f16_f32_e32 v136, v206
	v_cvt_f16_f32_e32 v137, v208
	v_cvt_f16_f32_e32 v138, v210
	v_cvt_f16_f32_e32 v139, v212
	v_cvt_f16_f32_sdwa v132, v199 dst_sel:WORD_1 dst_unused:UNUSED_PRESERVE src0_sel:DWORD
	v_cvt_f16_f32_sdwa v133, v201 dst_sel:WORD_1 dst_unused:UNUSED_PRESERVE src0_sel:DWORD
	v_cvt_f16_f32_sdwa v134, v203 dst_sel:WORD_1 dst_unused:UNUSED_PRESERVE src0_sel:DWORD
	v_cvt_f16_f32_sdwa v135, v205 dst_sel:WORD_1 dst_unused:UNUSED_PRESERVE src0_sel:DWORD
	v_cvt_f16_f32_sdwa v136, v207 dst_sel:WORD_1 dst_unused:UNUSED_PRESERVE src0_sel:DWORD
	v_cvt_f16_f32_sdwa v137, v209 dst_sel:WORD_1 dst_unused:UNUSED_PRESERVE src0_sel:DWORD
	v_cvt_f16_f32_sdwa v138, v211 dst_sel:WORD_1 dst_unused:UNUSED_PRESERVE src0_sel:DWORD
	v_cvt_f16_f32_sdwa v139, v213 dst_sel:WORD_1 dst_unused:UNUSED_PRESERVE src0_sel:DWORD
	s_nop 0
	global_store_dwordx4 v186, v[132:135], s[42:43] offset:0
	global_store_dwordx4 v186, v[136:139], s[42:43] offset:1024
	v_pk_mul_f32 v[140:141], v[198:199], v[198:199]
	v_pk_fma_f32 v[140:141], v[200:201], v[200:201], v[140:141]
	v_pk_fma_f32 v[140:141], v[202:203], v[202:203], v[140:141]
	v_pk_fma_f32 v[140:141], v[204:205], v[204:205], v[140:141]
	v_pk_fma_f32 v[140:141], v[206:207], v[206:207], v[140:141]
	v_pk_fma_f32 v[140:141], v[208:209], v[208:209], v[140:141]
	v_pk_fma_f32 v[140:141], v[210:211], v[210:211], v[140:141]
	v_pk_fma_f32 v[140:141], v[212:213], v[212:213], v[140:141]
	v_add_f32_e32 v140, v140, v141
	s_nop 1
	v_add_f32_dpp v140, v140, v140 quad_perm:[1,0,3,2] row_mask:0xf bank_mask:0xf
	s_nop 1
	v_add_f32_dpp v140, v140, v140 quad_perm:[2,3,0,1] row_mask:0xf bank_mask:0xf
	s_nop 1
	v_add_f32_dpp v140, v140, v140 row_ror:4 row_mask:0xf bank_mask:0xf
; template <int R, bool SRCB> ...
;     ...
;         for (int r = 0; r < R; ++r) {
;             f32x4 y[2][2]; float ss = 0.f;
; #pragma unroll
;             for (int j = 0; j < 2; ++j) { const u32x4 t = yr[r][j];
;                 y[j][0] = (f32x4){bf_lo(t.x), bf_hi(t.x), bf_lo(t.y), bf_hi(t.y)}; y[j][1] = (f32x4){bf_lo(t.z), bf_hi(t.z), bf_lo(t.w), bf_hi(t.w)};
;                 if (R == 1 && YP) {
; #pragma unroll
;                     for (int k = 0; k < 2; ++k) { const float* pp = YP + (size_t)(row0 - M_LAT) * DM + 8 * lane + 512 * j + 4 * k; f32x4 s = *(const f32x4*)pp;
; #pragma unroll
;                         for (int q = 1; q < pg8::NSL; ++q) s = s + *(const f32x4*)(pp + (size_t)q * 2048 * DM);
;                         y[j][k] = s; } }
; #pragma unroll
;                 for (int k = 0; k < 2; ++k) ss += (y[j][k][0] * y[j][k][0] + y[j][k][1] * y[j][k][1]) + (y[j][k][2] * y[j][k][2] + y[j][k][3] * y[j][k][3]); }
;             const float rr = __builtin_amdgcn_rsqf(wave_sum(ss) * (1.0f / DM) + 1e-6f) * w;
; #pragma unroll
;             for (int j = 0; j < 2; ++j)
; #pragma unroll
;                 for (int k = 0; k < 2; ++k) h[r][j][k] = h[r][j][k] + gg[j][k] * (y[j][k] * rr);
;         }
;     }
; #pragma unroll
;     for (int r = 0; r < R; ++r)
; #pragma unroll
;         for (int j = 0; j < 2; ++j) { const int c = 8 * lane + 512 * j;
;             if (final_out) { *(f32x4*)(final_out + (size_t)(row0 + r) * DM + c) = h[r][j][0]; *(f32x4*)(final_out + (size_t)(row0 + r) * DM + c + 4) = h[r][j][1]; }
;             else { u32x4 t; t.x = pkh2(h[r][j][0][0], h[r][j][0][1]); t.y = pkh2(h[r][j][0][2], h[r][j][0][3]); t.z = pkh2(h[r][j][1][0], h[r][j][1][1]); t.w = pkh2(h[r][j][1][2], h[r][j][1][3]);
;                 *(u32x4*)(hout + (size_t)(row0 + r) * DM + c) = t; } }
;     if (U) {
;         f32x4 gp[2][2], sc1[2][2], sh[2][2];
; #pragma unroll
;         for (int j = 0; j < 2; ++j)
; #pragma unroll
;             for (int k = 0; k < 2; ++k) { const int c = 8 * lane + 512 * j + 4 * k; gp[j][k] = *(const f32x4*)(gpre + c); sc1[j][k] = *(const f32x4*)(scale + (size_t)mrow * 9216 + c) + 1.0f; sh[j][k] = *(const f32x4*)(shift + (size_t)mrow * 9216 + c); }
; #pragma unroll
;         for (int r = 0; r < R; ++r) {
;             float ss = 0.f;
; #pragma unroll
;             for (int j = 0; j < 2; ++j)
; #pragma unroll
	s_nop 1
	v_add_f32_dpp v140, v140, v140 row_ror:8 row_mask:0xf bank_mask:0xf
	s_nop 1
	v_add_f32_dpp v140, v140, v140 row_bcast:15 row_mask:0xa bank_mask:0xf
	s_nop 1
	v_add_f32_dpp v140, v140, v140 row_bcast:31 row_mask:0xc bank_mask:0xf
	s_nop 1
	v_fmamk_f32 v140, v140, 0x3a800000, v224
	v_rsq_f32_e32 v140, v140
	s_nop 0
	v_readlane_b32 s6, v140, 63
	s_nop 1
	v_pk_mul_f32 v[198:199], v[198:199], s[6:7] op_sel_hi:[1,0]
	v_pk_mul_f32 v[200:201], v[200:201], s[6:7] op_sel_hi:[1,0]
	v_pk_mul_f32 v[202:203], v[202:203], s[6:7] op_sel_hi:[1,0]
	v_pk_mul_f32 v[204:205], v[204:205], s[6:7] op_sel_hi:[1,0]
	v_pk_mul_f32 v[206:207], v[206:207], s[6:7] op_sel_hi:[1,0]
	v_pk_mul_f32 v[208:209], v[208:209], s[6:7] op_sel_hi:[1,0]
	v_pk_mul_f32 v[210:211], v[210:211], s[6:7] op_sel_hi:[1,0]
	v_pk_mul_f32 v[212:213], v[212:213], s[6:7] op_sel_hi:[1,0]
	v_pk_mul_f32 v[198:199], v[16:17], v[198:199]
	v_pk_mul_f32 v[200:201], v[18:19], v[200:201]
	v_pk_mul_f32 v[202:203], v[20:21], v[202:203]
	v_pk_mul_f32 v[204:205], v[22:23], v[204:205]
	v_pk_mul_f32 v[206:207], v[24:25], v[206:207]
	v_pk_mul_f32 v[208:209], v[26:27], v[208:209]
	v_pk_mul_f32 v[210:211], v[28:29], v[210:211]
	v_pk_mul_f32 v[212:213], v[30:31], v[212:213]
	v_pk_fma_f32 v[198:199], v[32:33], v[198:199], v[48:49]
	v_pk_fma_f32 v[200:201], v[34:35], v[200:201], v[50:51]
	v_pk_fma_f32 v[202:203], v[36:37], v[202:203], v[52:53]
	v_pk_fma_f32 v[204:205], v[38:39], v[204:205], v[54:55]
	v_pk_fma_f32 v[206:207], v[40:41], v[206:207], v[56:57]
	v_pk_fma_f32 v[208:209], v[42:43], v[208:209], v[58:59]
	v_pk_fma_f32 v[210:211], v[44:45], v[210:211], v[60:61]
	v_pk_fma_f32 v[212:213], v[46:47], v[212:213], v[62:63]
	v_cvt_pk_bf16_f32 v230, v198, v199
	v_cvt_pk_bf16_f32 v231, v200, v201
	v_cvt_pk_bf16_f32 v232, v202, v203
	v_cvt_pk_bf16_f32 v233, v204, v205
	v_cvt_pk_bf16_f32 v234, v206, v207
	v_cvt_pk_bf16_f32 v235, v208, v209
	v_cvt_pk_bf16_f32 v236, v210, v211
	v_cvt_pk_bf16_f32 v237, v212, v213
	global_store_dwordx4 v186, v[230:233], s[44:45] offset:0
	global_store_dwordx4 v186, v[234:237], s[44:45] offset:1024
	s_waitcnt vmcnt(28)
	v_lshlrev_b32_e32 v116, 16, v172
	v_and_b32_e32 v117, 0xffff0000, v172
	v_lshlrev_b32_e32 v118, 16, v173
	v_and_b32_e32 v119, 0xffff0000, v173
	v_lshlrev_b32_e32 v120, 16, v174
	v_and_b32_e32 v121, 0xffff0000, v174
	v_lshlrev_b32_e32 v122, 16, v175
	v_and_b32_e32 v123, 0xffff0000, v175
	v_lshlrev_b32_e32 v124, 16, v176
	v_and_b32_e32 v125, 0xffff0000, v176
	v_lshlrev_b32_e32 v126, 16, v177
	v_and_b32_e32 v127, 0xffff0000, v177
	v_lshlrev_b32_e32 v128, 16, v178
	v_and_b32_e32 v129, 0xffff0000, v178
	v_lshlrev_b32_e32 v130, 16, v179
	v_and_b32_e32 v131, 0xffff0000, v179
	v_cvt_f32_f16_e32 v198, v88
	v_cvt_f32_f16_sdwa v199, v88 dst_sel:DWORD dst_unused:UNUSED_PAD src0_sel:WORD_1
	v_cvt_f32_f16_e32 v200, v89
	v_cvt_f32_f16_sdwa v201, v89 dst_sel:DWORD dst_unused:UNUSED_PAD src0_sel:WORD_1
	v_cvt_f32_f16_e32 v202, v90
	v_cvt_f32_f16_sdwa v203, v90 dst_sel:DWORD dst_unused:UNUSED_PAD src0_sel:WORD_1
	v_cvt_f32_f16_e32 v204, v91
	v_cvt_f32_f16_sdwa v205, v91 dst_sel:DWORD dst_unused:UNUSED_PAD src0_sel:WORD_1
	v_cvt_f32_f16_e32 v206, v92
	v_cvt_f32_f16_sdwa v207, v92 dst_sel:DWORD dst_unused:UNUSED_PAD src0_sel:WORD_1
	v_cvt_f32_f16_e32 v208, v93
	v_cvt_f32_f16_sdwa v209, v93 dst_sel:DWORD dst_unused:UNUSED_PAD src0_sel:WORD_1
	v_cvt_f32_f16_e32 v210, v94
	v_cvt_f32_f16_sdwa v211, v94 dst_sel:DWORD dst_unused:UNUSED_PAD src0_sel:WORD_1
	v_cvt_f32_f16_e32 v212, v95
	v_cvt_f32_f16_sdwa v213, v95 dst_sel:DWORD dst_unused:UNUSED_PAD src0_sel:WORD_1
	global_load_dwordx4 v[88:91], v187, s[42:43] offset:2048
	global_load_dwordx4 v[92:95], v187, s[42:43] offset:3072
	global_load_dwordx4 v[172:175], v187, s[44:45] offset:2048
	global_load_dwordx4 v[176:179], v187, s[44:45] offset:3072
	v_pk_mul_f32 v[140:141], v[116:117], v[116:117]
	v_pk_fma_f32 v[140:141], v[118:119], v[118:119], v[140:141]
	v_pk_fma_f32 v[140:141], v[120:121], v[120:121], v[140:141]
	v_pk_fma_f32 v[140:141], v[122:123], v[122:123], v[140:141]
	v_pk_fma_f32 v[140:141], v[124:125], v[124:125], v[140:141]
	v_pk_fma_f32 v[140:141], v[126:127], v[126:127], v[140:141]
	v_pk_fma_f32 v[140:141], v[128:129], v[128:129], v[140:141]
	v_pk_fma_f32 v[140:141], v[130:131], v[130:131], v[140:141]
	v_add_f32_e32 v140, v140, v141
	s_nop 1
	v_add_f32_dpp v140, v140, v140 quad_perm:[1,0,3,2] row_mask:0xf bank_mask:0xf
	s_nop 1
	v_add_f32_dpp v140, v140, v140 quad_perm:[2,3,0,1] row_mask:0xf bank_mask:0xf
	s_nop 1
	v_add_f32_dpp v140, v140, v140 row_ror:4 row_mask:0xf bank_mask:0xf
	s_nop 1
	v_add_f32_dpp v140, v140, v140 row_ror:8 row_mask:0xf bank_mask:0xf
	s_nop 1
	v_add_f32_dpp v140, v140, v140 row_bcast:15 row_mask:0xa bank_mask:0xf
	s_nop 1
	v_add_f32_dpp v140, v140, v140 row_bcast:31 row_mask:0xc bank_mask:0xf
	s_nop 1
	v_fmamk_f32 v140, v140, 0x3a800000, v224
	v_rsq_f32_e32 v140, v140
	s_nop 0
	v_mul_f32_e32 v140, v144, v140
	s_nop 0
	v_readlane_b32 s4, v140, 63
	s_nop 1
	v_pk_mul_f32 v[116:117], v[116:117], s[4:5] op_sel_hi:[1,0]
	v_pk_mul_f32 v[118:119], v[118:119], s[4:5] op_sel_hi:[1,0]
	v_pk_mul_f32 v[120:121], v[120:121], s[4:5] op_sel_hi:[1,0]
	v_pk_mul_f32 v[122:123], v[122:123], s[4:5] op_sel_hi:[1,0]
	v_pk_mul_f32 v[124:125], v[124:125], s[4:5] op_sel_hi:[1,0]
	v_pk_mul_f32 v[126:127], v[126:127], s[4:5] op_sel_hi:[1,0]
	v_pk_mul_f32 v[128:129], v[128:129], s[4:5] op_sel_hi:[1,0]
	v_pk_mul_f32 v[130:131], v[130:131], s[4:5] op_sel_hi:[1,0]
	v_pk_fma_f32 v[198:199], v[0:1], v[116:117], v[198:199]
	v_pk_fma_f32 v[200:201], v[2:3], v[118:119], v[200:201]
	v_pk_fma_f32 v[202:203], v[4:5], v[120:121], v[202:203]
; __device__ __forceinline__ unsigned pk2(float lo, float hi) { return pg8::cvt_pk_bf16(lo, hi); }
; template <int R, bool SRCB> ...
;     ...
;             const float rr = __builtin_amdgcn_rsqf(wave_sum(ss) * (1.0f / DM) + 1e-6f) * w;
; #pragma unroll
;             for (int j = 0; j < 2; ++j)
; #pragma unroll
;                 for (int k = 0; k < 2; ++k) h[r][j][k] = h[r][j][k] + gg[j][k] * (y[j][k] * rr);
;         }
;     }
; #pragma unroll
;     for (int r = 0; r < R; ++r)
; #pragma unroll
;         for (int j = 0; j < 2; ++j) { const int c = 8 * lane + 512 * j;
;             if (final_out) { *(f32x4*)(final_out + (size_t)(row0 + r) * DM + c) = h[r][j][0]; *(f32x4*)(final_out + (size_t)(row0 + r) * DM + c + 4) = h[r][j][1]; }
;             else { u32x4 t; t.x = pkh2(h[r][j][0][0], h[r][j][0][1]); t.y = pkh2(h[r][j][0][2], h[r][j][0][3]); t.z = pkh2(h[r][j][1][0], h[r][j][1][1]); t.w = pkh2(h[r][j][1][2], h[r][j][1][3]);
;                 *(u32x4*)(hout + (size_t)(row0 + r) * DM + c) = t; } }
;     if (U) {
;         f32x4 gp[2][2], sc1[2][2], sh[2][2];
; #pragma unroll
;         for (int j = 0; j < 2; ++j)
; #pragma unroll
;             for (int k = 0; k < 2; ++k) { const int c = 8 * lane + 512 * j + 4 * k; gp[j][k] = *(const f32x4*)(gpre + c); sc1[j][k] = *(const f32x4*)(scale + (size_t)mrow * 9216 + c) + 1.0f; sh[j][k] = *(const f32x4*)(shift + (size_t)mrow * 9216 + c); }
; #pragma unroll
;         for (int r = 0; r < R; ++r) {
;             float ss = 0.f;
; #pragma unroll
;             for (int j = 0; j < 2; ++j)
; #pragma unroll
;                 for (int k = 0; k < 2; ++k) ss += (h[r][j][k][0] * h[r][j][k][0] + h[r][j][k][1] * h[r][j][k][1]) + (h[r][j][k][2] * h[r][j][k][2] + h[r][j][k][3] * h[r][j][k][3]);
;             const float rr = __builtin_amdgcn_rsqf(wave_sum(ss) * (1.0f / DM) + 1e-6f);
; #pragma unroll
;             for (int j = 0; j < 2; ++j) { const f32x4 v0 = (h[r][j][0] * rr * gp[j][0]) * sc1[j][0] + sh[j][0], v1 = (h[r][j][1] * rr * gp[j][1]) * sc1[j][1] + sh[j][1];
;                 u32x4 t; t.x = pk2(v0[0], v0[1]); t.y = pk2(v0[2], v0[3]); t.z = pk2(v1[0], v1[1]); t.w = pk2(v1[2], v1[3]);
;                 *(u32x4*)(U + (size_t)(row0 + r) * DM + 8 * lane + 512 * j) = t; }
	v_pk_fma_f32 v[204:205], v[6:7], v[122:123], v[204:205]
	v_pk_fma_f32 v[206:207], v[8:9], v[124:125], v[206:207]
	v_pk_fma_f32 v[208:209], v[10:11], v[126:127], v[208:209]
	v_pk_fma_f32 v[210:211], v[12:13], v[128:129], v[210:211]
	v_pk_fma_f32 v[212:213], v[14:15], v[130:131], v[212:213]
	v_cvt_f16_f32_e32 v132, v198
	v_cvt_f16_f32_e32 v133, v200
	v_cvt_f16_f32_e32 v134, v202
	v_cvt_f16_f32_e32 v135, v204
	v_cvt_f16_f32_e32 v136, v206
	v_cvt_f16_f32_e32 v137, v208
	v_cvt_f16_f32_e32 v138, v210
	v_cvt_f16_f32_e32 v139, v212
	v_cvt_f16_f32_sdwa v132, v199 dst_sel:WORD_1 dst_unused:UNUSED_PRESERVE src0_sel:DWORD
	v_cvt_f16_f32_sdwa v133, v201 dst_sel:WORD_1 dst_unused:UNUSED_PRESERVE src0_sel:DWORD
	v_cvt_f16_f32_sdwa v134, v203 dst_sel:WORD_1 dst_unused:UNUSED_PRESERVE src0_sel:DWORD
	v_cvt_f16_f32_sdwa v135, v205 dst_sel:WORD_1 dst_unused:UNUSED_PRESERVE src0_sel:DWORD
	v_cvt_f16_f32_sdwa v136, v207 dst_sel:WORD_1 dst_unused:UNUSED_PRESERVE src0_sel:DWORD
	v_cvt_f16_f32_sdwa v137, v209 dst_sel:WORD_1 dst_unused:UNUSED_PRESERVE src0_sel:DWORD
	v_cvt_f16_f32_sdwa v138, v211 dst_sel:WORD_1 dst_unused:UNUSED_PRESERVE src0_sel:DWORD
	v_cvt_f16_f32_sdwa v139, v213 dst_sel:WORD_1 dst_unused:UNUSED_PRESERVE src0_sel:DWORD
	s_nop 0
	global_store_dwordx4 v186, v[132:135], s[42:43] offset:2048
	global_store_dwordx4 v186, v[136:139], s[42:43] offset:3072
	v_pk_mul_f32 v[140:141], v[198:199], v[198:199]
	v_pk_fma_f32 v[140:141], v[200:201], v[200:201], v[140:141]
	v_pk_fma_f32 v[140:141], v[202:203], v[202:203], v[140:141]
	v_pk_fma_f32 v[140:141], v[204:205], v[204:205], v[140:141]
	v_pk_fma_f32 v[140:141], v[206:207], v[206:207], v[140:141]
	v_pk_fma_f32 v[140:141], v[208:209], v[208:209], v[140:141]
	v_pk_fma_f32 v[140:141], v[210:211], v[210:211], v[140:141]
	v_pk_fma_f32 v[140:141], v[212:213], v[212:213], v[140:141]
	v_add_f32_e32 v140, v140, v141
	s_nop 1
	v_add_f32_dpp v140, v140, v140 quad_perm:[1,0,3,2] row_mask:0xf bank_mask:0xf
	s_nop 1
	v_add_f32_dpp v140, v140, v140 quad_perm:[2,3,0,1] row_mask:0xf bank_mask:0xf
	s_nop 1
	v_add_f32_dpp v140, v140, v140 row_ror:4 row_mask:0xf bank_mask:0xf
	s_nop 1
	v_add_f32_dpp v140, v140, v140 row_ror:8 row_mask:0xf bank_mask:0xf
	s_nop 1
	v_add_f32_dpp v140, v140, v140 row_bcast:15 row_mask:0xa bank_mask:0xf
	s_nop 1
	v_add_f32_dpp v140, v140, v140 row_bcast:31 row_mask:0xc bank_mask:0xf
	s_nop 1
	v_fmamk_f32 v140, v140, 0x3a800000, v224
	v_rsq_f32_e32 v140, v140
	s_nop 0
	v_readlane_b32 s6, v140, 63
	s_nop 1
	v_pk_mul_f32 v[198:199], v[198:199], s[6:7] op_sel_hi:[1,0]
	v_pk_mul_f32 v[200:201], v[200:201], s[6:7] op_sel_hi:[1,0]
	v_pk_mul_f32 v[202:203], v[202:203], s[6:7] op_sel_hi:[1,0]
	v_pk_mul_f32 v[204:205], v[204:205], s[6:7] op_sel_hi:[1,0]
	v_pk_mul_f32 v[206:207], v[206:207], s[6:7] op_sel_hi:[1,0]
	v_pk_mul_f32 v[208:209], v[208:209], s[6:7] op_sel_hi:[1,0]
	v_pk_mul_f32 v[210:211], v[210:211], s[6:7] op_sel_hi:[1,0]
	v_pk_mul_f32 v[212:213], v[212:213], s[6:7] op_sel_hi:[1,0]
	v_pk_mul_f32 v[198:199], v[16:17], v[198:199]
	v_pk_mul_f32 v[200:201], v[18:19], v[200:201]
	v_pk_mul_f32 v[202:203], v[20:21], v[202:203]
	v_pk_mul_f32 v[204:205], v[22:23], v[204:205]
	v_pk_mul_f32 v[206:207], v[24:25], v[206:207]
	v_pk_mul_f32 v[208:209], v[26:27], v[208:209]
	v_pk_mul_f32 v[210:211], v[28:29], v[210:211]
	v_pk_mul_f32 v[212:213], v[30:31], v[212:213]
	v_pk_fma_f32 v[198:199], v[32:33], v[198:199], v[48:49]
	v_pk_fma_f32 v[200:201], v[34:35], v[200:201], v[50:51]
	v_pk_fma_f32 v[202:203], v[36:37], v[202:203], v[52:53]
	v_pk_fma_f32 v[204:205], v[38:39], v[204:205], v[54:55]
	v_pk_fma_f32 v[206:207], v[40:41], v[206:207], v[56:57]
	v_pk_fma_f32 v[208:209], v[42:43], v[208:209], v[58:59]
	v_pk_fma_f32 v[210:211], v[44:45], v[210:211], v[60:61]
	v_pk_fma_f32 v[212:213], v[46:47], v[212:213], v[62:63]
	v_cvt_pk_bf16_f32 v230, v198, v199
	v_cvt_pk_bf16_f32 v231, v200, v201
	v_cvt_pk_bf16_f32 v232, v202, v203
	v_cvt_pk_bf16_f32 v233, v204, v205
	v_cvt_pk_bf16_f32 v234, v206, v207
	v_cvt_pk_bf16_f32 v235, v208, v209
	v_cvt_pk_bf16_f32 v236, v210, v211
	v_cvt_pk_bf16_f32 v237, v212, v213
	global_store_dwordx4 v186, v[230:233], s[44:45] offset:2048
	global_store_dwordx4 v186, v[234:237], s[44:45] offset:3072
	s_waitcnt vmcnt(28)
; template <int R, bool SRCB> ...
;     ...
;         for (int r = 0; r < R; ++r) {
;             f32x4 y[2][2]; float ss = 0.f;
; #pragma unroll
;             for (int j = 0; j < 2; ++j) { const u32x4 t = yr[r][j];
;                 y[j][0] = (f32x4){bf_lo(t.x), bf_hi(t.x), bf_lo(t.y), bf_hi(t.y)}; y[j][1] = (f32x4){bf_lo(t.z), bf_hi(t.z), bf_lo(t.w), bf_hi(t.w)};
;                 if (R == 1 && YP) {
; #pragma unroll
;                     for (int k = 0; k < 2; ++k) { const float* pp = YP + (size_t)(row0 - M_LAT) * DM + 8 * lane + 512 * j + 4 * k; f32x4 s = *(const f32x4*)pp;
; #pragma unroll
;                         for (int q = 1; q < pg8::NSL; ++q) s = s + *(const f32x4*)(pp + (size_t)q * 2048 * DM);
;                         y[j][k] = s; } }
; #pragma unroll
;                 for (int k = 0; k < 2; ++k) ss += (y[j][k][0] * y[j][k][0] + y[j][k][1] * y[j][k][1]) + (y[j][k][2] * y[j][k][2] + y[j][k][3] * y[j][k][3]); }
;             const float rr = __builtin_amdgcn_rsqf(wave_sum(ss) * (1.0f / DM) + 1e-6f) * w;
; #pragma unroll
;             for (int j = 0; j < 2; ++j)
; #pragma unroll
;                 for (int k = 0; k < 2; ++k) h[r][j][k] = h[r][j][k] + gg[j][k] * (y[j][k] * rr);
;         }
;     }
; #pragma unroll
;     for (int r = 0; r < R; ++r)
; #pragma unroll
;         for (int j = 0; j < 2; ++j) { const int c = 8 * lane + 512 * j;
;             if (final_out) { *(f32x4*)(final_out + (size_t)(row0 + r) * DM + c) = h[r][j][0]; *(f32x4*)(final_out + (size_t)(row0 + r) * DM + c + 4) = h[r][j][1]; }
;             else { u32x4 t; t.x = pkh2(h[r][j][0][0], h[r][j][0][1]); t.y = pkh2(h[r][j][0][2], h[r][j][0][3]); t.z = pkh2(h[r][j][1][0], h[r][j][1][1]); t.w = pkh2(h[r][j][1][2], h[r][j][1][3]);
;                 *(u32x4*)(hout + (size_t)(row0 + r) * DM + c) = t; } }
;     if (U) {
;         f32x4 gp[2][2], sc1[2][2], sh[2][2];
; #pragma unroll
;         for (int j = 0; j < 2; ++j)
; #pragma unroll
;             for (int k = 0; k < 2; ++k) { const int c = 8 * lane + 512 * j + 4 * k; gp[j][k] = *(const f32x4*)(gpre + c); sc1[j][k] = *(const f32x4*)(scale + (size_t)mrow * 9216 + c) + 1.0f; sh[j][k] = *(const f32x4*)(shift + (size_t)mrow * 9216 + c); }
; #pragma unroll
;         for (int r = 0; r < R; ++r) {
;             float ss = 0.f;
; #pragma unroll
;             for (int j = 0; j < 2; ++j)
; #pragma unroll
	v_lshlrev_b32_e32 v116, 16, v148
	v_and_b32_e32 v117, 0xffff0000, v148
	v_lshlrev_b32_e32 v118, 16, v149
	v_and_b32_e32 v119, 0xffff0000, v149
	v_lshlrev_b32_e32 v120, 16, v150
	v_and_b32_e32 v121, 0xffff0000, v150
	v_lshlrev_b32_e32 v122, 16, v151
	v_and_b32_e32 v123, 0xffff0000, v151
	v_lshlrev_b32_e32 v124, 16, v152
	v_and_b32_e32 v125, 0xffff0000, v152
	v_lshlrev_b32_e32 v126, 16, v153
	v_and_b32_e32 v127, 0xffff0000, v153
	v_lshlrev_b32_e32 v128, 16, v154
	v_and_b32_e32 v129, 0xffff0000, v154
	v_lshlrev_b32_e32 v130, 16, v155
	v_and_b32_e32 v131, 0xffff0000, v155
	v_cvt_f32_f16_e32 v198, v64
	v_cvt_f32_f16_sdwa v199, v64 dst_sel:DWORD dst_unused:UNUSED_PAD src0_sel:WORD_1
	v_cvt_f32_f16_e32 v200, v65
	v_cvt_f32_f16_sdwa v201, v65 dst_sel:DWORD dst_unused:UNUSED_PAD src0_sel:WORD_1
	v_cvt_f32_f16_e32 v202, v66
	v_cvt_f32_f16_sdwa v203, v66 dst_sel:DWORD dst_unused:UNUSED_PAD src0_sel:WORD_1
	v_cvt_f32_f16_e32 v204, v67
	v_cvt_f32_f16_sdwa v205, v67 dst_sel:DWORD dst_unused:UNUSED_PAD src0_sel:WORD_1
	v_cvt_f32_f16_e32 v206, v68
	v_cvt_f32_f16_sdwa v207, v68 dst_sel:DWORD dst_unused:UNUSED_PAD src0_sel:WORD_1
	v_cvt_f32_f16_e32 v208, v69
	v_cvt_f32_f16_sdwa v209, v69 dst_sel:DWORD dst_unused:UNUSED_PAD src0_sel:WORD_1
	v_cvt_f32_f16_e32 v210, v70
	v_cvt_f32_f16_sdwa v211, v70 dst_sel:DWORD dst_unused:UNUSED_PAD src0_sel:WORD_1
	v_cvt_f32_f16_e32 v212, v71
	v_cvt_f32_f16_sdwa v213, v71 dst_sel:DWORD dst_unused:UNUSED_PAD src0_sel:WORD_1
	v_pk_mul_f32 v[140:141], v[116:117], v[116:117]
	v_pk_fma_f32 v[140:141], v[118:119], v[118:119], v[140:141]
	v_pk_fma_f32 v[140:141], v[120:121], v[120:121], v[140:141]
	v_pk_fma_f32 v[140:141], v[122:123], v[122:123], v[140:141]
	v_pk_fma_f32 v[140:141], v[124:125], v[124:125], v[140:141]
	v_pk_fma_f32 v[140:141], v[126:127], v[126:127], v[140:141]
	v_pk_fma_f32 v[140:141], v[128:129], v[128:129], v[140:141]
	v_pk_fma_f32 v[140:141], v[130:131], v[130:131], v[140:141]
	v_add_f32_e32 v140, v140, v141
	s_nop 1
	v_add_f32_dpp v140, v140, v140 quad_perm:[1,0,3,2] row_mask:0xf bank_mask:0xf
	s_nop 1
	v_add_f32_dpp v140, v140, v140 quad_perm:[2,3,0,1] row_mask:0xf bank_mask:0xf
	s_nop 1
	v_add_f32_dpp v140, v140, v140 row_ror:4 row_mask:0xf bank_mask:0xf
	s_nop 1
	v_add_f32_dpp v140, v140, v140 row_ror:8 row_mask:0xf bank_mask:0xf
	s_nop 1
	v_add_f32_dpp v140, v140, v140 row_bcast:15 row_mask:0xa bank_mask:0xf
	s_nop 1
	v_add_f32_dpp v140, v140, v140 row_bcast:31 row_mask:0xc bank_mask:0xf
	s_nop 1
	v_fmamk_f32 v140, v140, 0x3a800000, v224
	v_rsq_f32_e32 v140, v140
	s_nop 0
	v_mul_f32_e32 v140, v144, v140
	s_nop 0
	v_readlane_b32 s4, v140, 63
	s_nop 1
	v_pk_mul_f32 v[116:117], v[116:117], s[4:5] op_sel_hi:[1,0]
	v_pk_mul_f32 v[118:119], v[118:119], s[4:5] op_sel_hi:[1,0]
	v_pk_mul_f32 v[120:121], v[120:121], s[4:5] op_sel_hi:[1,0]
	v_pk_mul_f32 v[122:123], v[122:123], s[4:5] op_sel_hi:[1,0]
	v_pk_mul_f32 v[124:125], v[124:125], s[4:5] op_sel_hi:[1,0]
	v_pk_mul_f32 v[126:127], v[126:127], s[4:5] op_sel_hi:[1,0]
	v_pk_mul_f32 v[128:129], v[128:129], s[4:5] op_sel_hi:[1,0]
	v_pk_mul_f32 v[130:131], v[130:131], s[4:5] op_sel_hi:[1,0]
	v_pk_fma_f32 v[198:199], v[0:1], v[116:117], v[198:199]
	v_pk_fma_f32 v[200:201], v[2:3], v[118:119], v[200:201]
	v_pk_fma_f32 v[202:203], v[4:5], v[120:121], v[202:203]
	v_pk_fma_f32 v[204:205], v[6:7], v[122:123], v[204:205]
	v_pk_fma_f32 v[206:207], v[8:9], v[124:125], v[206:207]
	v_pk_fma_f32 v[208:209], v[10:11], v[126:127], v[208:209]
	v_pk_fma_f32 v[210:211], v[12:13], v[128:129], v[210:211]
	v_pk_fma_f32 v[212:213], v[14:15], v[130:131], v[212:213]
	v_cvt_f16_f32_e32 v132, v198
	v_cvt_f16_f32_e32 v133, v200
	v_cvt_f16_f32_e32 v134, v202
	v_cvt_f16_f32_e32 v135, v204
	v_cvt_f16_f32_e32 v136, v206
	v_cvt_f16_f32_e32 v137, v208
	v_cvt_f16_f32_e32 v138, v210
	v_cvt_f16_f32_e32 v139, v212
	v_cvt_f16_f32_sdwa v132, v199 dst_sel:WORD_1 dst_unused:UNUSED_PRESERVE src0_sel:DWORD
	v_cvt_f16_f32_sdwa v133, v201 dst_sel:WORD_1 dst_unused:UNUSED_PRESERVE src0_sel:DWORD
	v_cvt_f16_f32_sdwa v134, v203 dst_sel:WORD_1 dst_unused:UNUSED_PRESERVE src0_sel:DWORD
	v_cvt_f16_f32_sdwa v135, v205 dst_sel:WORD_1 dst_unused:UNUSED_PRESERVE src0_sel:DWORD
	v_cvt_f16_f32_sdwa v136, v207 dst_sel:WORD_1 dst_unused:UNUSED_PRESERVE src0_sel:DWORD
	v_cvt_f16_f32_sdwa v137, v209 dst_sel:WORD_1 dst_unused:UNUSED_PRESERVE src0_sel:DWORD
	v_cvt_f16_f32_sdwa v138, v211 dst_sel:WORD_1 dst_unused:UNUSED_PRESERVE src0_sel:DWORD
	v_cvt_f16_f32_sdwa v139, v213 dst_sel:WORD_1 dst_unused:UNUSED_PRESERVE src0_sel:DWORD
	s_nop 0
	global_store_dwordx4 v187, v[132:135], s[42:43] offset:-4096
	global_store_dwordx4 v187, v[136:139], s[42:43] offset:-3072
	v_pk_mul_f32 v[140:141], v[198:199], v[198:199]
	v_pk_fma_f32 v[140:141], v[200:201], v[200:201], v[140:141]
	v_pk_fma_f32 v[140:141], v[202:203], v[202:203], v[140:141]
	v_pk_fma_f32 v[140:141], v[204:205], v[204:205], v[140:141]
	v_pk_fma_f32 v[140:141], v[206:207], v[206:207], v[140:141]
	v_pk_fma_f32 v[140:141], v[208:209], v[208:209], v[140:141]
	v_pk_fma_f32 v[140:141], v[210:211], v[210:211], v[140:141]
	v_pk_fma_f32 v[140:141], v[212:213], v[212:213], v[140:141]
	v_add_f32_e32 v140, v140, v141
	s_nop 1
	v_add_f32_dpp v140, v140, v140 quad_perm:[1,0,3,2] row_mask:0xf bank_mask:0xf
	s_nop 1
	v_add_f32_dpp v140, v140, v140 quad_perm:[2,3,0,1] row_mask:0xf bank_mask:0xf
	s_nop 1
	v_add_f32_dpp v140, v140, v140 row_ror:4 row_mask:0xf bank_mask:0xf
	s_nop 1
	v_add_f32_dpp v140, v140, v140 row_ror:8 row_mask:0xf bank_mask:0xf
	s_nop 1
	v_add_f32_dpp v140, v140, v140 row_bcast:15 row_mask:0xa bank_mask:0xf
	s_nop 1
	v_add_f32_dpp v140, v140, v140 row_bcast:31 row_mask:0xc bank_mask:0xf
; template <int R, bool SRCB> ...
;     ...
;         for (int r = 0; r < R; ++r) {
;             f32x4 y[2][2]; float ss = 0.f;
; #pragma unroll
;             for (int j = 0; j < 2; ++j) { const u32x4 t = yr[r][j];
;                 y[j][0] = (f32x4){bf_lo(t.x), bf_hi(t.x), bf_lo(t.y), bf_hi(t.y)}; y[j][1] = (f32x4){bf_lo(t.z), bf_hi(t.z), bf_lo(t.w), bf_hi(t.w)};
;                 if (R == 1 && YP) {
; #pragma unroll
;                     for (int k = 0; k < 2; ++k) { const float* pp = YP + (size_t)(row0 - M_LAT) * DM + 8 * lane + 512 * j + 4 * k; f32x4 s = *(const f32x4*)pp;
; #pragma unroll
;                         for (int q = 1; q < pg8::NSL; ++q) s = s + *(const f32x4*)(pp + (size_t)q * 2048 * DM);
;                         y[j][k] = s; } }
; #pragma unroll
;                 for (int k = 0; k < 2; ++k) ss += (y[j][k][0] * y[j][k][0] + y[j][k][1] * y[j][k][1]) + (y[j][k][2] * y[j][k][2] + y[j][k][3] * y[j][k][3]); }
;             const float rr = __builtin_amdgcn_rsqf(wave_sum(ss) * (1.0f / DM) + 1e-6f) * w;
; #pragma unroll
;             for (int j = 0; j < 2; ++j)
; #pragma unroll
;                 for (int k = 0; k < 2; ++k) h[r][j][k] = h[r][j][k] + gg[j][k] * (y[j][k] * rr);
;         }
;     }
; #pragma unroll
;     for (int r = 0; r < R; ++r)
; #pragma unroll
;         for (int j = 0; j < 2; ++j) { const int c = 8 * lane + 512 * j;
;             if (final_out) { *(f32x4*)(final_out + (size_t)(row0 + r) * DM + c) = h[r][j][0]; *(f32x4*)(final_out + (size_t)(row0 + r) * DM + c + 4) = h[r][j][1]; }
;     ...
;         for (int r = 0; r < R; ++r) {
;             float ss = 0.f;
; #pragma unroll
;             for (int j = 0; j < 2; ++j)
; #pragma unroll
;                 for (int k = 0; k < 2; ++k) ss += (h[r][j][k][0] * h[r][j][k][0] + h[r][j][k][1] * h[r][j][k][1]) + (h[r][j][k][2] * h[r][j][k][2] + h[r][j][k][3] * h[r][j][k][3]);
;             const float rr = __builtin_amdgcn_rsqf(wave_sum(ss) * (1.0f / DM) + 1e-6f);
; #pragma unroll
;             for (int j = 0; j < 2; ++j) { const f32x4 v0 = (h[r][j][0] * rr * gp[j][0]) * sc1[j][0] + sh[j][0], v1 = (h[r][j][1] * rr * gp[j][1]) * sc1[j][1] + sh[j][1];
;                 u32x4 t; t.x = pk2(v0[0], v0[1]); t.y = pk2(v0[2], v0[3]); t.z = pk2(v1[0], v1[1]); t.w = pk2(v1[2], v1[3]);
;                 *(u32x4*)(U + (size_t)(row0 + r) * DM + 8 * lane + 512 * j) = t; }
	s_nop 1
	v_fmamk_f32 v140, v140, 0x3a800000, v224
	v_rsq_f32_e32 v140, v140
	s_nop 0
	v_readlane_b32 s6, v140, 63
	s_nop 1
	v_pk_mul_f32 v[198:199], v[198:199], s[6:7] op_sel_hi:[1,0]
	v_pk_mul_f32 v[200:201], v[200:201], s[6:7] op_sel_hi:[1,0]
	v_pk_mul_f32 v[202:203], v[202:203], s[6:7] op_sel_hi:[1,0]
	v_pk_mul_f32 v[204:205], v[204:205], s[6:7] op_sel_hi:[1,0]
	v_pk_mul_f32 v[206:207], v[206:207], s[6:7] op_sel_hi:[1,0]
	v_pk_mul_f32 v[208:209], v[208:209], s[6:7] op_sel_hi:[1,0]
	v_pk_mul_f32 v[210:211], v[210:211], s[6:7] op_sel_hi:[1,0]
	v_pk_mul_f32 v[212:213], v[212:213], s[6:7] op_sel_hi:[1,0]
	v_pk_mul_f32 v[198:199], v[16:17], v[198:199]
	v_pk_mul_f32 v[200:201], v[18:19], v[200:201]
	v_pk_mul_f32 v[202:203], v[20:21], v[202:203]
	v_pk_mul_f32 v[204:205], v[22:23], v[204:205]
	v_pk_mul_f32 v[206:207], v[24:25], v[206:207]
	v_pk_mul_f32 v[208:209], v[26:27], v[208:209]
	v_pk_mul_f32 v[210:211], v[28:29], v[210:211]
	v_pk_mul_f32 v[212:213], v[30:31], v[212:213]
	v_pk_fma_f32 v[198:199], v[32:33], v[198:199], v[48:49]
	v_pk_fma_f32 v[200:201], v[34:35], v[200:201], v[50:51]
	v_pk_fma_f32 v[202:203], v[36:37], v[202:203], v[52:53]
	v_pk_fma_f32 v[204:205], v[38:39], v[204:205], v[54:55]
	v_pk_fma_f32 v[206:207], v[40:41], v[206:207], v[56:57]
	v_pk_fma_f32 v[208:209], v[42:43], v[208:209], v[58:59]
	v_pk_fma_f32 v[210:211], v[44:45], v[210:211], v[60:61]
	v_pk_fma_f32 v[212:213], v[46:47], v[212:213], v[62:63]
	v_cvt_pk_bf16_f32 v230, v198, v199
	v_cvt_pk_bf16_f32 v231, v200, v201
	v_cvt_pk_bf16_f32 v232, v202, v203
	v_cvt_pk_bf16_f32 v233, v204, v205
	v_cvt_pk_bf16_f32 v234, v206, v207
	v_cvt_pk_bf16_f32 v235, v208, v209
	v_cvt_pk_bf16_f32 v236, v210, v211
	v_cvt_pk_bf16_f32 v237, v212, v213
	global_store_dwordx4 v187, v[230:233], s[44:45] offset:-4096
	global_store_dwordx4 v187, v[234:237], s[44:45] offset:-3072
	s_waitcnt vmcnt(24)
	v_lshlrev_b32_e32 v116, 16, v156
	v_and_b32_e32 v117, 0xffff0000, v156
	v_lshlrev_b32_e32 v118, 16, v157
	v_and_b32_e32 v119, 0xffff0000, v157
	v_lshlrev_b32_e32 v120, 16, v158
	v_and_b32_e32 v121, 0xffff0000, v158
	v_lshlrev_b32_e32 v122, 16, v159
	v_and_b32_e32 v123, 0xffff0000, v159
	v_lshlrev_b32_e32 v124, 16, v160
	v_and_b32_e32 v125, 0xffff0000, v160
	v_lshlrev_b32_e32 v126, 16, v161
	v_and_b32_e32 v127, 0xffff0000, v161
	v_lshlrev_b32_e32 v128, 16, v162
	v_and_b32_e32 v129, 0xffff0000, v162
	v_lshlrev_b32_e32 v130, 16, v163
	v_and_b32_e32 v131, 0xffff0000, v163
	v_cvt_f32_f16_e32 v198, v72
	v_cvt_f32_f16_sdwa v199, v72 dst_sel:DWORD dst_unused:UNUSED_PAD src0_sel:WORD_1
	v_cvt_f32_f16_e32 v200, v73
	v_cvt_f32_f16_sdwa v201, v73 dst_sel:DWORD dst_unused:UNUSED_PAD src0_sel:WORD_1
	v_cvt_f32_f16_e32 v202, v74
	v_cvt_f32_f16_sdwa v203, v74 dst_sel:DWORD dst_unused:UNUSED_PAD src0_sel:WORD_1
	v_cvt_f32_f16_e32 v204, v75
	v_cvt_f32_f16_sdwa v205, v75 dst_sel:DWORD dst_unused:UNUSED_PAD src0_sel:WORD_1
	v_cvt_f32_f16_e32 v206, v76
	v_cvt_f32_f16_sdwa v207, v76 dst_sel:DWORD dst_unused:UNUSED_PAD src0_sel:WORD_1
	v_cvt_f32_f16_e32 v208, v77
	v_cvt_f32_f16_sdwa v209, v77 dst_sel:DWORD dst_unused:UNUSED_PAD src0_sel:WORD_1
	v_cvt_f32_f16_e32 v210, v78
	v_cvt_f32_f16_sdwa v211, v78 dst_sel:DWORD dst_unused:UNUSED_PAD src0_sel:WORD_1
	v_cvt_f32_f16_e32 v212, v79
	v_cvt_f32_f16_sdwa v213, v79 dst_sel:DWORD dst_unused:UNUSED_PAD src0_sel:WORD_1
	v_pk_mul_f32 v[140:141], v[116:117], v[116:117]
	v_pk_fma_f32 v[140:141], v[118:119], v[118:119], v[140:141]
	v_pk_fma_f32 v[140:141], v[120:121], v[120:121], v[140:141]
	v_pk_fma_f32 v[140:141], v[122:123], v[122:123], v[140:141]
	v_pk_fma_f32 v[140:141], v[124:125], v[124:125], v[140:141]
	v_pk_fma_f32 v[140:141], v[126:127], v[126:127], v[140:141]
	v_pk_fma_f32 v[140:141], v[128:129], v[128:129], v[140:141]
	v_pk_fma_f32 v[140:141], v[130:131], v[130:131], v[140:141]
	v_add_f32_e32 v140, v140, v141
	s_nop 1
	v_add_f32_dpp v140, v140, v140 quad_perm:[1,0,3,2] row_mask:0xf bank_mask:0xf
	s_nop 1
	v_add_f32_dpp v140, v140, v140 quad_perm:[2,3,0,1] row_mask:0xf bank_mask:0xf
	s_nop 1
	v_add_f32_dpp v140, v140, v140 row_ror:4 row_mask:0xf bank_mask:0xf
	s_nop 1
	v_add_f32_dpp v140, v140, v140 row_ror:8 row_mask:0xf bank_mask:0xf
	s_nop 1
	v_add_f32_dpp v140, v140, v140 row_bcast:15 row_mask:0xa bank_mask:0xf
	s_nop 1
	v_add_f32_dpp v140, v140, v140 row_bcast:31 row_mask:0xc bank_mask:0xf
	s_nop 1
	v_fmamk_f32 v140, v140, 0x3a800000, v224
	v_rsq_f32_e32 v140, v140
	s_nop 0
	v_mul_f32_e32 v140, v144, v140
	s_nop 0
	v_readlane_b32 s4, v140, 63
	s_nop 1
	v_pk_mul_f32 v[116:117], v[116:117], s[4:5] op_sel_hi:[1,0]
	v_pk_mul_f32 v[118:119], v[118:119], s[4:5] op_sel_hi:[1,0]
	v_pk_mul_f32 v[120:121], v[120:121], s[4:5] op_sel_hi:[1,0]
	v_pk_mul_f32 v[122:123], v[122:123], s[4:5] op_sel_hi:[1,0]
	v_pk_mul_f32 v[124:125], v[124:125], s[4:5] op_sel_hi:[1,0]
	v_pk_mul_f32 v[126:127], v[126:127], s[4:5] op_sel_hi:[1,0]
	v_pk_mul_f32 v[128:129], v[128:129], s[4:5] op_sel_hi:[1,0]
	v_pk_mul_f32 v[130:131], v[130:131], s[4:5] op_sel_hi:[1,0]
	v_pk_fma_f32 v[198:199], v[0:1], v[116:117], v[198:199]
	v_pk_fma_f32 v[200:201], v[2:3], v[118:119], v[200:201]
	v_pk_fma_f32 v[202:203], v[4:5], v[120:121], v[202:203]
	v_pk_fma_f32 v[204:205], v[6:7], v[122:123], v[204:205]
	v_pk_fma_f32 v[206:207], v[8:9], v[124:125], v[206:207]
	v_pk_fma_f32 v[208:209], v[10:11], v[126:127], v[208:209]
	v_pk_fma_f32 v[210:211], v[12:13], v[128:129], v[210:211]
	v_pk_fma_f32 v[212:213], v[14:15], v[130:131], v[212:213]
	v_cvt_f16_f32_e32 v132, v198
	v_cvt_f16_f32_e32 v133, v200
	v_cvt_f16_f32_e32 v134, v202
	v_cvt_f16_f32_e32 v135, v204
	v_cvt_f16_f32_e32 v136, v206
	v_cvt_f16_f32_e32 v137, v208
; __device__ __forceinline__ unsigned pk2(float lo, float hi) { return pg8::cvt_pk_bf16(lo, hi); }
; template <int R, bool SRCB> ...
;     ...
;         for (int r = 0; r < R; ++r) {
;             f32x4 y[2][2]; float ss = 0.f;
; #pragma unroll
;             for (int j = 0; j < 2; ++j) { const u32x4 t = yr[r][j];
;                 y[j][0] = (f32x4){bf_lo(t.x), bf_hi(t.x), bf_lo(t.y), bf_hi(t.y)}; y[j][1] = (f32x4){bf_lo(t.z), bf_hi(t.z), bf_lo(t.w), bf_hi(t.w)};
;                 if (R == 1 && YP) {
; #pragma unroll
;                     for (int k = 0; k < 2; ++k) { const float* pp = YP + (size_t)(row0 - M_LAT) * DM + 8 * lane + 512 * j + 4 * k; f32x4 s = *(const f32x4*)pp;
; #pragma unroll
;                         for (int q = 1; q < pg8::NSL; ++q) s = s + *(const f32x4*)(pp + (size_t)q * 2048 * DM);
;                         y[j][k] = s; } }
; #pragma unroll
;     ...
;             else { u32x4 t; t.x = pkh2(h[r][j][0][0], h[r][j][0][1]); t.y = pkh2(h[r][j][0][2], h[r][j][0][3]); t.z = pkh2(h[r][j][1][0], h[r][j][1][1]); t.w = pkh2(h[r][j][1][2], h[r][j][1][3]);
;                 *(u32x4*)(hout + (size_t)(row0 + r) * DM + c) = t; } }
;     if (U) {
;         f32x4 gp[2][2], sc1[2][2], sh[2][2];
; #pragma unroll
;         for (int j = 0; j < 2; ++j)
; #pragma unroll
;             for (int k = 0; k < 2; ++k) { const int c = 8 * lane + 512 * j + 4 * k; gp[j][k] = *(const f32x4*)(gpre + c); sc1[j][k] = *(const f32x4*)(scale + (size_t)mrow * 9216 + c) + 1.0f; sh[j][k] = *(const f32x4*)(shift + (size_t)mrow * 9216 + c); }
; #pragma unroll
;         for (int r = 0; r < R; ++r) {
;             float ss = 0.f;
; #pragma unroll
;             for (int j = 0; j < 2; ++j)
; #pragma unroll
;                 for (int k = 0; k < 2; ++k) ss += (h[r][j][k][0] * h[r][j][k][0] + h[r][j][k][1] * h[r][j][k][1]) + (h[r][j][k][2] * h[r][j][k][2] + h[r][j][k][3] * h[r][j][k][3]);
;             const float rr = __builtin_amdgcn_rsqf(wave_sum(ss) * (1.0f / DM) + 1e-6f);
; #pragma unroll
;             for (int j = 0; j < 2; ++j) { const f32x4 v0 = (h[r][j][0] * rr * gp[j][0]) * sc1[j][0] + sh[j][0], v1 = (h[r][j][1] * rr * gp[j][1]) * sc1[j][1] + sh[j][1];
;                 u32x4 t; t.x = pk2(v0[0], v0[1]); t.y = pk2(v0[2], v0[3]); t.z = pk2(v1[0], v1[1]); t.w = pk2(v1[2], v1[3]);
;                 *(u32x4*)(U + (size_t)(row0 + r) * DM + 8 * lane + 512 * j) = t; }
	v_cvt_f16_f32_e32 v138, v210
	v_cvt_f16_f32_e32 v139, v212
	v_cvt_f16_f32_sdwa v132, v199 dst_sel:WORD_1 dst_unused:UNUSED_PRESERVE src0_sel:DWORD
	v_cvt_f16_f32_sdwa v133, v201 dst_sel:WORD_1 dst_unused:UNUSED_PRESERVE src0_sel:DWORD
	v_cvt_f16_f32_sdwa v134, v203 dst_sel:WORD_1 dst_unused:UNUSED_PRESERVE src0_sel:DWORD
	v_cvt_f16_f32_sdwa v135, v205 dst_sel:WORD_1 dst_unused:UNUSED_PRESERVE src0_sel:DWORD
	v_cvt_f16_f32_sdwa v136, v207 dst_sel:WORD_1 dst_unused:UNUSED_PRESERVE src0_sel:DWORD
	v_cvt_f16_f32_sdwa v137, v209 dst_sel:WORD_1 dst_unused:UNUSED_PRESERVE src0_sel:DWORD
	v_cvt_f16_f32_sdwa v138, v211 dst_sel:WORD_1 dst_unused:UNUSED_PRESERVE src0_sel:DWORD
	v_cvt_f16_f32_sdwa v139, v213 dst_sel:WORD_1 dst_unused:UNUSED_PRESERVE src0_sel:DWORD
	s_nop 0
	global_store_dwordx4 v187, v[132:135], s[42:43] offset:-2048
	global_store_dwordx4 v187, v[136:139], s[42:43] offset:-1024
	v_pk_mul_f32 v[140:141], v[198:199], v[198:199]
	v_pk_fma_f32 v[140:141], v[200:201], v[200:201], v[140:141]
	v_pk_fma_f32 v[140:141], v[202:203], v[202:203], v[140:141]
	v_pk_fma_f32 v[140:141], v[204:205], v[204:205], v[140:141]
	v_pk_fma_f32 v[140:141], v[206:207], v[206:207], v[140:141]
	v_pk_fma_f32 v[140:141], v[208:209], v[208:209], v[140:141]
	v_pk_fma_f32 v[140:141], v[210:211], v[210:211], v[140:141]
	v_pk_fma_f32 v[140:141], v[212:213], v[212:213], v[140:141]
	v_add_f32_e32 v140, v140, v141
	s_nop 1
	v_add_f32_dpp v140, v140, v140 quad_perm:[1,0,3,2] row_mask:0xf bank_mask:0xf
	s_nop 1
	v_add_f32_dpp v140, v140, v140 quad_perm:[2,3,0,1] row_mask:0xf bank_mask:0xf
	s_nop 1
	v_add_f32_dpp v140, v140, v140 row_ror:4 row_mask:0xf bank_mask:0xf
	s_nop 1
	v_add_f32_dpp v140, v140, v140 row_ror:8 row_mask:0xf bank_mask:0xf
	s_nop 1
	v_add_f32_dpp v140, v140, v140 row_bcast:15 row_mask:0xa bank_mask:0xf
	s_nop 1
	v_add_f32_dpp v140, v140, v140 row_bcast:31 row_mask:0xc bank_mask:0xf
	s_nop 1
	v_fmamk_f32 v140, v140, 0x3a800000, v224
	v_rsq_f32_e32 v140, v140
	s_nop 0
	v_readlane_b32 s6, v140, 63
	s_nop 1
	v_pk_mul_f32 v[198:199], v[198:199], s[6:7] op_sel_hi:[1,0]
	v_pk_mul_f32 v[200:201], v[200:201], s[6:7] op_sel_hi:[1,0]
	v_pk_mul_f32 v[202:203], v[202:203], s[6:7] op_sel_hi:[1,0]
	v_pk_mul_f32 v[204:205], v[204:205], s[6:7] op_sel_hi:[1,0]
	v_pk_mul_f32 v[206:207], v[206:207], s[6:7] op_sel_hi:[1,0]
	v_pk_mul_f32 v[208:209], v[208:209], s[6:7] op_sel_hi:[1,0]
	v_pk_mul_f32 v[210:211], v[210:211], s[6:7] op_sel_hi:[1,0]
	v_pk_mul_f32 v[212:213], v[212:213], s[6:7] op_sel_hi:[1,0]
	v_pk_mul_f32 v[198:199], v[16:17], v[198:199]
	v_pk_mul_f32 v[200:201], v[18:19], v[200:201]
	v_pk_mul_f32 v[202:203], v[20:21], v[202:203]
	v_pk_mul_f32 v[204:205], v[22:23], v[204:205]
	v_pk_mul_f32 v[206:207], v[24:25], v[206:207]
	v_pk_mul_f32 v[208:209], v[26:27], v[208:209]
	v_pk_mul_f32 v[210:211], v[28:29], v[210:211]
	v_pk_mul_f32 v[212:213], v[30:31], v[212:213]
	v_pk_fma_f32 v[198:199], v[32:33], v[198:199], v[48:49]
	v_pk_fma_f32 v[200:201], v[34:35], v[200:201], v[50:51]
	v_pk_fma_f32 v[202:203], v[36:37], v[202:203], v[52:53]
	v_pk_fma_f32 v[204:205], v[38:39], v[204:205], v[54:55]
	v_pk_fma_f32 v[206:207], v[40:41], v[206:207], v[56:57]
	v_pk_fma_f32 v[208:209], v[42:43], v[208:209], v[58:59]
	v_pk_fma_f32 v[210:211], v[44:45], v[210:211], v[60:61]
	v_pk_fma_f32 v[212:213], v[46:47], v[212:213], v[62:63]
	v_cvt_pk_bf16_f32 v230, v198, v199
	v_cvt_pk_bf16_f32 v231, v200, v201
	v_cvt_pk_bf16_f32 v232, v202, v203
	v_cvt_pk_bf16_f32 v233, v204, v205
	v_cvt_pk_bf16_f32 v234, v206, v207
	v_cvt_pk_bf16_f32 v235, v208, v209
	v_cvt_pk_bf16_f32 v236, v210, v211
	v_cvt_pk_bf16_f32 v237, v212, v213
	global_store_dwordx4 v187, v[230:233], s[44:45] offset:-2048
	global_store_dwordx4 v187, v[234:237], s[44:45] offset:-1024
	s_waitcnt vmcnt(20)
	v_lshlrev_b32_e32 v116, 16, v164
	v_and_b32_e32 v117, 0xffff0000, v164
	v_lshlrev_b32_e32 v118, 16, v165
	v_and_b32_e32 v119, 0xffff0000, v165
	v_lshlrev_b32_e32 v120, 16, v166
	v_and_b32_e32 v121, 0xffff0000, v166
	v_lshlrev_b32_e32 v122, 16, v167
	v_and_b32_e32 v123, 0xffff0000, v167
	v_lshlrev_b32_e32 v124, 16, v168
	v_and_b32_e32 v125, 0xffff0000, v168
	v_lshlrev_b32_e32 v126, 16, v169
	v_and_b32_e32 v127, 0xffff0000, v169
	v_lshlrev_b32_e32 v128, 16, v170
	v_and_b32_e32 v129, 0xffff0000, v170
	v_lshlrev_b32_e32 v130, 16, v171
	v_and_b32_e32 v131, 0xffff0000, v171
	v_cvt_f32_f16_e32 v198, v80
	v_cvt_f32_f16_sdwa v199, v80 dst_sel:DWORD dst_unused:UNUSED_PAD src0_sel:WORD_1
	v_cvt_f32_f16_e32 v200, v81
	v_cvt_f32_f16_sdwa v201, v81 dst_sel:DWORD dst_unused:UNUSED_PAD src0_sel:WORD_1
	v_cvt_f32_f16_e32 v202, v82
	v_cvt_f32_f16_sdwa v203, v82 dst_sel:DWORD dst_unused:UNUSED_PAD src0_sel:WORD_1
	v_cvt_f32_f16_e32 v204, v83
	v_cvt_f32_f16_sdwa v205, v83 dst_sel:DWORD dst_unused:UNUSED_PAD src0_sel:WORD_1
	v_cvt_f32_f16_e32 v206, v84
	v_cvt_f32_f16_sdwa v207, v84 dst_sel:DWORD dst_unused:UNUSED_PAD src0_sel:WORD_1
	v_cvt_f32_f16_e32 v208, v85
	v_cvt_f32_f16_sdwa v209, v85 dst_sel:DWORD dst_unused:UNUSED_PAD src0_sel:WORD_1
	v_cvt_f32_f16_e32 v210, v86
	v_cvt_f32_f16_sdwa v211, v86 dst_sel:DWORD dst_unused:UNUSED_PAD src0_sel:WORD_1
	v_cvt_f32_f16_e32 v212, v87
	v_cvt_f32_f16_sdwa v213, v87 dst_sel:DWORD dst_unused:UNUSED_PAD src0_sel:WORD_1
	v_pk_mul_f32 v[140:141], v[116:117], v[116:117]
	v_pk_fma_f32 v[140:141], v[118:119], v[118:119], v[140:141]
	v_pk_fma_f32 v[140:141], v[120:121], v[120:121], v[140:141]
	v_pk_fma_f32 v[140:141], v[122:123], v[122:123], v[140:141]
	v_pk_fma_f32 v[140:141], v[124:125], v[124:125], v[140:141]
	v_pk_fma_f32 v[140:141], v[126:127], v[126:127], v[140:141]
	v_pk_fma_f32 v[140:141], v[128:129], v[128:129], v[140:141]
; __device__ __forceinline__ unsigned pk2(float lo, float hi) { return pg8::cvt_pk_bf16(lo, hi); }
; template <int R, bool SRCB> ...
;     ...
;             const float rr = __builtin_amdgcn_rsqf(wave_sum(ss) * (1.0f / DM) + 1e-6f) * w;
; #pragma unroll
;             for (int j = 0; j < 2; ++j)
; #pragma unroll
;                 for (int k = 0; k < 2; ++k) h[r][j][k] = h[r][j][k] + gg[j][k] * (y[j][k] * rr);
;         }
;     }
; #pragma unroll
;     for (int r = 0; r < R; ++r)
; #pragma unroll
;         for (int j = 0; j < 2; ++j) { const int c = 8 * lane + 512 * j;
;             if (final_out) { *(f32x4*)(final_out + (size_t)(row0 + r) * DM + c) = h[r][j][0]; *(f32x4*)(final_out + (size_t)(row0 + r) * DM + c + 4) = h[r][j][1]; }
;             else { u32x4 t; t.x = pkh2(h[r][j][0][0], h[r][j][0][1]); t.y = pkh2(h[r][j][0][2], h[r][j][0][3]); t.z = pkh2(h[r][j][1][0], h[r][j][1][1]); t.w = pkh2(h[r][j][1][2], h[r][j][1][3]);
;                 *(u32x4*)(hout + (size_t)(row0 + r) * DM + c) = t; } }
;     if (U) {
;         f32x4 gp[2][2], sc1[2][2], sh[2][2];
; #pragma unroll
;         for (int j = 0; j < 2; ++j)
; #pragma unroll
;             for (int k = 0; k < 2; ++k) { const int c = 8 * lane + 512 * j + 4 * k; gp[j][k] = *(const f32x4*)(gpre + c); sc1[j][k] = *(const f32x4*)(scale + (size_t)mrow * 9216 + c) + 1.0f; sh[j][k] = *(const f32x4*)(shift + (size_t)mrow * 9216 + c); }
; #pragma unroll
;         for (int r = 0; r < R; ++r) {
;             float ss = 0.f;
; #pragma unroll
;             for (int j = 0; j < 2; ++j)
; #pragma unroll
;                 for (int k = 0; k < 2; ++k) ss += (h[r][j][k][0] * h[r][j][k][0] + h[r][j][k][1] * h[r][j][k][1]) + (h[r][j][k][2] * h[r][j][k][2] + h[r][j][k][3] * h[r][j][k][3]);
;             const float rr = __builtin_amdgcn_rsqf(wave_sum(ss) * (1.0f / DM) + 1e-6f);
; #pragma unroll
;             for (int j = 0; j < 2; ++j) { const f32x4 v0 = (h[r][j][0] * rr * gp[j][0]) * sc1[j][0] + sh[j][0], v1 = (h[r][j][1] * rr * gp[j][1]) * sc1[j][1] + sh[j][1];
;                 u32x4 t; t.x = pk2(v0[0], v0[1]); t.y = pk2(v0[2], v0[3]); t.z = pk2(v1[0], v1[1]); t.w = pk2(v1[2], v1[3]);
;                 *(u32x4*)(U + (size_t)(row0 + r) * DM + 8 * lane + 512 * j) = t; }
	v_pk_fma_f32 v[140:141], v[130:131], v[130:131], v[140:141]
	v_add_f32_e32 v140, v140, v141
	s_nop 1
	v_add_f32_dpp v140, v140, v140 quad_perm:[1,0,3,2] row_mask:0xf bank_mask:0xf
	s_nop 1
	v_add_f32_dpp v140, v140, v140 quad_perm:[2,3,0,1] row_mask:0xf bank_mask:0xf
	s_nop 1
	v_add_f32_dpp v140, v140, v140 row_ror:4 row_mask:0xf bank_mask:0xf
	s_nop 1
	v_add_f32_dpp v140, v140, v140 row_ror:8 row_mask:0xf bank_mask:0xf
	s_nop 1
	v_add_f32_dpp v140, v140, v140 row_bcast:15 row_mask:0xa bank_mask:0xf
	s_nop 1
	v_add_f32_dpp v140, v140, v140 row_bcast:31 row_mask:0xc bank_mask:0xf
	s_nop 1
	v_fmamk_f32 v140, v140, 0x3a800000, v224
	v_rsq_f32_e32 v140, v140
	s_nop 0
	v_mul_f32_e32 v140, v144, v140
	s_nop 0
	v_readlane_b32 s4, v140, 63
	s_nop 1
	v_pk_mul_f32 v[116:117], v[116:117], s[4:5] op_sel_hi:[1,0]
	v_pk_mul_f32 v[118:119], v[118:119], s[4:5] op_sel_hi:[1,0]
	v_pk_mul_f32 v[120:121], v[120:121], s[4:5] op_sel_hi:[1,0]
	v_pk_mul_f32 v[122:123], v[122:123], s[4:5] op_sel_hi:[1,0]
	v_pk_mul_f32 v[124:125], v[124:125], s[4:5] op_sel_hi:[1,0]
	v_pk_mul_f32 v[126:127], v[126:127], s[4:5] op_sel_hi:[1,0]
	v_pk_mul_f32 v[128:129], v[128:129], s[4:5] op_sel_hi:[1,0]
	v_pk_mul_f32 v[130:131], v[130:131], s[4:5] op_sel_hi:[1,0]
	v_pk_fma_f32 v[198:199], v[0:1], v[116:117], v[198:199]
	v_pk_fma_f32 v[200:201], v[2:3], v[118:119], v[200:201]
	v_pk_fma_f32 v[202:203], v[4:5], v[120:121], v[202:203]
	v_pk_fma_f32 v[204:205], v[6:7], v[122:123], v[204:205]
	v_pk_fma_f32 v[206:207], v[8:9], v[124:125], v[206:207]
	v_pk_fma_f32 v[208:209], v[10:11], v[126:127], v[208:209]
	v_pk_fma_f32 v[210:211], v[12:13], v[128:129], v[210:211]
	v_pk_fma_f32 v[212:213], v[14:15], v[130:131], v[212:213]
	v_cvt_f16_f32_e32 v132, v198
	v_cvt_f16_f32_e32 v133, v200
	v_cvt_f16_f32_e32 v134, v202
	v_cvt_f16_f32_e32 v135, v204
	v_cvt_f16_f32_e32 v136, v206
	v_cvt_f16_f32_e32 v137, v208
	v_cvt_f16_f32_e32 v138, v210
	v_cvt_f16_f32_e32 v139, v212
	v_cvt_f16_f32_sdwa v132, v199 dst_sel:WORD_1 dst_unused:UNUSED_PRESERVE src0_sel:DWORD
	v_cvt_f16_f32_sdwa v133, v201 dst_sel:WORD_1 dst_unused:UNUSED_PRESERVE src0_sel:DWORD
	v_cvt_f16_f32_sdwa v134, v203 dst_sel:WORD_1 dst_unused:UNUSED_PRESERVE src0_sel:DWORD
	v_cvt_f16_f32_sdwa v135, v205 dst_sel:WORD_1 dst_unused:UNUSED_PRESERVE src0_sel:DWORD
	v_cvt_f16_f32_sdwa v136, v207 dst_sel:WORD_1 dst_unused:UNUSED_PRESERVE src0_sel:DWORD
	v_cvt_f16_f32_sdwa v137, v209 dst_sel:WORD_1 dst_unused:UNUSED_PRESERVE src0_sel:DWORD
	v_cvt_f16_f32_sdwa v138, v211 dst_sel:WORD_1 dst_unused:UNUSED_PRESERVE src0_sel:DWORD
	v_cvt_f16_f32_sdwa v139, v213 dst_sel:WORD_1 dst_unused:UNUSED_PRESERVE src0_sel:DWORD
	s_nop 0
	global_store_dwordx4 v187, v[132:135], s[42:43] offset:0
	global_store_dwordx4 v187, v[136:139], s[42:43] offset:1024
	v_pk_mul_f32 v[140:141], v[198:199], v[198:199]
	v_pk_fma_f32 v[140:141], v[200:201], v[200:201], v[140:141]
	v_pk_fma_f32 v[140:141], v[202:203], v[202:203], v[140:141]
	v_pk_fma_f32 v[140:141], v[204:205], v[204:205], v[140:141]
	v_pk_fma_f32 v[140:141], v[206:207], v[206:207], v[140:141]
	v_pk_fma_f32 v[140:141], v[208:209], v[208:209], v[140:141]
	v_pk_fma_f32 v[140:141], v[210:211], v[210:211], v[140:141]
	v_pk_fma_f32 v[140:141], v[212:213], v[212:213], v[140:141]
	v_add_f32_e32 v140, v140, v141
	s_nop 1
	v_add_f32_dpp v140, v140, v140 quad_perm:[1,0,3,2] row_mask:0xf bank_mask:0xf
	s_nop 1
	v_add_f32_dpp v140, v140, v140 quad_perm:[2,3,0,1] row_mask:0xf bank_mask:0xf
	s_nop 1
	v_add_f32_dpp v140, v140, v140 row_ror:4 row_mask:0xf bank_mask:0xf
	s_nop 1
	v_add_f32_dpp v140, v140, v140 row_ror:8 row_mask:0xf bank_mask:0xf
	s_nop 1
	v_add_f32_dpp v140, v140, v140 row_bcast:15 row_mask:0xa bank_mask:0xf
	s_nop 1
	v_add_f32_dpp v140, v140, v140 row_bcast:31 row_mask:0xc bank_mask:0xf
	s_nop 1
	v_fmamk_f32 v140, v140, 0x3a800000, v224
	v_rsq_f32_e32 v140, v140
	s_nop 0
	v_readlane_b32 s6, v140, 63
	s_nop 1
	v_pk_mul_f32 v[198:199], v[198:199], s[6:7] op_sel_hi:[1,0]
	v_pk_mul_f32 v[200:201], v[200:201], s[6:7] op_sel_hi:[1,0]
	v_pk_mul_f32 v[202:203], v[202:203], s[6:7] op_sel_hi:[1,0]
	v_pk_mul_f32 v[204:205], v[204:205], s[6:7] op_sel_hi:[1,0]
	v_pk_mul_f32 v[206:207], v[206:207], s[6:7] op_sel_hi:[1,0]
	v_pk_mul_f32 v[208:209], v[208:209], s[6:7] op_sel_hi:[1,0]
	v_pk_mul_f32 v[210:211], v[210:211], s[6:7] op_sel_hi:[1,0]
	v_pk_mul_f32 v[212:213], v[212:213], s[6:7] op_sel_hi:[1,0]
	v_pk_mul_f32 v[198:199], v[16:17], v[198:199]
	v_pk_mul_f32 v[200:201], v[18:19], v[200:201]
	v_pk_mul_f32 v[202:203], v[20:21], v[202:203]
	v_pk_mul_f32 v[204:205], v[22:23], v[204:205]
	v_pk_mul_f32 v[206:207], v[24:25], v[206:207]
	v_pk_mul_f32 v[208:209], v[26:27], v[208:209]
	v_pk_mul_f32 v[210:211], v[28:29], v[210:211]
	v_pk_mul_f32 v[212:213], v[30:31], v[212:213]
	v_pk_fma_f32 v[198:199], v[32:33], v[198:199], v[48:49]
	v_pk_fma_f32 v[200:201], v[34:35], v[200:201], v[50:51]
	v_pk_fma_f32 v[202:203], v[36:37], v[202:203], v[52:53]
	v_pk_fma_f32 v[204:205], v[38:39], v[204:205], v[54:55]
	v_pk_fma_f32 v[206:207], v[40:41], v[206:207], v[56:57]
	v_pk_fma_f32 v[208:209], v[42:43], v[208:209], v[58:59]
	v_pk_fma_f32 v[210:211], v[44:45], v[210:211], v[60:61]
	v_pk_fma_f32 v[212:213], v[46:47], v[212:213], v[62:63]
	v_cvt_pk_bf16_f32 v230, v198, v199
	v_cvt_pk_bf16_f32 v231, v200, v201
	v_cvt_pk_bf16_f32 v232, v202, v203
	v_cvt_pk_bf16_f32 v233, v204, v205
	v_cvt_pk_bf16_f32 v234, v206, v207
	v_cvt_pk_bf16_f32 v235, v208, v209
	v_cvt_pk_bf16_f32 v236, v210, v211
	v_cvt_pk_bf16_f32 v237, v212, v213
	global_store_dwordx4 v187, v[230:233], s[44:45] offset:0
	global_store_dwordx4 v187, v[234:237], s[44:45] offset:1024
	s_waitcnt vmcnt(16)
; __device__ __forceinline__ float bf_lo(unsigned w) { return __uint_as_float(w << 16); }
; __device__ __forceinline__ float bf_hi(unsigned w) { return __uint_as_float(w & 0xffff0000u); }
; __device__ __forceinline__ unsigned pkh2(float lo, float hi) { return (unsigned)__builtin_bit_cast(unsigned short, (_Float16)lo) | ((unsigned)__builtin_bit_cast(unsigned short, (_Float16)hi) << 16); }
; template <int R, bool SRCB> ...
;     ...
;             for (int j = 0; j < 2; ++j) { const u32x4 t = yr[r][j];
;                 y[j][0] = (f32x4){bf_lo(t.x), bf_hi(t.x), bf_lo(t.y), bf_hi(t.y)}; y[j][1] = (f32x4){bf_lo(t.z), bf_hi(t.z), bf_lo(t.w), bf_hi(t.w)};
;                 if (R == 1 && YP) {
; #pragma unroll
;                     for (int k = 0; k < 2; ++k) { const float* pp = YP + (size_t)(row0 - M_LAT) * DM + 8 * lane + 512 * j + 4 * k; f32x4 s = *(const f32x4*)pp;
; #pragma unroll
;                         for (int q = 1; q < pg8::NSL; ++q) s = s + *(const f32x4*)(pp + (size_t)q * 2048 * DM);
;                         y[j][k] = s; } }
; #pragma unroll
;                 for (int k = 0; k < 2; ++k) ss += (y[j][k][0] * y[j][k][0] + y[j][k][1] * y[j][k][1]) + (y[j][k][2] * y[j][k][2] + y[j][k][3] * y[j][k][3]); }
;             const float rr = __builtin_amdgcn_rsqf(wave_sum(ss) * (1.0f / DM) + 1e-6f) * w;
; #pragma unroll
;             for (int j = 0; j < 2; ++j)
; #pragma unroll
;                 for (int k = 0; k < 2; ++k) h[r][j][k] = h[r][j][k] + gg[j][k] * (y[j][k] * rr);
;         }
;     }
; #pragma unroll
;     for (int r = 0; r < R; ++r)
; #pragma unroll
;         for (int j = 0; j < 2; ++j) { const int c = 8 * lane + 512 * j;
;             if (final_out) { *(f32x4*)(final_out + (size_t)(row0 + r) * DM + c) = h[r][j][0]; *(f32x4*)(final_out + (size_t)(row0 + r) * DM + c + 4) = h[r][j][1]; }
;             else { u32x4 t; t.x = pkh2(h[r][j][0][0], h[r][j][0][1]); t.y = pkh2(h[r][j][0][2], h[r][j][0][3]); t.z = pkh2(h[r][j][1][0], h[r][j][1][1]); t.w = pkh2(h[r][j][1][2], h[r][j][1][3]);
;                 *(u32x4*)(hout + (size_t)(row0 + r) * DM + c) = t; } }
	v_lshlrev_b32_e32 v116, 16, v172
	v_and_b32_e32 v117, 0xffff0000, v172
	v_lshlrev_b32_e32 v118, 16, v173
	v_and_b32_e32 v119, 0xffff0000, v173
	v_lshlrev_b32_e32 v120, 16, v174
	v_and_b32_e32 v121, 0xffff0000, v174
	v_lshlrev_b32_e32 v122, 16, v175
	v_and_b32_e32 v123, 0xffff0000, v175
	v_lshlrev_b32_e32 v124, 16, v176
	v_and_b32_e32 v125, 0xffff0000, v176
	v_lshlrev_b32_e32 v126, 16, v177
	v_and_b32_e32 v127, 0xffff0000, v177
	v_lshlrev_b32_e32 v128, 16, v178
	v_and_b32_e32 v129, 0xffff0000, v178
	v_lshlrev_b32_e32 v130, 16, v179
	v_and_b32_e32 v131, 0xffff0000, v179
	v_cvt_f32_f16_e32 v198, v88
	v_cvt_f32_f16_sdwa v199, v88 dst_sel:DWORD dst_unused:UNUSED_PAD src0_sel:WORD_1
	v_cvt_f32_f16_e32 v200, v89
	v_cvt_f32_f16_sdwa v201, v89 dst_sel:DWORD dst_unused:UNUSED_PAD src0_sel:WORD_1
	v_cvt_f32_f16_e32 v202, v90
	v_cvt_f32_f16_sdwa v203, v90 dst_sel:DWORD dst_unused:UNUSED_PAD src0_sel:WORD_1
	v_cvt_f32_f16_e32 v204, v91
	v_cvt_f32_f16_sdwa v205, v91 dst_sel:DWORD dst_unused:UNUSED_PAD src0_sel:WORD_1
	v_cvt_f32_f16_e32 v206, v92
	v_cvt_f32_f16_sdwa v207, v92 dst_sel:DWORD dst_unused:UNUSED_PAD src0_sel:WORD_1
	v_cvt_f32_f16_e32 v208, v93
	v_cvt_f32_f16_sdwa v209, v93 dst_sel:DWORD dst_unused:UNUSED_PAD src0_sel:WORD_1
	v_cvt_f32_f16_e32 v210, v94
	v_cvt_f32_f16_sdwa v211, v94 dst_sel:DWORD dst_unused:UNUSED_PAD src0_sel:WORD_1
	v_cvt_f32_f16_e32 v212, v95
	v_cvt_f32_f16_sdwa v213, v95 dst_sel:DWORD dst_unused:UNUSED_PAD src0_sel:WORD_1
	v_pk_mul_f32 v[140:141], v[116:117], v[116:117]
	v_pk_fma_f32 v[140:141], v[118:119], v[118:119], v[140:141]
	v_pk_fma_f32 v[140:141], v[120:121], v[120:121], v[140:141]
	v_pk_fma_f32 v[140:141], v[122:123], v[122:123], v[140:141]
	v_pk_fma_f32 v[140:141], v[124:125], v[124:125], v[140:141]
	v_pk_fma_f32 v[140:141], v[126:127], v[126:127], v[140:141]
	v_pk_fma_f32 v[140:141], v[128:129], v[128:129], v[140:141]
	v_pk_fma_f32 v[140:141], v[130:131], v[130:131], v[140:141]
	v_add_f32_e32 v140, v140, v141
	s_nop 1
	v_add_f32_dpp v140, v140, v140 quad_perm:[1,0,3,2] row_mask:0xf bank_mask:0xf
	s_nop 1
	v_add_f32_dpp v140, v140, v140 quad_perm:[2,3,0,1] row_mask:0xf bank_mask:0xf
	s_nop 1
	v_add_f32_dpp v140, v140, v140 row_ror:4 row_mask:0xf bank_mask:0xf
	s_nop 1
	v_add_f32_dpp v140, v140, v140 row_ror:8 row_mask:0xf bank_mask:0xf
	s_nop 1
	v_add_f32_dpp v140, v140, v140 row_bcast:15 row_mask:0xa bank_mask:0xf
	s_nop 1
	v_add_f32_dpp v140, v140, v140 row_bcast:31 row_mask:0xc bank_mask:0xf
	s_nop 1
	v_fmamk_f32 v140, v140, 0x3a800000, v224
	v_rsq_f32_e32 v140, v140
	s_nop 0
	v_mul_f32_e32 v140, v144, v140
	s_nop 0
	v_readlane_b32 s4, v140, 63
	s_nop 1
	v_pk_mul_f32 v[116:117], v[116:117], s[4:5] op_sel_hi:[1,0]
	v_pk_mul_f32 v[118:119], v[118:119], s[4:5] op_sel_hi:[1,0]
	v_pk_mul_f32 v[120:121], v[120:121], s[4:5] op_sel_hi:[1,0]
	v_pk_mul_f32 v[122:123], v[122:123], s[4:5] op_sel_hi:[1,0]
	v_pk_mul_f32 v[124:125], v[124:125], s[4:5] op_sel_hi:[1,0]
	v_pk_mul_f32 v[126:127], v[126:127], s[4:5] op_sel_hi:[1,0]
	v_pk_mul_f32 v[128:129], v[128:129], s[4:5] op_sel_hi:[1,0]
	v_pk_mul_f32 v[130:131], v[130:131], s[4:5] op_sel_hi:[1,0]
	v_pk_fma_f32 v[198:199], v[0:1], v[116:117], v[198:199]
	v_pk_fma_f32 v[200:201], v[2:3], v[118:119], v[200:201]
	v_pk_fma_f32 v[202:203], v[4:5], v[120:121], v[202:203]
	v_pk_fma_f32 v[204:205], v[6:7], v[122:123], v[204:205]
	v_pk_fma_f32 v[206:207], v[8:9], v[124:125], v[206:207]
	v_pk_fma_f32 v[208:209], v[10:11], v[126:127], v[208:209]
	v_pk_fma_f32 v[210:211], v[12:13], v[128:129], v[210:211]
	v_pk_fma_f32 v[212:213], v[14:15], v[130:131], v[212:213]
	v_cvt_f16_f32_e32 v132, v198
	v_cvt_f16_f32_e32 v133, v200
	v_cvt_f16_f32_e32 v134, v202
	v_cvt_f16_f32_e32 v135, v204
	v_cvt_f16_f32_e32 v136, v206
	v_cvt_f16_f32_e32 v137, v208
	v_cvt_f16_f32_e32 v138, v210
	v_cvt_f16_f32_e32 v139, v212
	v_cvt_f16_f32_sdwa v132, v199 dst_sel:WORD_1 dst_unused:UNUSED_PRESERVE src0_sel:DWORD
	v_cvt_f16_f32_sdwa v133, v201 dst_sel:WORD_1 dst_unused:UNUSED_PRESERVE src0_sel:DWORD
	v_cvt_f16_f32_sdwa v134, v203 dst_sel:WORD_1 dst_unused:UNUSED_PRESERVE src0_sel:DWORD
	v_cvt_f16_f32_sdwa v135, v205 dst_sel:WORD_1 dst_unused:UNUSED_PRESERVE src0_sel:DWORD
	v_cvt_f16_f32_sdwa v136, v207 dst_sel:WORD_1 dst_unused:UNUSED_PRESERVE src0_sel:DWORD
	v_cvt_f16_f32_sdwa v137, v209 dst_sel:WORD_1 dst_unused:UNUSED_PRESERVE src0_sel:DWORD
	v_cvt_f16_f32_sdwa v138, v211 dst_sel:WORD_1 dst_unused:UNUSED_PRESERVE src0_sel:DWORD
	v_cvt_f16_f32_sdwa v139, v213 dst_sel:WORD_1 dst_unused:UNUSED_PRESERVE src0_sel:DWORD
; __device__ __forceinline__ unsigned pk2(float lo, float hi) { return pg8::cvt_pk_bf16(lo, hi); }
; template <int R, bool SRCB> ...
;     ...
;         for (int r = 0; r < R; ++r) {
;             float ss = 0.f;
; #pragma unroll
;             for (int j = 0; j < 2; ++j)
; #pragma unroll
;                 for (int k = 0; k < 2; ++k) ss += (h[r][j][k][0] * h[r][j][k][0] + h[r][j][k][1] * h[r][j][k][1]) + (h[r][j][k][2] * h[r][j][k][2] + h[r][j][k][3] * h[r][j][k][3]);
;             const float rr = __builtin_amdgcn_rsqf(wave_sum(ss) * (1.0f / DM) + 1e-6f);
; #pragma unroll
;             for (int j = 0; j < 2; ++j) { const f32x4 v0 = (h[r][j][0] * rr * gp[j][0]) * sc1[j][0] + sh[j][0], v1 = (h[r][j][1] * rr * gp[j][1]) * sc1[j][1] + sh[j][1];
;                 u32x4 t; t.x = pk2(v0[0], v0[1]); t.y = pk2(v0[2], v0[3]); t.z = pk2(v1[0], v1[1]); t.w = pk2(v1[2], v1[3]);
;                 *(u32x4*)(U + (size_t)(row0 + r) * DM + 8 * lane + 512 * j) = t; }
; template <bool SRCB> ...
;     ...
;     for (int g = gw; g < M_LAT / 4; g += NGW) norm_rows<4, SRCB>(4 * g, g >> 10, SRCB ? (const void*)((const bf16_t*)hsrc_lat + (size_t)g * 4 * DM) : (const void*)((const float*)hsrc_lat + (size_t)g * 4 * DM), hout, final_out, Y, nullptr, w, gpost, gate, U, gpre, shift, scale, lane);
;     if (with_ctx) for (int row = M_LAT + gw; row < MTOT; row += NGW) norm_rows<1, SRCB>(row, 8, SRCB ? (const void*)((const bf16_t*)hsrc_ctx + (size_t)(row - M_LAT) * DM) : (const void*)((const float*)hsrc_ctx + (size_t)(row - M_LAT) * DM), hout, final_out, Y, YP, w, gpost, gate, U, gpre, shift, scale, lane);
	s_nop 0
	global_store_dwordx4 v187, v[132:135], s[42:43] offset:2048
	global_store_dwordx4 v187, v[136:139], s[42:43] offset:3072
	v_pk_mul_f32 v[140:141], v[198:199], v[198:199]
	v_pk_fma_f32 v[140:141], v[200:201], v[200:201], v[140:141]
	v_pk_fma_f32 v[140:141], v[202:203], v[202:203], v[140:141]
	v_pk_fma_f32 v[140:141], v[204:205], v[204:205], v[140:141]
	v_pk_fma_f32 v[140:141], v[206:207], v[206:207], v[140:141]
	v_pk_fma_f32 v[140:141], v[208:209], v[208:209], v[140:141]
	v_pk_fma_f32 v[140:141], v[210:211], v[210:211], v[140:141]
	v_pk_fma_f32 v[140:141], v[212:213], v[212:213], v[140:141]
	v_add_f32_e32 v140, v140, v141
	s_nop 1
	v_add_f32_dpp v140, v140, v140 quad_perm:[1,0,3,2] row_mask:0xf bank_mask:0xf
	s_nop 1
	v_add_f32_dpp v140, v140, v140 quad_perm:[2,3,0,1] row_mask:0xf bank_mask:0xf
	s_nop 1
	v_add_f32_dpp v140, v140, v140 row_ror:4 row_mask:0xf bank_mask:0xf
	s_nop 1
	v_add_f32_dpp v140, v140, v140 row_ror:8 row_mask:0xf bank_mask:0xf
	s_nop 1
	v_add_f32_dpp v140, v140, v140 row_bcast:15 row_mask:0xa bank_mask:0xf
	s_nop 1
	v_add_f32_dpp v140, v140, v140 row_bcast:31 row_mask:0xc bank_mask:0xf
	s_nop 1
	v_fmamk_f32 v140, v140, 0x3a800000, v224
	v_rsq_f32_e32 v140, v140
	s_nop 0
	v_readlane_b32 s6, v140, 63
	s_nop 1
	v_pk_mul_f32 v[198:199], v[198:199], s[6:7] op_sel_hi:[1,0]
	v_pk_mul_f32 v[200:201], v[200:201], s[6:7] op_sel_hi:[1,0]
	v_pk_mul_f32 v[202:203], v[202:203], s[6:7] op_sel_hi:[1,0]
	v_pk_mul_f32 v[204:205], v[204:205], s[6:7] op_sel_hi:[1,0]
	v_pk_mul_f32 v[206:207], v[206:207], s[6:7] op_sel_hi:[1,0]
	v_pk_mul_f32 v[208:209], v[208:209], s[6:7] op_sel_hi:[1,0]
	v_pk_mul_f32 v[210:211], v[210:211], s[6:7] op_sel_hi:[1,0]
	v_pk_mul_f32 v[212:213], v[212:213], s[6:7] op_sel_hi:[1,0]
	v_pk_mul_f32 v[198:199], v[16:17], v[198:199]
	v_pk_mul_f32 v[200:201], v[18:19], v[200:201]
	v_pk_mul_f32 v[202:203], v[20:21], v[202:203]
	v_pk_mul_f32 v[204:205], v[22:23], v[204:205]
	v_pk_mul_f32 v[206:207], v[24:25], v[206:207]
	v_pk_mul_f32 v[208:209], v[26:27], v[208:209]
	v_pk_mul_f32 v[210:211], v[28:29], v[210:211]
	v_pk_mul_f32 v[212:213], v[30:31], v[212:213]
	v_pk_fma_f32 v[198:199], v[32:33], v[198:199], v[48:49]
	v_pk_fma_f32 v[200:201], v[34:35], v[200:201], v[50:51]
	v_pk_fma_f32 v[202:203], v[36:37], v[202:203], v[52:53]
	v_pk_fma_f32 v[204:205], v[38:39], v[204:205], v[54:55]
	v_pk_fma_f32 v[206:207], v[40:41], v[206:207], v[56:57]
	v_pk_fma_f32 v[208:209], v[42:43], v[208:209], v[58:59]
	v_pk_fma_f32 v[210:211], v[44:45], v[210:211], v[60:61]
	v_pk_fma_f32 v[212:213], v[46:47], v[212:213], v[62:63]
	v_cvt_pk_bf16_f32 v230, v198, v199
	v_cvt_pk_bf16_f32 v231, v200, v201
	v_cvt_pk_bf16_f32 v232, v202, v203
	v_cvt_pk_bf16_f32 v233, v204, v205
	v_cvt_pk_bf16_f32 v234, v206, v207
	v_cvt_pk_bf16_f32 v235, v208, v209
	v_cvt_pk_bf16_f32 v236, v210, v211
	v_cvt_pk_bf16_f32 v237, v212, v213
	global_store_dwordx4 v187, v[230:233], s[44:45] offset:2048
	global_store_dwordx4 v187, v[234:237], s[44:45] offset:3072
	s_add_i32 s23, s23, s76
	s_cmpk_lt_i32 s23, 0x800
	s_cbranch_scc1 nrmx_chunk
	s_branch .LBB0_245
nrmx_orig:
	v_lshlrev_b32_e32 v96, 3, v196
	s_cmp_lg_u64 s[18:19], 0
	v_cndmask_b32_e64 v4, v216, v226, s[14:15]
	v_ashrrev_i32_e32 v97, 31, v96
	s_cselect_b64 s[38:39], -1, 0
	s_cmp_lg_u64 s[16:17], 0
	v_lshlrev_b32_e32 v145, 2, v4
	v_cndmask_b32_e64 v4, v216, v246, s[12:13]
	v_readlane_b32 s2, v254, 59
	s_cselect_b64 s[40:41], -1, 0
	v_lshlrev_b64 v[2:3], 1, v[96:97]
	v_lshlrev_b32_e32 v146, 2, v4
	v_cndmask_b32_e64 v4, v216, v247, s[10:11]
	v_readlane_b32 s3, v254, 60
	s_ashr_i32 s23, s22, 31
	v_lshlrev_b32_e32 v147, 2, v4
	v_xor_b32_e32 v4, 8, v216
	v_lshl_add_u64 v[104:105], s[2:3], 0, v[2:3]
	s_lshl_b64 s[2:3], s[22:23], 13
	v_cndmask_b32_e64 v4, v216, v4, s[8:9]
	s_add_u32 s2, s98, s2
	v_lshlrev_b32_e32 v148, 2, v4
	v_cndmask_b32_e64 v4, v216, v222, s[6:7]
	s_addc_u32 s3, s99, s3
	v_lshlrev_b64 v[0:1], 2, v[96:97]
	v_lshlrev_b32_e32 v149, 2, v4
	v_cndmask_b32_e32 v4, v216, v223, vcc
	v_lshl_add_u64 v[112:113], s[2:3], 0, v[2:3]
	s_lshl_b32 s2, s52, 2
	v_readlane_b32 s3, v254, 41
	v_lshl_add_u64 v[98:99], s[34:35], 0, v[0:1]
	v_lshl_add_u64 v[100:101], s[26:27], 0, v[0:1]
	v_lshl_add_u64 v[102:103], s[16:17], 0, v[2:3]
	v_lshlrev_b32_e32 v150, 2, v4
	v_lshl_add_u64 v[106:107], s[36:37], 0, v[0:1]
	v_lshl_add_u64 v[108:109], s[30:31], 0, v[0:1]
	v_lshl_add_u64 v[110:111], s[28:29], 0, v[0:1]
	s_add_i32 s8, s3, s2
	s_mov_b32 s23, s22
	s_branch .LBB0_211
